# stack + nt hint on the weight (B) LDS-DMA loads in GEMM mainloops
# baseline (speedup 1.0000x reference)
; #define PG8_STAGE(bufoff, gbase, voff) do { _Pragma("unroll") for (int _i = 0; _i < 2; ++_i) \
;         __builtin_amdgcn_global_load_lds((const unsigned*)((const char*)(gbase) + (voff)[_i]), (LAS unsigned*)(lds + (bufoff) + ldsw + _i * 8192), 16, 0, 0); } while (0)
; #define PG8_LDA(dst, b, h) do { _Pragma("unroll") for (int m = 0; m < 4; ++m) _Pragma("unroll") for (int k = 0; k < 2; ++k) dst[m][k] = *(const LAS bf16x8*)(lds + PG8_SA(b, h) + aoff + m * 2048 + k * 1024); } while (0)
; #define PG8_LDB(dst, b, h) do { _Pragma("unroll") for (int n = 0; n < 2; ++n) _Pragma("unroll") for (int k = 0; k < 2; ++k) dst[n][k] = *(const LAS bf16x8*)(lds + PG8_SB(b, h) + boff + n * 2048 + k * 1024); } while (0)
; #define PG8_MMA(ai, bj, At, Bt) do { __builtin_amdgcn_s_setprio(1); _Pragma("unroll") for (int m = 0; m < 4; ++m) _Pragma("unroll") for (int n = 0; n < 2; ++n) _Pragma("unroll") for (int k = 0; k < 2; ++k) \
;         acc[ai][bj][m][n] = __builtin_amdgcn_mfma_f32_16x16x32_bf16(Bt[n][k], At[m][k], acc[ai][bj][m][n], 0, 0, 0); __builtin_amdgcn_s_setprio(0); } while (0)
; #define PG8_WAIT_V(n) asm volatile("s_waitcnt vmcnt(" #n ")" ::: "memory")
; #define PG8_WAIT_L(n) asm volatile("s_waitcnt lgkmcnt(" #n ")" ::: "memory")
; #define PG8_BAR __builtin_amdgcn_s_barrier()
; #define PG8_SCHED __builtin_amdgcn_sched_barrier(0)
; template <class Epi>
; __device__ __forceinline__ void gemm_phase(LAS unsigned char* lds, const Gemm g, const StaticOrder& S, const Epi& E) {
;     ...
;             PG8_LDB(B0, 0, 0); PG8_LDB(B1, 0, 1); PG8_SCHED; PG8_LDA(At, 0, 0); PG8_STAGE(PG8_SA(1, 1), a1 + hstepA, voffA);
;             PG8_WAIT_V(8); PG8_WAIT_L(0); PG8_BAR; PG8_MMA(0, 0, At, B0); PG8_MMA(0, 1, At, B1); PG8_BAR; PG8_SCHED;
;             PG8_LDA(At, 0, 1); PG8_STAGE(PG8_SB(0, 0), b2, voffB); PG8_STAGE(PG8_SB(0, 1), b2 + hstepB, voffB); PG8_STAGE(PG8_SA(0, 0), a2, voffA);
;             PG8_WAIT_V(8); PG8_WAIT_L(0); PG8_BAR; PG8_MMA(1, 0, At, B0); PG8_MMA(1, 1, At, B1); PG8_BAR; PG8_SCHED;
.LBB0_414:
	s_add_u32 s14, s26, 0xfff80080
	s_addc_u32 s15, s27, -1
	s_add_i32 s33, 0, 0x10000
	s_cmp_eq_u32 s21, 28
	s_cselect_b32 s29, s0, s15
	s_cselect_b32 s28, s1, s14
	s_cselect_b32 s15, s3, s19
	s_cselect_b32 s14, s7, s9
	s_add_i32 s52, 0, 0x14000
	v_add_u32_e32 v150, s33, v1
	v_add_u32_e32 v159, s52, v1
	ds_read_b128 v[138:141], v150
	ds_read_b128 v[142:145], v150 offset:1024
	ds_read_b128 v[146:149], v150 offset:2048
	ds_read_b128 v[150:153], v150 offset:3072
	ds_read_b128 v[154:157], v159
	ds_read_b128 v[160:163], v159 offset:1024
	ds_read_b128 v[164:167], v159 offset:2048
	ds_read_b128 v[168:171], v159 offset:3072
	v_lshl_add_u64 v[184:185], s[26:27], 0, v[134:135]
	s_add_i32 m0, s35, 0xc000
	ds_read_b128 v[172:175], v158
	ds_read_b128 v[176:179], v158 offset:1024
	ds_read_b128 v[188:191], v158 offset:2048
	ds_read_b128 v[192:195], v158 offset:3072
	ds_read_b128 v[196:199], v158 offset:4096
	ds_read_b128 v[200:203], v158 offset:5120
	ds_read_b128 v[204:207], v158 offset:6144
	ds_read_b128 v[208:211], v158 offset:7168
	global_load_lds_dwordx4 v[184:185], off
	v_lshl_add_u64 v[184:185], s[26:27], 0, v[136:137]
	s_add_i32 m0, s35, 0xe000
	s_nop 0
	global_load_lds_dwordx4 v[184:185], off
	s_waitcnt vmcnt(8)
	s_waitcnt lgkmcnt(0)
	s_barrier
	s_setprio 1
	s_waitcnt lgkmcnt(0)
	v_mfma_f32_16x16x32_bf16 v[126:129], v[138:141], v[172:175], v[126:129]
	v_mfma_f32_16x16x32_bf16 v[122:125], v[146:149], v[172:175], v[122:125]
	v_mfma_f32_16x16x32_bf16 v[110:113], v[138:141], v[188:191], v[110:113]
	v_mfma_f32_16x16x32_bf16 v[106:109], v[146:149], v[188:191], v[106:109]
	v_mfma_f32_16x16x32_bf16 v[94:97], v[138:141], v[196:199], v[94:97]
	v_mfma_f32_16x16x32_bf16 v[90:93], v[146:149], v[196:199], v[90:93]
	v_mfma_f32_16x16x32_bf16 v[78:81], v[138:141], v[204:207], v[78:81]
	v_mfma_f32_16x16x32_bf16 v[74:77], v[146:149], v[204:207], v[74:77]
	v_mfma_f32_16x16x32_bf16 v[126:129], v[142:145], v[176:179], v[126:129]
	v_mfma_f32_16x16x32_bf16 v[122:125], v[150:153], v[176:179], v[122:125]
	v_mfma_f32_16x16x32_bf16 v[110:113], v[142:145], v[192:195], v[110:113]
	v_mfma_f32_16x16x32_bf16 v[106:109], v[150:153], v[192:195], v[106:109]
	v_mfma_f32_16x16x32_bf16 v[94:97], v[142:145], v[200:203], v[94:97]
	v_mfma_f32_16x16x32_bf16 v[90:93], v[150:153], v[200:203], v[90:93]
	v_mfma_f32_16x16x32_bf16 v[78:81], v[142:145], v[208:211], v[78:81]
	v_mfma_f32_16x16x32_bf16 v[74:77], v[150:153], v[208:211], v[74:77]
	s_setprio 0
	s_setprio 1
	v_mfma_f32_16x16x32_bf16 v[118:121], v[154:157], v[172:175], v[118:121]
	v_mfma_f32_16x16x32_bf16 v[114:117], v[164:167], v[172:175], v[114:117]
	v_mfma_f32_16x16x32_bf16 v[102:105], v[154:157], v[188:191], v[102:105]
	v_mfma_f32_16x16x32_bf16 v[98:101], v[164:167], v[188:191], v[98:101]
	v_mfma_f32_16x16x32_bf16 v[86:89], v[154:157], v[196:199], v[86:89]
	v_mfma_f32_16x16x32_bf16 v[82:85], v[164:167], v[196:199], v[82:85]
	v_mfma_f32_16x16x32_bf16 v[70:73], v[154:157], v[204:207], v[70:73]
	v_mfma_f32_16x16x32_bf16 v[66:69], v[164:167], v[204:207], v[66:69]
	v_mfma_f32_16x16x32_bf16 v[118:121], v[160:163], v[176:179], v[118:121]
	v_mfma_f32_16x16x32_bf16 v[114:117], v[168:171], v[176:179], v[114:117]
	v_mfma_f32_16x16x32_bf16 v[102:105], v[160:163], v[192:195], v[102:105]
	v_mfma_f32_16x16x32_bf16 v[98:101], v[168:171], v[192:195], v[98:101]
	v_mfma_f32_16x16x32_bf16 v[86:89], v[160:163], v[200:203], v[86:89]
	v_mfma_f32_16x16x32_bf16 v[82:85], v[168:171], v[200:203], v[82:85]
	v_mfma_f32_16x16x32_bf16 v[70:73], v[160:163], v[208:211], v[70:73]
	v_mfma_f32_16x16x32_bf16 v[66:69], v[168:171], v[208:211], v[66:69]
	s_setprio 0
	s_barrier
	s_add_i32 s33, s33, s34
	v_lshl_add_u64 v[184:185], s[14:15], 0, v[130:131]
	s_mov_b32 m0, s33
	ds_read_b128 v[172:175], v158 offset:16384
	ds_read_b128 v[176:179], v158 offset:17408
	ds_read_b128 v[188:191], v158 offset:18432
	ds_read_b128 v[192:195], v158 offset:19456
	ds_read_b128 v[196:199], v158 offset:20480
	ds_read_b128 v[200:203], v158 offset:21504
	ds_read_b128 v[204:207], v158 offset:22528
	ds_read_b128 v[208:211], v158 offset:23552
	global_load_lds_dwordx4 v[184:185], off nt
	s_add_i32 m0, s33, 0x2000
	s_add_u32 s40, s14, 0x80000
	v_lshl_add_u64 v[212:213], s[14:15], 0, v[132:133]
	s_addc_u32 s41, s15, 0
	s_add_i32 s33, s52, s34
	global_load_lds_dwordx4 v[212:213], off nt
	v_lshl_add_u64 v[214:215], s[40:41], 0, v[130:131]
	s_mov_b32 m0, s33
	v_lshl_add_u64 v[216:217], s[28:29], 0, v[132:133]
	global_load_lds_dwordx4 v[214:215], off nt
	v_lshl_add_u64 v[214:215], s[40:41], 0, v[132:133]
	s_add_i32 m0, s33, 0x2000
	s_nop 0
	global_load_lds_dwordx4 v[214:215], off nt
	v_lshl_add_u64 v[214:215], s[28:29], 0, v[130:131]
	s_mov_b32 m0, s35
	s_nop 0
	global_load_lds_dwordx4 v[214:215], off
	s_mov_b32 m0, s42
	s_nop 0
	global_load_lds_dwordx4 v[216:217], off
	s_waitcnt vmcnt(8)
	s_waitcnt lgkmcnt(0)
	s_barrier
; #define PG8_STAGE(bufoff, gbase, voff) do { _Pragma("unroll") for (int _i = 0; _i < 2; ++_i) \
;         __builtin_amdgcn_global_load_lds((const unsigned*)((const char*)(gbase) + (voff)[_i]), (LAS unsigned*)(lds + (bufoff) + ldsw + _i * 8192), 16, 0, 0); } while (0)
; #define PG8_LDA(dst, b, h) do { _Pragma("unroll") for (int m = 0; m < 4; ++m) _Pragma("unroll") for (int k = 0; k < 2; ++k) dst[m][k] = *(const LAS bf16x8*)(lds + PG8_SA(b, h) + aoff + m * 2048 + k * 1024); } while (0)
; #define PG8_LDB(dst, b, h) do { _Pragma("unroll") for (int n = 0; n < 2; ++n) _Pragma("unroll") for (int k = 0; k < 2; ++k) dst[n][k] = *(const LAS bf16x8*)(lds + PG8_SB(b, h) + boff + n * 2048 + k * 1024); } while (0)
; #define PG8_MMA(ai, bj, At, Bt) do { __builtin_amdgcn_s_setprio(1); _Pragma("unroll") for (int m = 0; m < 4; ++m) _Pragma("unroll") for (int n = 0; n < 2; ++n) _Pragma("unroll") for (int k = 0; k < 2; ++k) \
;         acc[ai][bj][m][n] = __builtin_amdgcn_mfma_f32_16x16x32_bf16(Bt[n][k], At[m][k], acc[ai][bj][m][n], 0, 0, 0); __builtin_amdgcn_s_setprio(0); } while (0)
; #define PG8_WAIT_V(n) asm volatile("s_waitcnt vmcnt(" #n ")" ::: "memory")
; #define PG8_WAIT_L(n) asm volatile("s_waitcnt lgkmcnt(" #n ")" ::: "memory")
; #define PG8_BAR __builtin_amdgcn_s_barrier()
; #define PG8_SCHED __builtin_amdgcn_sched_barrier(0)
; template <class Epi>
; __device__ __forceinline__ void gemm_phase(LAS unsigned char* lds, const Gemm g, const StaticOrder& S, const Epi& E) {
;     ...
;             PG8_WAIT_V(8); PG8_WAIT_L(0); PG8_BAR; PG8_MMA(1, 0, At, B0); PG8_MMA(1, 1, At, B1); PG8_BAR; PG8_SCHED;
;             PG8_LDB(B0, 1, 0); PG8_LDB(B1, 1, 1); PG8_SCHED; PG8_LDA(At, 1, 0); PG8_STAGE(PG8_SA(0, 1), a2 + hstepA, voffA);
;             PG8_WAIT_V(8); PG8_WAIT_L(0); PG8_BAR; PG8_MMA(0, 0, At, B0); PG8_MMA(0, 1, At, B1); PG8_BAR; PG8_SCHED;
	s_setprio 1
	s_waitcnt lgkmcnt(0)
	v_mfma_f32_16x16x32_bf16 v[62:65], v[138:141], v[172:175], v[62:65]
	v_mfma_f32_16x16x32_bf16 v[58:61], v[146:149], v[172:175], v[58:61]
	v_mfma_f32_16x16x32_bf16 v[46:49], v[138:141], v[188:191], v[46:49]
	v_mfma_f32_16x16x32_bf16 v[42:45], v[146:149], v[188:191], v[42:45]
	v_mfma_f32_16x16x32_bf16 v[30:33], v[138:141], v[196:199], v[30:33]
	v_mfma_f32_16x16x32_bf16 v[26:29], v[146:149], v[196:199], v[26:29]
	v_mfma_f32_16x16x32_bf16 v[14:17], v[138:141], v[204:207], v[14:17]
	v_mfma_f32_16x16x32_bf16 v[10:13], v[146:149], v[204:207], v[10:13]
	v_mfma_f32_16x16x32_bf16 v[62:65], v[142:145], v[176:179], v[62:65]
	v_mfma_f32_16x16x32_bf16 v[58:61], v[150:153], v[176:179], v[58:61]
	v_mfma_f32_16x16x32_bf16 v[46:49], v[142:145], v[192:195], v[46:49]
	v_mfma_f32_16x16x32_bf16 v[42:45], v[150:153], v[192:195], v[42:45]
	v_mfma_f32_16x16x32_bf16 v[30:33], v[142:145], v[200:203], v[30:33]
	v_mfma_f32_16x16x32_bf16 v[26:29], v[150:153], v[200:203], v[26:29]
	v_mfma_f32_16x16x32_bf16 v[14:17], v[142:145], v[208:211], v[14:17]
	v_mfma_f32_16x16x32_bf16 v[10:13], v[150:153], v[208:211], v[10:13]
	s_setprio 0
	s_setprio 1
	v_mfma_f32_16x16x32_bf16 v[54:57], v[154:157], v[172:175], v[54:57]
	v_mfma_f32_16x16x32_bf16 v[50:53], v[164:167], v[172:175], v[50:53]
	v_mfma_f32_16x16x32_bf16 v[38:41], v[154:157], v[188:191], v[38:41]
	v_mfma_f32_16x16x32_bf16 v[34:37], v[164:167], v[188:191], v[34:37]
	v_mfma_f32_16x16x32_bf16 v[22:25], v[154:157], v[196:199], v[22:25]
	v_mfma_f32_16x16x32_bf16 v[18:21], v[164:167], v[196:199], v[18:21]
	v_mfma_f32_16x16x32_bf16 v[6:9], v[154:157], v[204:207], v[6:9]
	v_mfma_f32_16x16x32_bf16 v[2:5], v[164:167], v[204:207], v[2:5]
	v_mfma_f32_16x16x32_bf16 v[54:57], v[160:163], v[176:179], v[54:57]
	v_mfma_f32_16x16x32_bf16 v[50:53], v[168:171], v[176:179], v[50:53]
	v_mfma_f32_16x16x32_bf16 v[38:41], v[160:163], v[192:195], v[38:41]
	v_mfma_f32_16x16x32_bf16 v[34:37], v[168:171], v[192:195], v[34:37]
	v_mfma_f32_16x16x32_bf16 v[22:25], v[160:163], v[200:203], v[22:25]
	v_mfma_f32_16x16x32_bf16 v[18:21], v[168:171], v[200:203], v[18:21]
	v_mfma_f32_16x16x32_bf16 v[6:9], v[160:163], v[208:211], v[6:9]
	v_mfma_f32_16x16x32_bf16 v[2:5], v[168:171], v[208:211], v[2:5]
	s_setprio 0
	s_barrier
	s_add_i32 s33, 0, 0x18000
	s_add_i32 s40, 0, 0x1c000
	v_add_u32_e32 v150, s33, v1
	v_add_u32_e32 v159, s40, v1
	ds_read_b128 v[138:141], v150
	ds_read_b128 v[142:145], v150 offset:1024
	ds_read_b128 v[146:149], v150 offset:2048
	ds_read_b128 v[150:153], v150 offset:3072
	ds_read_b128 v[154:157], v159
	ds_read_b128 v[160:163], v159 offset:1024
	ds_read_b128 v[164:167], v159 offset:2048
	ds_read_b128 v[168:171], v159 offset:3072
	s_add_u32 s28, s28, 0x80000
	s_addc_u32 s29, s29, 0
	s_mov_b32 m0, s45
	v_lshl_add_u64 v[218:219], s[28:29], 0, v[130:131]
	ds_read_b128 v[172:175], v158 offset:32768
	ds_read_b128 v[176:179], v158 offset:33792
	ds_read_b128 v[188:191], v158 offset:34816
	ds_read_b128 v[192:195], v158 offset:35840
	ds_read_b128 v[196:199], v158 offset:36864
	ds_read_b128 v[200:203], v158 offset:37888
	ds_read_b128 v[204:207], v158 offset:38912
	ds_read_b128 v[208:211], v158 offset:39936
	global_load_lds_dwordx4 v[218:219], off
	v_lshl_add_u64 v[218:219], s[28:29], 0, v[132:133]
	s_mov_b32 m0, s68
	s_nop 0
	global_load_lds_dwordx4 v[218:219], off
	s_waitcnt vmcnt(8)
	s_waitcnt lgkmcnt(0)
	s_barrier
	s_setprio 1
	s_waitcnt lgkmcnt(0)
	v_mfma_f32_16x16x32_bf16 v[126:129], v[138:141], v[172:175], v[126:129]
	v_mfma_f32_16x16x32_bf16 v[122:125], v[146:149], v[172:175], v[122:125]
	v_mfma_f32_16x16x32_bf16 v[110:113], v[138:141], v[188:191], v[110:113]
	v_mfma_f32_16x16x32_bf16 v[106:109], v[146:149], v[188:191], v[106:109]
	v_mfma_f32_16x16x32_bf16 v[94:97], v[138:141], v[196:199], v[94:97]
	v_mfma_f32_16x16x32_bf16 v[90:93], v[146:149], v[196:199], v[90:93]
	v_mfma_f32_16x16x32_bf16 v[78:81], v[138:141], v[204:207], v[78:81]
	v_mfma_f32_16x16x32_bf16 v[74:77], v[146:149], v[204:207], v[74:77]
	v_mfma_f32_16x16x32_bf16 v[126:129], v[142:145], v[176:179], v[126:129]
	v_mfma_f32_16x16x32_bf16 v[122:125], v[150:153], v[176:179], v[122:125]
	v_mfma_f32_16x16x32_bf16 v[110:113], v[142:145], v[192:195], v[110:113]
	v_mfma_f32_16x16x32_bf16 v[106:109], v[150:153], v[192:195], v[106:109]
	v_mfma_f32_16x16x32_bf16 v[94:97], v[142:145], v[200:203], v[94:97]
	v_mfma_f32_16x16x32_bf16 v[90:93], v[150:153], v[200:203], v[90:93]
	v_mfma_f32_16x16x32_bf16 v[78:81], v[142:145], v[208:211], v[78:81]
	v_mfma_f32_16x16x32_bf16 v[74:77], v[150:153], v[208:211], v[74:77]
	s_setprio 0
	s_setprio 1
	v_mfma_f32_16x16x32_bf16 v[118:121], v[154:157], v[172:175], v[118:121]
	v_mfma_f32_16x16x32_bf16 v[114:117], v[164:167], v[172:175], v[114:117]
	v_mfma_f32_16x16x32_bf16 v[102:105], v[154:157], v[188:191], v[102:105]
	v_mfma_f32_16x16x32_bf16 v[98:101], v[164:167], v[188:191], v[98:101]
	v_mfma_f32_16x16x32_bf16 v[86:89], v[154:157], v[196:199], v[86:89]
	v_mfma_f32_16x16x32_bf16 v[82:85], v[164:167], v[196:199], v[82:85]
	v_mfma_f32_16x16x32_bf16 v[70:73], v[154:157], v[204:207], v[70:73]
	v_mfma_f32_16x16x32_bf16 v[66:69], v[164:167], v[204:207], v[66:69]
	v_mfma_f32_16x16x32_bf16 v[118:121], v[160:163], v[176:179], v[118:121]
	v_mfma_f32_16x16x32_bf16 v[114:117], v[168:171], v[176:179], v[114:117]
	v_mfma_f32_16x16x32_bf16 v[102:105], v[160:163], v[192:195], v[102:105]
	v_mfma_f32_16x16x32_bf16 v[98:101], v[168:171], v[192:195], v[98:101]
	v_mfma_f32_16x16x32_bf16 v[86:89], v[160:163], v[200:203], v[86:89]
	v_mfma_f32_16x16x32_bf16 v[82:85], v[168:171], v[200:203], v[82:85]
	v_mfma_f32_16x16x32_bf16 v[70:73], v[160:163], v[208:211], v[70:73]
	v_mfma_f32_16x16x32_bf16 v[66:69], v[168:171], v[208:211], v[66:69]
	s_setprio 0
	s_barrier
; #define PG8_STAGE(bufoff, gbase, voff) do { _Pragma("unroll") for (int _i = 0; _i < 2; ++_i) \
;         __builtin_amdgcn_global_load_lds((const unsigned*)((const char*)(gbase) + (voff)[_i]), (LAS unsigned*)(lds + (bufoff) + ldsw + _i * 8192), 16, 0, 0); } while (0)
; #define PG8_LDA(dst, b, h) do { _Pragma("unroll") for (int m = 0; m < 4; ++m) _Pragma("unroll") for (int k = 0; k < 2; ++k) dst[m][k] = *(const LAS bf16x8*)(lds + PG8_SA(b, h) + aoff + m * 2048 + k * 1024); } while (0)
; #define PG8_MMA(ai, bj, At, Bt) do { __builtin_amdgcn_s_setprio(1); _Pragma("unroll") for (int m = 0; m < 4; ++m) _Pragma("unroll") for (int n = 0; n < 2; ++n) _Pragma("unroll") for (int k = 0; k < 2; ++k) \
;         acc[ai][bj][m][n] = __builtin_amdgcn_mfma_f32_16x16x32_bf16(Bt[n][k], At[m][k], acc[ai][bj][m][n], 0, 0, 0); __builtin_amdgcn_s_setprio(0); } while (0)
; #define PG8_WAIT_V(n) asm volatile("s_waitcnt vmcnt(" #n ")" ::: "memory")
; #define PG8_WAIT_L(n) asm volatile("s_waitcnt lgkmcnt(" #n ")" ::: "memory")
; #define PG8_BAR __builtin_amdgcn_s_barrier()
; #define PG8_SCHED __builtin_amdgcn_sched_barrier(0)
; template <class Epi>
; __device__ __forceinline__ void gemm_phase(LAS unsigned char* lds, const Gemm g, const StaticOrder& S, const Epi& E) {
;     ...
;             PG8_LDA(At, 1, 1); PG8_STAGE(PG8_SB(1, 0), b3, voffB); PG8_STAGE(PG8_SB(1, 1), b3 + hstepB, voffB); PG8_STAGE(PG8_SA(1, 0), a3, voffA);
;             PG8_WAIT_V(8); PG8_WAIT_L(0); PG8_BAR; PG8_MMA(1, 0, At, B0); PG8_MMA(1, 1, At, B1); PG8_BAR; PG8_SCHED;
;         }
	s_add_i32 s28, s33, s34
	v_lshl_add_u64 v[184:185], v[184:185], 0, s[84:85]
	s_mov_b32 m0, s28
	ds_read_b128 v[172:175], v158 offset:49152
	ds_read_b128 v[176:179], v158 offset:50176
	ds_read_b128 v[188:191], v158 offset:51200
	ds_read_b128 v[192:195], v158 offset:52224
	ds_read_b128 v[196:199], v158 offset:53248
	ds_read_b128 v[200:203], v158 offset:54272
	ds_read_b128 v[204:207], v158 offset:55296
	ds_read_b128 v[208:211], v158 offset:56320
	global_load_lds_dwordx4 v[184:185], off nt
	s_add_i32 m0, s28, 0x2000
	s_add_u32 s14, s14, 0x80080
	v_lshl_add_u64 v[184:185], v[212:213], 0, s[84:85]
	s_addc_u32 s15, s15, 0
	s_add_i32 s28, s40, s34
	global_load_lds_dwordx4 v[184:185], off nt
	v_lshl_add_u64 v[184:185], s[14:15], 0, v[130:131]
	s_mov_b32 m0, s28
	s_nop 0
	global_load_lds_dwordx4 v[184:185], off nt
	v_lshl_add_u64 v[184:185], s[14:15], 0, v[132:133]
	s_add_i32 m0, s28, 0x2000
	s_nop 0
	global_load_lds_dwordx4 v[184:185], off nt
	v_lshl_add_u64 v[184:185], v[214:215], 0, s[84:85]
	s_mov_b32 m0, s87
	s_nop 0
	global_load_lds_dwordx4 v[184:185], off
	v_lshl_add_u64 v[184:185], v[216:217], 0, s[84:85]
	s_mov_b32 m0, s91
	s_nop 0
	global_load_lds_dwordx4 v[184:185], off
	s_waitcnt vmcnt(8)
	s_waitcnt lgkmcnt(0)
	s_barrier
	s_setprio 1
	s_waitcnt lgkmcnt(0)
	v_mfma_f32_16x16x32_bf16 v[62:65], v[138:141], v[172:175], v[62:65]
	v_mfma_f32_16x16x32_bf16 v[58:61], v[146:149], v[172:175], v[58:61]
	v_mfma_f32_16x16x32_bf16 v[46:49], v[138:141], v[188:191], v[46:49]
	v_mfma_f32_16x16x32_bf16 v[42:45], v[146:149], v[188:191], v[42:45]
	v_mfma_f32_16x16x32_bf16 v[30:33], v[138:141], v[196:199], v[30:33]
	v_mfma_f32_16x16x32_bf16 v[26:29], v[146:149], v[196:199], v[26:29]
	v_mfma_f32_16x16x32_bf16 v[14:17], v[138:141], v[204:207], v[14:17]
	v_mfma_f32_16x16x32_bf16 v[10:13], v[146:149], v[204:207], v[10:13]
	v_mfma_f32_16x16x32_bf16 v[62:65], v[142:145], v[176:179], v[62:65]
	v_mfma_f32_16x16x32_bf16 v[58:61], v[150:153], v[176:179], v[58:61]
	v_mfma_f32_16x16x32_bf16 v[46:49], v[142:145], v[192:195], v[46:49]
	v_mfma_f32_16x16x32_bf16 v[42:45], v[150:153], v[192:195], v[42:45]
	v_mfma_f32_16x16x32_bf16 v[30:33], v[142:145], v[200:203], v[30:33]
	v_mfma_f32_16x16x32_bf16 v[26:29], v[150:153], v[200:203], v[26:29]
	v_mfma_f32_16x16x32_bf16 v[14:17], v[142:145], v[208:211], v[14:17]
	v_mfma_f32_16x16x32_bf16 v[10:13], v[150:153], v[208:211], v[10:13]
	s_setprio 0
	s_setprio 1
	v_mfma_f32_16x16x32_bf16 v[54:57], v[154:157], v[172:175], v[54:57]
	v_mfma_f32_16x16x32_bf16 v[50:53], v[164:167], v[172:175], v[50:53]
	v_mfma_f32_16x16x32_bf16 v[38:41], v[154:157], v[188:191], v[38:41]
	v_mfma_f32_16x16x32_bf16 v[34:37], v[164:167], v[188:191], v[34:37]
	v_mfma_f32_16x16x32_bf16 v[22:25], v[154:157], v[196:199], v[22:25]
	v_mfma_f32_16x16x32_bf16 v[18:21], v[164:167], v[196:199], v[18:21]
	v_mfma_f32_16x16x32_bf16 v[6:9], v[154:157], v[204:207], v[6:9]
	v_mfma_f32_16x16x32_bf16 v[2:5], v[164:167], v[204:207], v[2:5]
	v_mfma_f32_16x16x32_bf16 v[54:57], v[160:163], v[176:179], v[54:57]
	v_mfma_f32_16x16x32_bf16 v[50:53], v[168:171], v[176:179], v[50:53]
	v_mfma_f32_16x16x32_bf16 v[38:41], v[160:163], v[192:195], v[38:41]
	v_mfma_f32_16x16x32_bf16 v[34:37], v[168:171], v[192:195], v[34:37]
	v_mfma_f32_16x16x32_bf16 v[22:25], v[160:163], v[200:203], v[22:25]
	v_mfma_f32_16x16x32_bf16 v[18:21], v[168:171], v[200:203], v[18:21]
	v_mfma_f32_16x16x32_bf16 v[6:9], v[160:163], v[208:211], v[6:9]
	v_mfma_f32_16x16x32_bf16 v[2:5], v[168:171], v[208:211], v[2:5]
	s_setprio 0
	s_barrier
	s_add_i32 s21, s21, 2
	s_add_u32 s26, s26, 0x100
	s_addc_u32 s27, s27, 0
	s_add_u32 s9, s9, 0x100
	s_addc_u32 s19, s19, 0
	s_cmp_gt_u32 s21, 29
	s_cbranch_scc0 .LBB0_414
	s_and_b64 vcc, exec, s[16:17]
	s_cbranch_vccz .LBB0_417
	s_barrier

; #define PG8_STAGE(bufoff, gbase, voff) do { _Pragma("unroll") for (int _i = 0; _i < 2; ++_i) \
;         __builtin_amdgcn_global_load_lds((const unsigned*)((const char*)(gbase) + (voff)[_i]), (LAS unsigned*)(lds + (bufoff) + ldsw + _i * 8192), 16, 0, 0); } while (0)
; #define PG8_LDA(dst, b, h) do { _Pragma("unroll") for (int m = 0; m < 4; ++m) _Pragma("unroll") for (int k = 0; k < 2; ++k) dst[m][k] = *(const LAS bf16x8*)(lds + PG8_SA(b, h) + aoff + m * 2048 + k * 1024); } while (0)
; #define PG8_LDB(dst, b, h) do { _Pragma("unroll") for (int n = 0; n < 2; ++n) _Pragma("unroll") for (int k = 0; k < 2; ++k) dst[n][k] = *(const LAS bf16x8*)(lds + PG8_SB(b, h) + boff + n * 2048 + k * 1024); } while (0)
; #define PG8_MMA(ai, bj, At, Bt) do { __builtin_amdgcn_s_setprio(1); _Pragma("unroll") for (int m = 0; m < 4; ++m) _Pragma("unroll") for (int n = 0; n < 2; ++n) _Pragma("unroll") for (int k = 0; k < 2; ++k) \
;         acc[ai][bj][m][n] = __builtin_amdgcn_mfma_f32_16x16x32_bf16(Bt[n][k], At[m][k], acc[ai][bj][m][n], 0, 0, 0); __builtin_amdgcn_s_setprio(0); } while (0)
; #define PG8_WAIT_V(n) asm volatile("s_waitcnt vmcnt(" #n ")" ::: "memory")
; #define PG8_WAIT_L(n) asm volatile("s_waitcnt lgkmcnt(" #n ")" ::: "memory")
; #define PG8_BAR __builtin_amdgcn_s_barrier()
; #define PG8_SCHED __builtin_amdgcn_sched_barrier(0)
; template <class Epi>
; __device__ __forceinline__ void gemm_phase(LAS unsigned char* lds, const Gemm g, const StaticOrder& S, const Epi& E) {
;     ...
;             PG8_LDB(B0, 0, 0); PG8_LDB(B1, 0, 1); PG8_SCHED; PG8_LDA(At, 0, 0); PG8_STAGE(PG8_SA(1, 1), a1 + hstepA, voffA);
;             PG8_WAIT_V(8); PG8_WAIT_L(0); PG8_BAR; PG8_MMA(0, 0, At, B0); PG8_MMA(0, 1, At, B1); PG8_BAR; PG8_SCHED;
;             PG8_LDA(At, 0, 1); PG8_STAGE(PG8_SB(0, 0), b2, voffB); PG8_STAGE(PG8_SB(0, 1), b2 + hstepB, voffB); PG8_STAGE(PG8_SA(0, 0), a2, voffA);
;             PG8_WAIT_V(8); PG8_WAIT_L(0); PG8_BAR; PG8_MMA(1, 0, At, B0); PG8_MMA(1, 1, At, B1); PG8_BAR; PG8_SCHED;
.LBB0_1010:
	s_add_u32 s14, s26, 0xfff80080
	s_addc_u32 s15, s27, -1
	s_add_i32 s41, 0, 0x10000
	s_cmp_eq_u32 s52, 28
	s_cselect_b32 s29, s1, s15
	s_cselect_b32 s28, s3, s14
	s_cselect_b32 s15, s7, s40
	s_cselect_b32 s14, s17, s19
	s_add_i32 s53, 0, 0x14000
	v_add_u32_e32 v142, s41, v1
	v_add_u32_e32 v158, s53, v1
	ds_read_b128 v[130:133], v142
	ds_read_b128 v[134:137], v142 offset:1024
	ds_read_b128 v[138:141], v142 offset:2048
	ds_read_b128 v[142:145], v142 offset:3072
	ds_read_b128 v[146:149], v158
	ds_read_b128 v[150:153], v158 offset:1024
	ds_read_b128 v[154:157], v158 offset:2048
	ds_read_b128 v[158:161], v158 offset:3072
	v_lshl_add_u64 v[178:179], s[26:27], 0, v[196:197]
	s_add_i32 m0, s25, 0xc000
	ds_read_b128 v[162:165], v181
	ds_read_b128 v[166:169], v181 offset:1024
	ds_read_b128 v[170:173], v181 offset:2048
	ds_read_b128 v[174:177], v181 offset:3072
	ds_read_b128 v[200:203], v181 offset:4096
	ds_read_b128 v[204:207], v181 offset:5120
	ds_read_b128 v[208:211], v181 offset:6144
	ds_read_b128 v[212:215], v181 offset:7168
	global_load_lds_dwordx4 v[178:179], off
	v_lshl_add_u64 v[178:179], s[26:27], 0, v[198:199]
	s_add_i32 m0, s25, 0xe000
	s_nop 0
	global_load_lds_dwordx4 v[178:179], off
	s_waitcnt vmcnt(8)
	s_waitcnt lgkmcnt(0)
	s_barrier
	s_setprio 1
	s_waitcnt lgkmcnt(0)
	v_mfma_f32_16x16x32_bf16 v[126:129], v[130:133], v[162:165], v[126:129]
	v_mfma_f32_16x16x32_bf16 v[122:125], v[138:141], v[162:165], v[122:125]
	v_mfma_f32_16x16x32_bf16 v[110:113], v[130:133], v[170:173], v[110:113]
	v_mfma_f32_16x16x32_bf16 v[106:109], v[138:141], v[170:173], v[106:109]
	v_mfma_f32_16x16x32_bf16 v[94:97], v[130:133], v[200:203], v[94:97]
	v_mfma_f32_16x16x32_bf16 v[90:93], v[138:141], v[200:203], v[90:93]
	v_mfma_f32_16x16x32_bf16 v[82:85], v[130:133], v[208:211], v[82:85]
	v_mfma_f32_16x16x32_bf16 v[74:77], v[138:141], v[208:211], v[74:77]
	v_mfma_f32_16x16x32_bf16 v[126:129], v[134:137], v[166:169], v[126:129]
	v_mfma_f32_16x16x32_bf16 v[122:125], v[142:145], v[166:169], v[122:125]
	v_mfma_f32_16x16x32_bf16 v[110:113], v[134:137], v[174:177], v[110:113]
	v_mfma_f32_16x16x32_bf16 v[106:109], v[142:145], v[174:177], v[106:109]
	v_mfma_f32_16x16x32_bf16 v[94:97], v[134:137], v[204:207], v[94:97]
	v_mfma_f32_16x16x32_bf16 v[90:93], v[142:145], v[204:207], v[90:93]
	v_mfma_f32_16x16x32_bf16 v[82:85], v[134:137], v[212:215], v[82:85]
	v_mfma_f32_16x16x32_bf16 v[74:77], v[142:145], v[212:215], v[74:77]
	s_setprio 0
	s_setprio 1
	v_mfma_f32_16x16x32_bf16 v[118:121], v[146:149], v[162:165], v[118:121]
	v_mfma_f32_16x16x32_bf16 v[114:117], v[154:157], v[162:165], v[114:117]
	v_mfma_f32_16x16x32_bf16 v[102:105], v[146:149], v[170:173], v[102:105]
	v_mfma_f32_16x16x32_bf16 v[98:101], v[154:157], v[170:173], v[98:101]
	v_mfma_f32_16x16x32_bf16 v[86:89], v[146:149], v[200:203], v[86:89]
	v_mfma_f32_16x16x32_bf16 v[78:81], v[154:157], v[200:203], v[78:81]
	v_mfma_f32_16x16x32_bf16 v[70:73], v[146:149], v[208:211], v[70:73]
	v_mfma_f32_16x16x32_bf16 v[66:69], v[154:157], v[208:211], v[66:69]
	v_mfma_f32_16x16x32_bf16 v[118:121], v[150:153], v[166:169], v[118:121]
	v_mfma_f32_16x16x32_bf16 v[114:117], v[158:161], v[166:169], v[114:117]
	v_mfma_f32_16x16x32_bf16 v[102:105], v[150:153], v[174:177], v[102:105]
	v_mfma_f32_16x16x32_bf16 v[98:101], v[158:161], v[174:177], v[98:101]
	v_mfma_f32_16x16x32_bf16 v[86:89], v[150:153], v[204:207], v[86:89]
	v_mfma_f32_16x16x32_bf16 v[78:81], v[158:161], v[204:207], v[78:81]
	v_mfma_f32_16x16x32_bf16 v[70:73], v[150:153], v[212:215], v[70:73]
	v_mfma_f32_16x16x32_bf16 v[66:69], v[158:161], v[212:215], v[66:69]
	s_setprio 0
	s_barrier
	s_add_i32 s41, s41, s30
	v_lshl_add_u64 v[178:179], s[14:15], 0, v[190:191]
	s_mov_b32 m0, s41
	ds_read_b128 v[162:165], v181 offset:16384
	ds_read_b128 v[166:169], v181 offset:17408
	ds_read_b128 v[170:173], v181 offset:18432
	ds_read_b128 v[174:177], v181 offset:19456
	ds_read_b128 v[200:203], v181 offset:20480
	ds_read_b128 v[204:207], v181 offset:21504
	ds_read_b128 v[208:211], v181 offset:22528
	ds_read_b128 v[212:215], v181 offset:23552
	global_load_lds_dwordx4 v[178:179], off nt
	s_add_i32 m0, s41, 0x2000
	s_add_u32 s62, s14, 0x80000
	v_lshl_add_u64 v[184:185], s[14:15], 0, v[194:195]
	s_addc_u32 s63, s15, 0
	s_add_i32 s41, s53, s30
	global_load_lds_dwordx4 v[184:185], off nt
	v_lshl_add_u64 v[216:217], s[62:63], 0, v[190:191]
	s_mov_b32 m0, s41
	v_lshl_add_u64 v[218:219], s[28:29], 0, v[192:193]
	global_load_lds_dwordx4 v[216:217], off nt
	v_lshl_add_u64 v[216:217], s[62:63], 0, v[194:195]
	s_add_i32 m0, s41, 0x2000
	s_nop 0
	global_load_lds_dwordx4 v[216:217], off nt
	v_lshl_add_u64 v[216:217], s[28:29], 0, v[188:189]
	s_mov_b32 m0, s25
	s_nop 0
	global_load_lds_dwordx4 v[216:217], off
	s_mov_b32 m0, s31
	s_nop 0
	global_load_lds_dwordx4 v[218:219], off
	s_waitcnt vmcnt(8)
	s_waitcnt lgkmcnt(0)
	s_barrier
; #define PG8_STAGE(bufoff, gbase, voff) do { _Pragma("unroll") for (int _i = 0; _i < 2; ++_i) \
;         __builtin_amdgcn_global_load_lds((const unsigned*)((const char*)(gbase) + (voff)[_i]), (LAS unsigned*)(lds + (bufoff) + ldsw + _i * 8192), 16, 0, 0); } while (0)
; #define PG8_LDA(dst, b, h) do { _Pragma("unroll") for (int m = 0; m < 4; ++m) _Pragma("unroll") for (int k = 0; k < 2; ++k) dst[m][k] = *(const LAS bf16x8*)(lds + PG8_SA(b, h) + aoff + m * 2048 + k * 1024); } while (0)
; #define PG8_LDB(dst, b, h) do { _Pragma("unroll") for (int n = 0; n < 2; ++n) _Pragma("unroll") for (int k = 0; k < 2; ++k) dst[n][k] = *(const LAS bf16x8*)(lds + PG8_SB(b, h) + boff + n * 2048 + k * 1024); } while (0)
; #define PG8_MMA(ai, bj, At, Bt) do { __builtin_amdgcn_s_setprio(1); _Pragma("unroll") for (int m = 0; m < 4; ++m) _Pragma("unroll") for (int n = 0; n < 2; ++n) _Pragma("unroll") for (int k = 0; k < 2; ++k) \
;         acc[ai][bj][m][n] = __builtin_amdgcn_mfma_f32_16x16x32_bf16(Bt[n][k], At[m][k], acc[ai][bj][m][n], 0, 0, 0); __builtin_amdgcn_s_setprio(0); } while (0)
; #define PG8_WAIT_V(n) asm volatile("s_waitcnt vmcnt(" #n ")" ::: "memory")
; #define PG8_WAIT_L(n) asm volatile("s_waitcnt lgkmcnt(" #n ")" ::: "memory")
; #define PG8_BAR __builtin_amdgcn_s_barrier()
; #define PG8_SCHED __builtin_amdgcn_sched_barrier(0)
; template <class Epi>
; __device__ __forceinline__ void gemm_phase(LAS unsigned char* lds, const Gemm g, const StaticOrder& S, const Epi& E) {
;     ...
;             PG8_WAIT_V(8); PG8_WAIT_L(0); PG8_BAR; PG8_MMA(1, 0, At, B0); PG8_MMA(1, 1, At, B1); PG8_BAR; PG8_SCHED;
;             PG8_LDB(B0, 1, 0); PG8_LDB(B1, 1, 1); PG8_SCHED; PG8_LDA(At, 1, 0); PG8_STAGE(PG8_SA(0, 1), a2 + hstepA, voffA);
;             PG8_WAIT_V(8); PG8_WAIT_L(0); PG8_BAR; PG8_MMA(0, 0, At, B0); PG8_MMA(0, 1, At, B1); PG8_BAR; PG8_SCHED;
	s_setprio 1
	s_waitcnt lgkmcnt(0)
	v_mfma_f32_16x16x32_bf16 v[62:65], v[130:133], v[162:165], v[62:65]
	v_mfma_f32_16x16x32_bf16 v[58:61], v[138:141], v[162:165], v[58:61]
	v_mfma_f32_16x16x32_bf16 v[50:53], v[130:133], v[170:173], v[50:53]
	v_mfma_f32_16x16x32_bf16 v[42:45], v[138:141], v[170:173], v[42:45]
	v_mfma_f32_16x16x32_bf16 v[30:33], v[130:133], v[200:203], v[30:33]
	v_mfma_f32_16x16x32_bf16 v[26:29], v[138:141], v[200:203], v[26:29]
	v_mfma_f32_16x16x32_bf16 v[18:21], v[130:133], v[208:211], v[18:21]
	v_mfma_f32_16x16x32_bf16 v[10:13], v[138:141], v[208:211], v[10:13]
	v_mfma_f32_16x16x32_bf16 v[62:65], v[134:137], v[166:169], v[62:65]
	v_mfma_f32_16x16x32_bf16 v[58:61], v[142:145], v[166:169], v[58:61]
	v_mfma_f32_16x16x32_bf16 v[50:53], v[134:137], v[174:177], v[50:53]
	v_mfma_f32_16x16x32_bf16 v[42:45], v[142:145], v[174:177], v[42:45]
	v_mfma_f32_16x16x32_bf16 v[30:33], v[134:137], v[204:207], v[30:33]
	v_mfma_f32_16x16x32_bf16 v[26:29], v[142:145], v[204:207], v[26:29]
	v_mfma_f32_16x16x32_bf16 v[18:21], v[134:137], v[212:215], v[18:21]
	v_mfma_f32_16x16x32_bf16 v[10:13], v[142:145], v[212:215], v[10:13]
	s_setprio 0
	s_setprio 1
	v_mfma_f32_16x16x32_bf16 v[54:57], v[146:149], v[162:165], v[54:57]
	v_mfma_f32_16x16x32_bf16 v[46:49], v[154:157], v[162:165], v[46:49]
	v_mfma_f32_16x16x32_bf16 v[38:41], v[146:149], v[170:173], v[38:41]
	v_mfma_f32_16x16x32_bf16 v[34:37], v[154:157], v[170:173], v[34:37]
	v_mfma_f32_16x16x32_bf16 v[22:25], v[146:149], v[200:203], v[22:25]
	v_mfma_f32_16x16x32_bf16 v[14:17], v[154:157], v[200:203], v[14:17]
	v_mfma_f32_16x16x32_bf16 v[6:9], v[146:149], v[208:211], v[6:9]
	v_mfma_f32_16x16x32_bf16 v[2:5], v[154:157], v[208:211], v[2:5]
	v_mfma_f32_16x16x32_bf16 v[54:57], v[150:153], v[166:169], v[54:57]
	v_mfma_f32_16x16x32_bf16 v[46:49], v[158:161], v[166:169], v[46:49]
	v_mfma_f32_16x16x32_bf16 v[38:41], v[150:153], v[174:177], v[38:41]
	v_mfma_f32_16x16x32_bf16 v[34:37], v[158:161], v[174:177], v[34:37]
	v_mfma_f32_16x16x32_bf16 v[22:25], v[150:153], v[204:207], v[22:25]
	v_mfma_f32_16x16x32_bf16 v[14:17], v[158:161], v[204:207], v[14:17]
	v_mfma_f32_16x16x32_bf16 v[6:9], v[150:153], v[212:215], v[6:9]
	v_mfma_f32_16x16x32_bf16 v[2:5], v[158:161], v[212:215], v[2:5]
	s_setprio 0
	s_barrier
	s_add_i32 s41, 0, 0x18000
	s_add_i32 s53, 0, 0x1c000
	v_add_u32_e32 v142, s41, v1
	v_add_u32_e32 v158, s53, v1
	ds_read_b128 v[130:133], v142
	ds_read_b128 v[134:137], v142 offset:1024
	ds_read_b128 v[138:141], v142 offset:2048
	ds_read_b128 v[142:145], v142 offset:3072
	ds_read_b128 v[146:149], v158
	ds_read_b128 v[150:153], v158 offset:1024
	ds_read_b128 v[154:157], v158 offset:2048
	ds_read_b128 v[158:161], v158 offset:3072
	s_add_u32 s28, s28, 0x80000
	s_addc_u32 s29, s29, 0
	s_mov_b32 m0, s33
	v_lshl_add_u64 v[220:221], s[28:29], 0, v[188:189]
	ds_read_b128 v[162:165], v181 offset:32768
	ds_read_b128 v[166:169], v181 offset:33792
	ds_read_b128 v[170:173], v181 offset:34816
	ds_read_b128 v[174:177], v181 offset:35840
	ds_read_b128 v[200:203], v181 offset:36864
	ds_read_b128 v[204:207], v181 offset:37888
	ds_read_b128 v[208:211], v181 offset:38912
	ds_read_b128 v[212:215], v181 offset:39936
	global_load_lds_dwordx4 v[220:221], off
	v_lshl_add_u64 v[220:221], s[28:29], 0, v[192:193]
	s_mov_b32 m0, s34
	s_nop 0
	global_load_lds_dwordx4 v[220:221], off
	s_waitcnt vmcnt(8)
	s_waitcnt lgkmcnt(0)
	s_barrier
	s_setprio 1
	s_waitcnt lgkmcnt(0)
	v_mfma_f32_16x16x32_bf16 v[126:129], v[130:133], v[162:165], v[126:129]
	v_mfma_f32_16x16x32_bf16 v[122:125], v[138:141], v[162:165], v[122:125]
	v_mfma_f32_16x16x32_bf16 v[110:113], v[130:133], v[170:173], v[110:113]
	v_mfma_f32_16x16x32_bf16 v[106:109], v[138:141], v[170:173], v[106:109]
	v_mfma_f32_16x16x32_bf16 v[94:97], v[130:133], v[200:203], v[94:97]
	v_mfma_f32_16x16x32_bf16 v[90:93], v[138:141], v[200:203], v[90:93]
	v_mfma_f32_16x16x32_bf16 v[82:85], v[130:133], v[208:211], v[82:85]
	v_mfma_f32_16x16x32_bf16 v[74:77], v[138:141], v[208:211], v[74:77]
	v_mfma_f32_16x16x32_bf16 v[126:129], v[134:137], v[166:169], v[126:129]
	v_mfma_f32_16x16x32_bf16 v[122:125], v[142:145], v[166:169], v[122:125]
	v_mfma_f32_16x16x32_bf16 v[110:113], v[134:137], v[174:177], v[110:113]
	v_mfma_f32_16x16x32_bf16 v[106:109], v[142:145], v[174:177], v[106:109]
	v_mfma_f32_16x16x32_bf16 v[94:97], v[134:137], v[204:207], v[94:97]
	v_mfma_f32_16x16x32_bf16 v[90:93], v[142:145], v[204:207], v[90:93]
	v_mfma_f32_16x16x32_bf16 v[82:85], v[134:137], v[212:215], v[82:85]
	v_mfma_f32_16x16x32_bf16 v[74:77], v[142:145], v[212:215], v[74:77]
	s_setprio 0
	s_setprio 1
	v_mfma_f32_16x16x32_bf16 v[118:121], v[146:149], v[162:165], v[118:121]
	v_mfma_f32_16x16x32_bf16 v[114:117], v[154:157], v[162:165], v[114:117]
	v_mfma_f32_16x16x32_bf16 v[102:105], v[146:149], v[170:173], v[102:105]
	v_mfma_f32_16x16x32_bf16 v[98:101], v[154:157], v[170:173], v[98:101]
	v_mfma_f32_16x16x32_bf16 v[86:89], v[146:149], v[200:203], v[86:89]
	v_mfma_f32_16x16x32_bf16 v[78:81], v[154:157], v[200:203], v[78:81]
	v_mfma_f32_16x16x32_bf16 v[70:73], v[146:149], v[208:211], v[70:73]
	v_mfma_f32_16x16x32_bf16 v[66:69], v[154:157], v[208:211], v[66:69]
	v_mfma_f32_16x16x32_bf16 v[118:121], v[150:153], v[166:169], v[118:121]
	v_mfma_f32_16x16x32_bf16 v[114:117], v[158:161], v[166:169], v[114:117]
	v_mfma_f32_16x16x32_bf16 v[102:105], v[150:153], v[174:177], v[102:105]
	v_mfma_f32_16x16x32_bf16 v[98:101], v[158:161], v[174:177], v[98:101]
	v_mfma_f32_16x16x32_bf16 v[86:89], v[150:153], v[204:207], v[86:89]
	v_mfma_f32_16x16x32_bf16 v[78:81], v[158:161], v[204:207], v[78:81]
	v_mfma_f32_16x16x32_bf16 v[70:73], v[150:153], v[212:215], v[70:73]
	v_mfma_f32_16x16x32_bf16 v[66:69], v[158:161], v[212:215], v[66:69]
	s_setprio 0
	s_barrier
; #define PG8_STAGE(bufoff, gbase, voff) do { _Pragma("unroll") for (int _i = 0; _i < 2; ++_i) \
;         __builtin_amdgcn_global_load_lds((const unsigned*)((const char*)(gbase) + (voff)[_i]), (LAS unsigned*)(lds + (bufoff) + ldsw + _i * 8192), 16, 0, 0); } while (0)
; #define PG8_LDA(dst, b, h) do { _Pragma("unroll") for (int m = 0; m < 4; ++m) _Pragma("unroll") for (int k = 0; k < 2; ++k) dst[m][k] = *(const LAS bf16x8*)(lds + PG8_SA(b, h) + aoff + m * 2048 + k * 1024); } while (0)
; #define PG8_MMA(ai, bj, At, Bt) do { __builtin_amdgcn_s_setprio(1); _Pragma("unroll") for (int m = 0; m < 4; ++m) _Pragma("unroll") for (int n = 0; n < 2; ++n) _Pragma("unroll") for (int k = 0; k < 2; ++k) \
;         acc[ai][bj][m][n] = __builtin_amdgcn_mfma_f32_16x16x32_bf16(Bt[n][k], At[m][k], acc[ai][bj][m][n], 0, 0, 0); __builtin_amdgcn_s_setprio(0); } while (0)
; #define PG8_WAIT_V(n) asm volatile("s_waitcnt vmcnt(" #n ")" ::: "memory")
; #define PG8_WAIT_L(n) asm volatile("s_waitcnt lgkmcnt(" #n ")" ::: "memory")
; #define PG8_BAR __builtin_amdgcn_s_barrier()
; #define PG8_SCHED __builtin_amdgcn_sched_barrier(0)
; template <class Epi>
; __device__ __forceinline__ void gemm_phase(LAS unsigned char* lds, const Gemm g, const StaticOrder& S, const Epi& E) {
;     ...
;             PG8_LDA(At, 1, 1); PG8_STAGE(PG8_SB(1, 0), b3, voffB); PG8_STAGE(PG8_SB(1, 1), b3 + hstepB, voffB); PG8_STAGE(PG8_SA(1, 0), a3, voffA);
;             PG8_WAIT_V(8); PG8_WAIT_L(0); PG8_BAR; PG8_MMA(1, 0, At, B0); PG8_MMA(1, 1, At, B1); PG8_BAR; PG8_SCHED;
;         }
	s_add_i32 s28, s41, s30
	v_lshl_add_u64 v[178:179], v[178:179], 0, s[84:85]
	s_mov_b32 m0, s28
	ds_read_b128 v[162:165], v181 offset:49152
	ds_read_b128 v[166:169], v181 offset:50176
	ds_read_b128 v[170:173], v181 offset:51200
	ds_read_b128 v[174:177], v181 offset:52224
	ds_read_b128 v[200:203], v181 offset:53248
	ds_read_b128 v[204:207], v181 offset:54272
	ds_read_b128 v[208:211], v181 offset:55296
	ds_read_b128 v[212:215], v181 offset:56320
	global_load_lds_dwordx4 v[178:179], off nt
	s_add_i32 m0, s28, 0x2000
	s_add_u32 s14, s14, 0x80080
	v_lshl_add_u64 v[178:179], v[184:185], 0, s[84:85]
	s_addc_u32 s15, s15, 0
	s_add_i32 s28, s53, s30
	global_load_lds_dwordx4 v[178:179], off nt
	v_lshl_add_u64 v[178:179], s[14:15], 0, v[190:191]
	s_mov_b32 m0, s28
	s_nop 0
	global_load_lds_dwordx4 v[178:179], off nt
	v_lshl_add_u64 v[178:179], s[14:15], 0, v[194:195]
	s_add_i32 m0, s28, 0x2000
	s_nop 0
	global_load_lds_dwordx4 v[178:179], off nt
	v_lshl_add_u64 v[178:179], v[216:217], 0, s[84:85]
	s_mov_b32 m0, s44
	s_nop 0
	global_load_lds_dwordx4 v[178:179], off
	v_lshl_add_u64 v[178:179], v[218:219], 0, s[84:85]
	s_mov_b32 m0, s45
	s_nop 0
	global_load_lds_dwordx4 v[178:179], off
	s_waitcnt vmcnt(8)
	s_waitcnt lgkmcnt(0)
	s_barrier
	s_setprio 1
	s_waitcnt lgkmcnt(0)
	v_mfma_f32_16x16x32_bf16 v[62:65], v[130:133], v[162:165], v[62:65]
	v_mfma_f32_16x16x32_bf16 v[58:61], v[138:141], v[162:165], v[58:61]
	v_mfma_f32_16x16x32_bf16 v[50:53], v[130:133], v[170:173], v[50:53]
	v_mfma_f32_16x16x32_bf16 v[42:45], v[138:141], v[170:173], v[42:45]
	v_mfma_f32_16x16x32_bf16 v[30:33], v[130:133], v[200:203], v[30:33]
	v_mfma_f32_16x16x32_bf16 v[26:29], v[138:141], v[200:203], v[26:29]
	v_mfma_f32_16x16x32_bf16 v[18:21], v[130:133], v[208:211], v[18:21]
	v_mfma_f32_16x16x32_bf16 v[10:13], v[138:141], v[208:211], v[10:13]
	v_mfma_f32_16x16x32_bf16 v[62:65], v[134:137], v[166:169], v[62:65]
	v_mfma_f32_16x16x32_bf16 v[58:61], v[142:145], v[166:169], v[58:61]
	v_mfma_f32_16x16x32_bf16 v[50:53], v[134:137], v[174:177], v[50:53]
	v_mfma_f32_16x16x32_bf16 v[42:45], v[142:145], v[174:177], v[42:45]
	v_mfma_f32_16x16x32_bf16 v[30:33], v[134:137], v[204:207], v[30:33]
	v_mfma_f32_16x16x32_bf16 v[26:29], v[142:145], v[204:207], v[26:29]
	v_mfma_f32_16x16x32_bf16 v[18:21], v[134:137], v[212:215], v[18:21]
	v_mfma_f32_16x16x32_bf16 v[10:13], v[142:145], v[212:215], v[10:13]
	s_setprio 0
	s_setprio 1
	v_mfma_f32_16x16x32_bf16 v[54:57], v[146:149], v[162:165], v[54:57]
	v_mfma_f32_16x16x32_bf16 v[46:49], v[154:157], v[162:165], v[46:49]
	v_mfma_f32_16x16x32_bf16 v[38:41], v[146:149], v[170:173], v[38:41]
	v_mfma_f32_16x16x32_bf16 v[34:37], v[154:157], v[170:173], v[34:37]
	v_mfma_f32_16x16x32_bf16 v[22:25], v[146:149], v[200:203], v[22:25]
	v_mfma_f32_16x16x32_bf16 v[14:17], v[154:157], v[200:203], v[14:17]
	v_mfma_f32_16x16x32_bf16 v[6:9], v[146:149], v[208:211], v[6:9]
	v_mfma_f32_16x16x32_bf16 v[2:5], v[154:157], v[208:211], v[2:5]
	v_mfma_f32_16x16x32_bf16 v[54:57], v[150:153], v[166:169], v[54:57]
	v_mfma_f32_16x16x32_bf16 v[46:49], v[158:161], v[166:169], v[46:49]
	v_mfma_f32_16x16x32_bf16 v[38:41], v[150:153], v[174:177], v[38:41]
	v_mfma_f32_16x16x32_bf16 v[34:37], v[158:161], v[174:177], v[34:37]
	v_mfma_f32_16x16x32_bf16 v[22:25], v[150:153], v[204:207], v[22:25]
	v_mfma_f32_16x16x32_bf16 v[14:17], v[158:161], v[204:207], v[14:17]
	v_mfma_f32_16x16x32_bf16 v[6:9], v[150:153], v[212:215], v[6:9]
	v_mfma_f32_16x16x32_bf16 v[2:5], v[158:161], v[212:215], v[2:5]
	s_setprio 0
	s_barrier
	s_add_i32 s52, s52, 2
	s_add_u32 s26, s26, 0x100
	s_addc_u32 s27, s27, 0
	s_add_u32 s19, s19, 0x100
	s_addc_u32 s40, s40, 0
	s_cmp_gt_u32 s52, 29
	s_cbranch_scc0 .LBB0_1010
	s_and_b64 vcc, exec, s[12:13]
	s_cbranch_vccz .LBB0_1013
	s_barrier

; #define PG8_STAGE(bufoff, gbase, voff) do { _Pragma("unroll") for (int _i = 0; _i < 2; ++_i) \
;         __builtin_amdgcn_global_load_lds((const unsigned*)((const char*)(gbase) + (voff)[_i]), (LAS unsigned*)(lds + (bufoff) + ldsw + _i * 8192), 16, 0, 0); } while (0)
; #define PG8_LDA(dst, b, h) do { _Pragma("unroll") for (int m = 0; m < 4; ++m) _Pragma("unroll") for (int k = 0; k < 2; ++k) dst[m][k] = *(const LAS bf16x8*)(lds + PG8_SA(b, h) + aoff + m * 2048 + k * 1024); } while (0)
; #define PG8_LDB(dst, b, h) do { _Pragma("unroll") for (int n = 0; n < 2; ++n) _Pragma("unroll") for (int k = 0; k < 2; ++k) dst[n][k] = *(const LAS bf16x8*)(lds + PG8_SB(b, h) + boff + n * 2048 + k * 1024); } while (0)
; #define PG8_MMA(ai, bj, At, Bt) do { __builtin_amdgcn_s_setprio(1); _Pragma("unroll") for (int m = 0; m < 4; ++m) _Pragma("unroll") for (int n = 0; n < 2; ++n) _Pragma("unroll") for (int k = 0; k < 2; ++k) \
;         acc[ai][bj][m][n] = __builtin_amdgcn_mfma_f32_16x16x32_bf16(Bt[n][k], At[m][k], acc[ai][bj][m][n], 0, 0, 0); __builtin_amdgcn_s_setprio(0); } while (0)
; #define PG8_WAIT_V(n) asm volatile("s_waitcnt vmcnt(" #n ")" ::: "memory")
; #define PG8_WAIT_L(n) asm volatile("s_waitcnt lgkmcnt(" #n ")" ::: "memory")
; #define PG8_BAR __builtin_amdgcn_s_barrier()
; #define PG8_SCHED __builtin_amdgcn_sched_barrier(0)
; template <class Epi>
; __device__ __forceinline__ void gemm_phase(LAS unsigned char* lds, const Gemm g, const StaticOrder& S, const Epi& E) {
;     ...
;             PG8_LDB(B0, 0, 0); PG8_LDB(B1, 0, 1); PG8_SCHED; PG8_LDA(At, 0, 0); PG8_STAGE(PG8_SA(1, 1), a1 + hstepA, voffA);
;             PG8_WAIT_V(8); PG8_WAIT_L(0); PG8_BAR; PG8_MMA(0, 0, At, B0); PG8_MMA(0, 1, At, B1); PG8_BAR; PG8_SCHED;
;             PG8_LDA(At, 0, 1); PG8_STAGE(PG8_SB(0, 0), b2, voffB); PG8_STAGE(PG8_SB(0, 1), b2 + hstepB, voffB); PG8_STAGE(PG8_SA(0, 0), a2, voffA);
;             PG8_WAIT_V(8); PG8_WAIT_L(0); PG8_BAR; PG8_MMA(1, 0, At, B0); PG8_MMA(1, 1, At, B1); PG8_BAR; PG8_SCHED;
.LBB0_1107:
	s_add_u32 s34, vcc_lo, 0xfff80080
	s_addc_u32 s35, vcc_hi, -1
	s_add_i32 s76, 0, 0x10000
	s_cmp_eq_u32 s41, 28
	s_cselect_b32 s69, s3, s35
	s_cselect_b32 s68, s7, s34
	s_cselect_b32 s35, s13, s87
	s_cselect_b32 s34, s40, s65
	s_add_i32 s78, 0, 0x14000
	v_add_u32_e32 v142, s76, v1
	v_add_u32_e32 v163, s78, v1
	ds_read_b128 v[130:133], v142
	ds_read_b128 v[134:137], v142 offset:1024
	ds_read_b128 v[138:141], v142 offset:2048
	ds_read_b128 v[142:145], v142 offset:3072
	ds_read_b128 v[158:161], v163
	ds_read_b128 v[164:167], v163 offset:1024
	ds_read_b128 v[168:171], v163 offset:2048
	ds_read_b128 v[172:175], v163 offset:3072
	v_lshl_add_u64 v[184:185], vcc, 0, v[154:155]
	s_add_i32 m0, s70, 0xc000
	ds_read_b128 v[176:179], v162
	ds_read_b128 v[188:191], v162 offset:1024
	ds_read_b128 v[192:195], v162 offset:2048
	ds_read_b128 v[196:199], v162 offset:3072
	ds_read_b128 v[200:203], v162 offset:4096
	ds_read_b128 v[204:207], v162 offset:5120
	ds_read_b128 v[208:211], v162 offset:6144
	ds_read_b128 v[212:215], v162 offset:7168
	global_load_lds_dwordx4 v[184:185], off
	v_lshl_add_u64 v[184:185], vcc, 0, v[156:157]
	s_add_i32 m0, s70, 0xe000
	s_nop 0
	global_load_lds_dwordx4 v[184:185], off
	s_waitcnt vmcnt(8)
	s_waitcnt lgkmcnt(0)
	s_barrier
	s_setprio 1
	s_waitcnt lgkmcnt(0)
	v_mfma_f32_16x16x32_bf16 v[126:129], v[130:133], v[176:179], v[126:129]
	v_mfma_f32_16x16x32_bf16 v[122:125], v[138:141], v[176:179], v[122:125]
	v_mfma_f32_16x16x32_bf16 v[114:117], v[130:133], v[192:195], v[114:117]
	v_mfma_f32_16x16x32_bf16 v[106:109], v[138:141], v[192:195], v[106:109]
	v_mfma_f32_16x16x32_bf16 v[98:101], v[130:133], v[200:203], v[98:101]
	v_mfma_f32_16x16x32_bf16 v[90:93], v[138:141], v[200:203], v[90:93]
	v_mfma_f32_16x16x32_bf16 v[82:85], v[130:133], v[208:211], v[82:85]
	v_mfma_f32_16x16x32_bf16 v[74:77], v[138:141], v[208:211], v[74:77]
	v_mfma_f32_16x16x32_bf16 v[126:129], v[134:137], v[188:191], v[126:129]
	v_mfma_f32_16x16x32_bf16 v[122:125], v[142:145], v[188:191], v[122:125]
	v_mfma_f32_16x16x32_bf16 v[114:117], v[134:137], v[196:199], v[114:117]
	v_mfma_f32_16x16x32_bf16 v[106:109], v[142:145], v[196:199], v[106:109]
	v_mfma_f32_16x16x32_bf16 v[98:101], v[134:137], v[204:207], v[98:101]
	v_mfma_f32_16x16x32_bf16 v[90:93], v[142:145], v[204:207], v[90:93]
	v_mfma_f32_16x16x32_bf16 v[82:85], v[134:137], v[212:215], v[82:85]
	v_mfma_f32_16x16x32_bf16 v[74:77], v[142:145], v[212:215], v[74:77]
	s_setprio 0
	s_setprio 1
	v_mfma_f32_16x16x32_bf16 v[118:121], v[158:161], v[176:179], v[118:121]
	v_mfma_f32_16x16x32_bf16 v[110:113], v[168:171], v[176:179], v[110:113]
	v_mfma_f32_16x16x32_bf16 v[102:105], v[158:161], v[192:195], v[102:105]
	v_mfma_f32_16x16x32_bf16 v[94:97], v[168:171], v[192:195], v[94:97]
	v_mfma_f32_16x16x32_bf16 v[86:89], v[158:161], v[200:203], v[86:89]
	v_mfma_f32_16x16x32_bf16 v[78:81], v[168:171], v[200:203], v[78:81]
	v_mfma_f32_16x16x32_bf16 v[70:73], v[158:161], v[208:211], v[70:73]
	v_mfma_f32_16x16x32_bf16 v[66:69], v[168:171], v[208:211], v[66:69]
	v_mfma_f32_16x16x32_bf16 v[118:121], v[164:167], v[188:191], v[118:121]
	v_mfma_f32_16x16x32_bf16 v[110:113], v[172:175], v[188:191], v[110:113]
	v_mfma_f32_16x16x32_bf16 v[102:105], v[164:167], v[196:199], v[102:105]
	v_mfma_f32_16x16x32_bf16 v[94:97], v[172:175], v[196:199], v[94:97]
	v_mfma_f32_16x16x32_bf16 v[86:89], v[164:167], v[204:207], v[86:89]
	v_mfma_f32_16x16x32_bf16 v[78:81], v[172:175], v[204:207], v[78:81]
	v_mfma_f32_16x16x32_bf16 v[70:73], v[164:167], v[212:215], v[70:73]
	v_mfma_f32_16x16x32_bf16 v[66:69], v[172:175], v[212:215], v[66:69]
	s_setprio 0
	s_barrier
	s_add_i32 s76, s76, s42
	v_lshl_add_u64 v[184:185], s[34:35], 0, v[148:149]
	s_mov_b32 m0, s76
	ds_read_b128 v[176:179], v162 offset:16384
	ds_read_b128 v[188:191], v162 offset:17408
	ds_read_b128 v[192:195], v162 offset:18432
	ds_read_b128 v[196:199], v162 offset:19456
	ds_read_b128 v[200:203], v162 offset:20480
	ds_read_b128 v[204:207], v162 offset:21504
	ds_read_b128 v[208:211], v162 offset:22528
	ds_read_b128 v[212:215], v162 offset:23552
	global_load_lds_dwordx4 v[184:185], off nt
	s_add_i32 m0, s76, 0x2000
	s_add_u32 s76, s34, 0x80000
	v_lshl_add_u64 v[216:217], s[34:35], 0, v[152:153]
	s_addc_u32 s77, s35, 0
	s_add_i32 s78, s78, s42
	global_load_lds_dwordx4 v[216:217], off nt
	v_lshl_add_u64 v[218:219], s[76:77], 0, v[148:149]
	s_mov_b32 m0, s78
	v_lshl_add_u64 v[220:221], s[68:69], 0, v[150:151]
	global_load_lds_dwordx4 v[218:219], off nt
	v_lshl_add_u64 v[218:219], s[76:77], 0, v[152:153]
	s_add_i32 m0, s78, 0x2000
	s_nop 0
	global_load_lds_dwordx4 v[218:219], off nt
	v_lshl_add_u64 v[218:219], s[68:69], 0, v[146:147]
	s_mov_b32 m0, s70
	s_nop 0
	global_load_lds_dwordx4 v[218:219], off
	s_mov_b32 m0, s91
	s_nop 0
	global_load_lds_dwordx4 v[220:221], off
	s_waitcnt vmcnt(8)
	s_waitcnt lgkmcnt(0)
	s_barrier
; #define PG8_STAGE(bufoff, gbase, voff) do { _Pragma("unroll") for (int _i = 0; _i < 2; ++_i) \
;         __builtin_amdgcn_global_load_lds((const unsigned*)((const char*)(gbase) + (voff)[_i]), (LAS unsigned*)(lds + (bufoff) + ldsw + _i * 8192), 16, 0, 0); } while (0)
; #define PG8_LDA(dst, b, h) do { _Pragma("unroll") for (int m = 0; m < 4; ++m) _Pragma("unroll") for (int k = 0; k < 2; ++k) dst[m][k] = *(const LAS bf16x8*)(lds + PG8_SA(b, h) + aoff + m * 2048 + k * 1024); } while (0)
; #define PG8_LDB(dst, b, h) do { _Pragma("unroll") for (int n = 0; n < 2; ++n) _Pragma("unroll") for (int k = 0; k < 2; ++k) dst[n][k] = *(const LAS bf16x8*)(lds + PG8_SB(b, h) + boff + n * 2048 + k * 1024); } while (0)
; #define PG8_MMA(ai, bj, At, Bt) do { __builtin_amdgcn_s_setprio(1); _Pragma("unroll") for (int m = 0; m < 4; ++m) _Pragma("unroll") for (int n = 0; n < 2; ++n) _Pragma("unroll") for (int k = 0; k < 2; ++k) \
;         acc[ai][bj][m][n] = __builtin_amdgcn_mfma_f32_16x16x32_bf16(Bt[n][k], At[m][k], acc[ai][bj][m][n], 0, 0, 0); __builtin_amdgcn_s_setprio(0); } while (0)
; #define PG8_WAIT_V(n) asm volatile("s_waitcnt vmcnt(" #n ")" ::: "memory")
; #define PG8_WAIT_L(n) asm volatile("s_waitcnt lgkmcnt(" #n ")" ::: "memory")
; #define PG8_BAR __builtin_amdgcn_s_barrier()
; #define PG8_SCHED __builtin_amdgcn_sched_barrier(0)
; template <class Epi>
; __device__ __forceinline__ void gemm_phase(LAS unsigned char* lds, const Gemm g, const StaticOrder& S, const Epi& E) {
;     ...
;             PG8_WAIT_V(8); PG8_WAIT_L(0); PG8_BAR; PG8_MMA(1, 0, At, B0); PG8_MMA(1, 1, At, B1); PG8_BAR; PG8_SCHED;
;             PG8_LDB(B0, 1, 0); PG8_LDB(B1, 1, 1); PG8_SCHED; PG8_LDA(At, 1, 0); PG8_STAGE(PG8_SA(0, 1), a2 + hstepA, voffA);
;             PG8_WAIT_V(8); PG8_WAIT_L(0); PG8_BAR; PG8_MMA(0, 0, At, B0); PG8_MMA(0, 1, At, B1); PG8_BAR; PG8_SCHED;
	s_setprio 1
	s_waitcnt lgkmcnt(0)
	v_mfma_f32_16x16x32_bf16 v[62:65], v[130:133], v[176:179], v[62:65]
	v_mfma_f32_16x16x32_bf16 v[58:61], v[138:141], v[176:179], v[58:61]
	v_mfma_f32_16x16x32_bf16 v[54:57], v[130:133], v[192:195], v[54:57]
	v_mfma_f32_16x16x32_bf16 v[46:49], v[138:141], v[192:195], v[46:49]
	v_mfma_f32_16x16x32_bf16 v[38:41], v[130:133], v[200:203], v[38:41]
	v_mfma_f32_16x16x32_bf16 v[30:33], v[138:141], v[200:203], v[30:33]
	v_mfma_f32_16x16x32_bf16 v[22:25], v[130:133], v[208:211], v[22:25]
	v_mfma_f32_16x16x32_bf16 v[14:17], v[138:141], v[208:211], v[14:17]
	v_mfma_f32_16x16x32_bf16 v[62:65], v[134:137], v[188:191], v[62:65]
	v_mfma_f32_16x16x32_bf16 v[58:61], v[142:145], v[188:191], v[58:61]
	v_mfma_f32_16x16x32_bf16 v[54:57], v[134:137], v[196:199], v[54:57]
	v_mfma_f32_16x16x32_bf16 v[46:49], v[142:145], v[196:199], v[46:49]
	v_mfma_f32_16x16x32_bf16 v[38:41], v[134:137], v[204:207], v[38:41]
	v_mfma_f32_16x16x32_bf16 v[30:33], v[142:145], v[204:207], v[30:33]
	v_mfma_f32_16x16x32_bf16 v[22:25], v[134:137], v[212:215], v[22:25]
	v_mfma_f32_16x16x32_bf16 v[14:17], v[142:145], v[212:215], v[14:17]
	s_setprio 0
	s_setprio 1
	v_mfma_f32_16x16x32_bf16 v[50:53], v[158:161], v[176:179], v[50:53]
	v_mfma_f32_16x16x32_bf16 v[42:45], v[168:171], v[176:179], v[42:45]
	v_mfma_f32_16x16x32_bf16 v[34:37], v[158:161], v[192:195], v[34:37]
	v_mfma_f32_16x16x32_bf16 v[26:29], v[168:171], v[192:195], v[26:29]
	v_mfma_f32_16x16x32_bf16 v[18:21], v[158:161], v[200:203], v[18:21]
	v_mfma_f32_16x16x32_bf16 v[10:13], v[168:171], v[200:203], v[10:13]
	v_mfma_f32_16x16x32_bf16 v[6:9], v[158:161], v[208:211], v[6:9]
	v_mfma_f32_16x16x32_bf16 v[2:5], v[168:171], v[208:211], v[2:5]
	v_mfma_f32_16x16x32_bf16 v[50:53], v[164:167], v[188:191], v[50:53]
	v_mfma_f32_16x16x32_bf16 v[42:45], v[172:175], v[188:191], v[42:45]
	v_mfma_f32_16x16x32_bf16 v[34:37], v[164:167], v[196:199], v[34:37]
	v_mfma_f32_16x16x32_bf16 v[26:29], v[172:175], v[196:199], v[26:29]
	v_mfma_f32_16x16x32_bf16 v[18:21], v[164:167], v[204:207], v[18:21]
	v_mfma_f32_16x16x32_bf16 v[10:13], v[172:175], v[204:207], v[10:13]
	v_mfma_f32_16x16x32_bf16 v[6:9], v[164:167], v[212:215], v[6:9]
	v_mfma_f32_16x16x32_bf16 v[2:5], v[172:175], v[212:215], v[2:5]
	s_setprio 0
	s_barrier
	s_add_i32 s76, 0, 0x18000
	s_add_i32 s77, 0, 0x1c000
	v_add_u32_e32 v142, s76, v1
	v_add_u32_e32 v163, s77, v1
	ds_read_b128 v[130:133], v142
	ds_read_b128 v[134:137], v142 offset:1024
	ds_read_b128 v[138:141], v142 offset:2048
	ds_read_b128 v[142:145], v142 offset:3072
	ds_read_b128 v[158:161], v163
	ds_read_b128 v[164:167], v163 offset:1024
	ds_read_b128 v[168:171], v163 offset:2048
	ds_read_b128 v[172:175], v163 offset:3072
	s_add_u32 s68, s68, 0x80000
	s_addc_u32 s69, s69, 0
	s_mov_b32 m0, s62
	v_lshl_add_u64 v[222:223], s[68:69], 0, v[146:147]
	ds_read_b128 v[176:179], v162 offset:32768
	ds_read_b128 v[188:191], v162 offset:33792
	ds_read_b128 v[192:195], v162 offset:34816
	ds_read_b128 v[196:199], v162 offset:35840
	ds_read_b128 v[200:203], v162 offset:36864
	ds_read_b128 v[204:207], v162 offset:37888
	ds_read_b128 v[208:211], v162 offset:38912
	ds_read_b128 v[212:215], v162 offset:39936
	global_load_lds_dwordx4 v[222:223], off
	v_lshl_add_u64 v[222:223], s[68:69], 0, v[150:151]
	s_mov_b32 m0, s63
	s_nop 0
	global_load_lds_dwordx4 v[222:223], off
	s_waitcnt vmcnt(8)
	s_waitcnt lgkmcnt(0)
	s_barrier
	s_setprio 1
	s_waitcnt lgkmcnt(0)
	v_mfma_f32_16x16x32_bf16 v[126:129], v[130:133], v[176:179], v[126:129]
	v_mfma_f32_16x16x32_bf16 v[122:125], v[138:141], v[176:179], v[122:125]
	v_mfma_f32_16x16x32_bf16 v[114:117], v[130:133], v[192:195], v[114:117]
	v_mfma_f32_16x16x32_bf16 v[106:109], v[138:141], v[192:195], v[106:109]
	v_mfma_f32_16x16x32_bf16 v[98:101], v[130:133], v[200:203], v[98:101]
	v_mfma_f32_16x16x32_bf16 v[90:93], v[138:141], v[200:203], v[90:93]
	v_mfma_f32_16x16x32_bf16 v[82:85], v[130:133], v[208:211], v[82:85]
	v_mfma_f32_16x16x32_bf16 v[74:77], v[138:141], v[208:211], v[74:77]
	v_mfma_f32_16x16x32_bf16 v[126:129], v[134:137], v[188:191], v[126:129]
	v_mfma_f32_16x16x32_bf16 v[122:125], v[142:145], v[188:191], v[122:125]
	v_mfma_f32_16x16x32_bf16 v[114:117], v[134:137], v[196:199], v[114:117]
	v_mfma_f32_16x16x32_bf16 v[106:109], v[142:145], v[196:199], v[106:109]
	v_mfma_f32_16x16x32_bf16 v[98:101], v[134:137], v[204:207], v[98:101]
	v_mfma_f32_16x16x32_bf16 v[90:93], v[142:145], v[204:207], v[90:93]
	v_mfma_f32_16x16x32_bf16 v[82:85], v[134:137], v[212:215], v[82:85]
	v_mfma_f32_16x16x32_bf16 v[74:77], v[142:145], v[212:215], v[74:77]
	s_setprio 0
	s_setprio 1
	v_mfma_f32_16x16x32_bf16 v[118:121], v[158:161], v[176:179], v[118:121]
	v_mfma_f32_16x16x32_bf16 v[110:113], v[168:171], v[176:179], v[110:113]
	v_mfma_f32_16x16x32_bf16 v[102:105], v[158:161], v[192:195], v[102:105]
	v_mfma_f32_16x16x32_bf16 v[94:97], v[168:171], v[192:195], v[94:97]
	v_mfma_f32_16x16x32_bf16 v[86:89], v[158:161], v[200:203], v[86:89]
	v_mfma_f32_16x16x32_bf16 v[78:81], v[168:171], v[200:203], v[78:81]
	v_mfma_f32_16x16x32_bf16 v[70:73], v[158:161], v[208:211], v[70:73]
	v_mfma_f32_16x16x32_bf16 v[66:69], v[168:171], v[208:211], v[66:69]
	v_mfma_f32_16x16x32_bf16 v[118:121], v[164:167], v[188:191], v[118:121]
	v_mfma_f32_16x16x32_bf16 v[110:113], v[172:175], v[188:191], v[110:113]
	v_mfma_f32_16x16x32_bf16 v[102:105], v[164:167], v[196:199], v[102:105]
	v_mfma_f32_16x16x32_bf16 v[94:97], v[172:175], v[196:199], v[94:97]
	v_mfma_f32_16x16x32_bf16 v[86:89], v[164:167], v[204:207], v[86:89]
	v_mfma_f32_16x16x32_bf16 v[78:81], v[172:175], v[204:207], v[78:81]
	v_mfma_f32_16x16x32_bf16 v[70:73], v[164:167], v[212:215], v[70:73]
	v_mfma_f32_16x16x32_bf16 v[66:69], v[172:175], v[212:215], v[66:69]
	s_setprio 0
	s_barrier
; #define PG8_STAGE(bufoff, gbase, voff) do { _Pragma("unroll") for (int _i = 0; _i < 2; ++_i) \
;         __builtin_amdgcn_global_load_lds((const unsigned*)((const char*)(gbase) + (voff)[_i]), (LAS unsigned*)(lds + (bufoff) + ldsw + _i * 8192), 16, 0, 0); } while (0)
; #define PG8_LDA(dst, b, h) do { _Pragma("unroll") for (int m = 0; m < 4; ++m) _Pragma("unroll") for (int k = 0; k < 2; ++k) dst[m][k] = *(const LAS bf16x8*)(lds + PG8_SA(b, h) + aoff + m * 2048 + k * 1024); } while (0)
; #define PG8_MMA(ai, bj, At, Bt) do { __builtin_amdgcn_s_setprio(1); _Pragma("unroll") for (int m = 0; m < 4; ++m) _Pragma("unroll") for (int n = 0; n < 2; ++n) _Pragma("unroll") for (int k = 0; k < 2; ++k) \
;         acc[ai][bj][m][n] = __builtin_amdgcn_mfma_f32_16x16x32_bf16(Bt[n][k], At[m][k], acc[ai][bj][m][n], 0, 0, 0); __builtin_amdgcn_s_setprio(0); } while (0)
; #define PG8_WAIT_V(n) asm volatile("s_waitcnt vmcnt(" #n ")" ::: "memory")
; #define PG8_WAIT_L(n) asm volatile("s_waitcnt lgkmcnt(" #n ")" ::: "memory")
; #define PG8_BAR __builtin_amdgcn_s_barrier()
; #define PG8_SCHED __builtin_amdgcn_sched_barrier(0)
; template <class Epi>
; __device__ __forceinline__ void gemm_phase(LAS unsigned char* lds, const Gemm g, const StaticOrder& S, const Epi& E) {
;     ...
;             PG8_LDA(At, 1, 1); PG8_STAGE(PG8_SB(1, 0), b3, voffB); PG8_STAGE(PG8_SB(1, 1), b3 + hstepB, voffB); PG8_STAGE(PG8_SA(1, 0), a3, voffA);
;             PG8_WAIT_V(8); PG8_WAIT_L(0); PG8_BAR; PG8_MMA(1, 0, At, B0); PG8_MMA(1, 1, At, B1); PG8_BAR; PG8_SCHED;
;         }
	s_add_i32 s68, s76, s42
	v_lshl_add_u64 v[184:185], v[184:185], 0, s[84:85]
	s_mov_b32 m0, s68
	ds_read_b128 v[176:179], v162 offset:49152
	ds_read_b128 v[188:191], v162 offset:50176
	ds_read_b128 v[192:195], v162 offset:51200
	ds_read_b128 v[196:199], v162 offset:52224
	ds_read_b128 v[200:203], v162 offset:53248
	ds_read_b128 v[204:207], v162 offset:54272
	ds_read_b128 v[208:211], v162 offset:55296
	ds_read_b128 v[212:215], v162 offset:56320
	global_load_lds_dwordx4 v[184:185], off nt
	s_add_i32 m0, s68, 0x2000
	s_add_u32 s34, s34, 0x80080
	v_lshl_add_u64 v[184:185], v[216:217], 0, s[84:85]
	s_addc_u32 s35, s35, 0
	s_add_i32 s68, s77, s42
	global_load_lds_dwordx4 v[184:185], off nt
	v_lshl_add_u64 v[184:185], s[34:35], 0, v[148:149]
	s_mov_b32 m0, s68
	s_nop 0
	global_load_lds_dwordx4 v[184:185], off nt
	v_lshl_add_u64 v[184:185], s[34:35], 0, v[152:153]
	s_add_i32 m0, s68, 0x2000
	s_nop 0
	global_load_lds_dwordx4 v[184:185], off nt
	v_lshl_add_u64 v[184:185], v[218:219], 0, s[84:85]
	s_mov_b32 m0, s94
	s_nop 0
	global_load_lds_dwordx4 v[184:185], off
	v_lshl_add_u64 v[184:185], v[220:221], 0, s[84:85]
	s_mov_b32 m0, s95
	s_nop 0
	global_load_lds_dwordx4 v[184:185], off
	s_waitcnt vmcnt(8)
	s_waitcnt lgkmcnt(0)
	s_barrier
	s_setprio 1
	s_waitcnt lgkmcnt(0)
	v_mfma_f32_16x16x32_bf16 v[62:65], v[130:133], v[176:179], v[62:65]
	v_mfma_f32_16x16x32_bf16 v[58:61], v[138:141], v[176:179], v[58:61]
	v_mfma_f32_16x16x32_bf16 v[54:57], v[130:133], v[192:195], v[54:57]
	v_mfma_f32_16x16x32_bf16 v[46:49], v[138:141], v[192:195], v[46:49]
	v_mfma_f32_16x16x32_bf16 v[38:41], v[130:133], v[200:203], v[38:41]
	v_mfma_f32_16x16x32_bf16 v[30:33], v[138:141], v[200:203], v[30:33]
	v_mfma_f32_16x16x32_bf16 v[22:25], v[130:133], v[208:211], v[22:25]
	v_mfma_f32_16x16x32_bf16 v[14:17], v[138:141], v[208:211], v[14:17]
	v_mfma_f32_16x16x32_bf16 v[62:65], v[134:137], v[188:191], v[62:65]
	v_mfma_f32_16x16x32_bf16 v[58:61], v[142:145], v[188:191], v[58:61]
	v_mfma_f32_16x16x32_bf16 v[54:57], v[134:137], v[196:199], v[54:57]
	v_mfma_f32_16x16x32_bf16 v[46:49], v[142:145], v[196:199], v[46:49]
	v_mfma_f32_16x16x32_bf16 v[38:41], v[134:137], v[204:207], v[38:41]
	v_mfma_f32_16x16x32_bf16 v[30:33], v[142:145], v[204:207], v[30:33]
	v_mfma_f32_16x16x32_bf16 v[22:25], v[134:137], v[212:215], v[22:25]
	v_mfma_f32_16x16x32_bf16 v[14:17], v[142:145], v[212:215], v[14:17]
	s_setprio 0
	s_setprio 1
	v_mfma_f32_16x16x32_bf16 v[50:53], v[158:161], v[176:179], v[50:53]
	v_mfma_f32_16x16x32_bf16 v[42:45], v[168:171], v[176:179], v[42:45]
	v_mfma_f32_16x16x32_bf16 v[34:37], v[158:161], v[192:195], v[34:37]
	v_mfma_f32_16x16x32_bf16 v[26:29], v[168:171], v[192:195], v[26:29]
	v_mfma_f32_16x16x32_bf16 v[18:21], v[158:161], v[200:203], v[18:21]
	v_mfma_f32_16x16x32_bf16 v[10:13], v[168:171], v[200:203], v[10:13]
	v_mfma_f32_16x16x32_bf16 v[6:9], v[158:161], v[208:211], v[6:9]
	v_mfma_f32_16x16x32_bf16 v[2:5], v[168:171], v[208:211], v[2:5]
	v_mfma_f32_16x16x32_bf16 v[50:53], v[164:167], v[188:191], v[50:53]
	v_mfma_f32_16x16x32_bf16 v[42:45], v[172:175], v[188:191], v[42:45]
	v_mfma_f32_16x16x32_bf16 v[34:37], v[164:167], v[196:199], v[34:37]
	v_mfma_f32_16x16x32_bf16 v[26:29], v[172:175], v[196:199], v[26:29]
	v_mfma_f32_16x16x32_bf16 v[18:21], v[164:167], v[204:207], v[18:21]
	v_mfma_f32_16x16x32_bf16 v[10:13], v[172:175], v[204:207], v[10:13]
	v_mfma_f32_16x16x32_bf16 v[6:9], v[164:167], v[212:215], v[6:9]
	v_mfma_f32_16x16x32_bf16 v[2:5], v[172:175], v[212:215], v[2:5]
	s_setprio 0
	s_barrier
	s_add_i32 s41, s41, 2
	s_add_u32 vcc_lo, vcc_lo, 0x100
	s_addc_u32 vcc_hi, vcc_hi, 0
	s_add_u32 s65, s65, 0x100
	s_addc_u32 s87, s87, 0
	s_cmp_gt_u32 s41, 29
	s_cbranch_scc0 .LBB0_1107
	s_and_b64 vcc, exec, s[10:11]
	s_cbranch_vccz .LBB0_1110
	s_barrier

; #define PG8_STAGE(bufoff, gbase, voff) do { _Pragma("unroll") for (int _i = 0; _i < 2; ++_i) \
;         __builtin_amdgcn_global_load_lds((const unsigned*)((const char*)(gbase) + (voff)[_i]), (LAS unsigned*)(lds + (bufoff) + ldsw + _i * 8192), 16, 0, 0); } while (0)
; #define PG8_LDA(dst, b, h) do { _Pragma("unroll") for (int m = 0; m < 4; ++m) _Pragma("unroll") for (int k = 0; k < 2; ++k) dst[m][k] = *(const LAS bf16x8*)(lds + PG8_SA(b, h) + aoff + m * 2048 + k * 1024); } while (0)
; #define PG8_LDB(dst, b, h) do { _Pragma("unroll") for (int n = 0; n < 2; ++n) _Pragma("unroll") for (int k = 0; k < 2; ++k) dst[n][k] = *(const LAS bf16x8*)(lds + PG8_SB(b, h) + boff + n * 2048 + k * 1024); } while (0)
; #define PG8_MMA(ai, bj, At, Bt) do { __builtin_amdgcn_s_setprio(1); _Pragma("unroll") for (int m = 0; m < 4; ++m) _Pragma("unroll") for (int n = 0; n < 2; ++n) _Pragma("unroll") for (int k = 0; k < 2; ++k) \
;         acc[ai][bj][m][n] = __builtin_amdgcn_mfma_f32_16x16x32_bf16(Bt[n][k], At[m][k], acc[ai][bj][m][n], 0, 0, 0); __builtin_amdgcn_s_setprio(0); } while (0)
; #define PG8_WAIT_V(n) asm volatile("s_waitcnt vmcnt(" #n ")" ::: "memory")
; #define PG8_WAIT_L(n) asm volatile("s_waitcnt lgkmcnt(" #n ")" ::: "memory")
; #define PG8_BAR __builtin_amdgcn_s_barrier()
; #define PG8_SCHED __builtin_amdgcn_sched_barrier(0)
; template <class Epi>
; __device__ __forceinline__ void gemm_phase(LAS unsigned char* lds, const Gemm g, const StaticOrder& S, const Epi& E) {
;     ...
;             PG8_LDB(B0, 0, 0); PG8_LDB(B1, 0, 1); PG8_SCHED; PG8_LDA(At, 0, 0); PG8_STAGE(PG8_SA(1, 1), a1 + hstepA, voffA);
;             PG8_WAIT_V(8); PG8_WAIT_L(0); PG8_BAR; PG8_MMA(0, 0, At, B0); PG8_MMA(0, 1, At, B1); PG8_BAR; PG8_SCHED;
;             PG8_LDA(At, 0, 1); PG8_STAGE(PG8_SB(0, 0), b2, voffB); PG8_STAGE(PG8_SB(0, 1), b2 + hstepB, voffB); PG8_STAGE(PG8_SA(0, 0), a2, voffA);
;             PG8_WAIT_V(8); PG8_WAIT_L(0); PG8_BAR; PG8_MMA(1, 0, At, B0); PG8_MMA(1, 1, At, B1); PG8_BAR; PG8_SCHED;
.LBB0_1324:
	s_add_u32 s14, s24, 0xfff80080
	s_addc_u32 s15, s25, -1
	s_add_i32 s53, 0, 0x10000
	s_cmp_eq_u32 s41, 28
	s_cselect_b32 s27, s3, s15
	s_cselect_b32 s26, s7, s14
	s_cselect_b32 s15, s13, s52
	s_cselect_b32 s14, s17, s40
	s_add_i32 s69, 0, 0x14000
	v_add_u32_e32 v142, s53, v1
	v_add_u32_e32 v158, s69, v1
	ds_read_b128 v[130:133], v142
	ds_read_b128 v[134:137], v142 offset:1024
	ds_read_b128 v[138:141], v142 offset:2048
	ds_read_b128 v[142:145], v142 offset:3072
	ds_read_b128 v[146:149], v158
	ds_read_b128 v[150:153], v158 offset:1024
	ds_read_b128 v[154:157], v158 offset:2048
	ds_read_b128 v[158:161], v158 offset:3072
	v_lshl_add_u64 v[178:179], s[24:25], 0, v[170:171]
	s_add_i32 m0, s23, 0xc000
	ds_read_b128 v[162:165], v181
	ds_read_b128 v[174:177], v181 offset:1024
	ds_read_b128 v[188:191], v181 offset:2048
	ds_read_b128 v[192:195], v181 offset:3072
	ds_read_b128 v[196:199], v181 offset:4096
	ds_read_b128 v[200:203], v181 offset:5120
	ds_read_b128 v[204:207], v181 offset:6144
	ds_read_b128 v[208:211], v181 offset:7168
	global_load_lds_dwordx4 v[178:179], off
	v_lshl_add_u64 v[178:179], s[24:25], 0, v[172:173]
	s_add_i32 m0, s23, 0xe000
	s_nop 0
	global_load_lds_dwordx4 v[178:179], off
	s_waitcnt vmcnt(8)
	s_waitcnt lgkmcnt(0)
	s_barrier
	s_setprio 1
	s_waitcnt lgkmcnt(0)
	v_mfma_f32_16x16x32_bf16 v[122:125], v[130:133], v[162:165], v[122:125]
	v_mfma_f32_16x16x32_bf16 v[118:121], v[138:141], v[162:165], v[118:121]
	v_mfma_f32_16x16x32_bf16 v[110:113], v[130:133], v[188:191], v[110:113]
	v_mfma_f32_16x16x32_bf16 v[102:105], v[138:141], v[188:191], v[102:105]
	v_mfma_f32_16x16x32_bf16 v[94:97], v[130:133], v[196:199], v[94:97]
	v_mfma_f32_16x16x32_bf16 v[86:89], v[138:141], v[196:199], v[86:89]
	v_mfma_f32_16x16x32_bf16 v[78:81], v[130:133], v[204:207], v[78:81]
	v_mfma_f32_16x16x32_bf16 v[70:73], v[138:141], v[204:207], v[70:73]
	v_mfma_f32_16x16x32_bf16 v[122:125], v[134:137], v[174:177], v[122:125]
	v_mfma_f32_16x16x32_bf16 v[118:121], v[142:145], v[174:177], v[118:121]
	v_mfma_f32_16x16x32_bf16 v[110:113], v[134:137], v[192:195], v[110:113]
	v_mfma_f32_16x16x32_bf16 v[102:105], v[142:145], v[192:195], v[102:105]
	v_mfma_f32_16x16x32_bf16 v[94:97], v[134:137], v[200:203], v[94:97]
	v_mfma_f32_16x16x32_bf16 v[86:89], v[142:145], v[200:203], v[86:89]
	v_mfma_f32_16x16x32_bf16 v[78:81], v[134:137], v[208:211], v[78:81]
	v_mfma_f32_16x16x32_bf16 v[70:73], v[142:145], v[208:211], v[70:73]
	s_setprio 0
	s_setprio 1
	v_mfma_f32_16x16x32_bf16 v[126:129], v[146:149], v[162:165], v[126:129]
	v_mfma_f32_16x16x32_bf16 v[114:117], v[154:157], v[162:165], v[114:117]
	v_mfma_f32_16x16x32_bf16 v[106:109], v[146:149], v[188:191], v[106:109]
	v_mfma_f32_16x16x32_bf16 v[98:101], v[154:157], v[188:191], v[98:101]
	v_mfma_f32_16x16x32_bf16 v[90:93], v[146:149], v[196:199], v[90:93]
	v_mfma_f32_16x16x32_bf16 v[82:85], v[154:157], v[196:199], v[82:85]
	v_mfma_f32_16x16x32_bf16 v[74:77], v[146:149], v[204:207], v[74:77]
	v_mfma_f32_16x16x32_bf16 v[66:69], v[154:157], v[204:207], v[66:69]
	v_mfma_f32_16x16x32_bf16 v[126:129], v[150:153], v[174:177], v[126:129]
	v_mfma_f32_16x16x32_bf16 v[114:117], v[158:161], v[174:177], v[114:117]
	v_mfma_f32_16x16x32_bf16 v[106:109], v[150:153], v[192:195], v[106:109]
	v_mfma_f32_16x16x32_bf16 v[98:101], v[158:161], v[192:195], v[98:101]
	v_mfma_f32_16x16x32_bf16 v[90:93], v[150:153], v[200:203], v[90:93]
	v_mfma_f32_16x16x32_bf16 v[82:85], v[158:161], v[200:203], v[82:85]
	v_mfma_f32_16x16x32_bf16 v[74:77], v[150:153], v[208:211], v[74:77]
	v_mfma_f32_16x16x32_bf16 v[66:69], v[158:161], v[208:211], v[66:69]
	s_setprio 0
	s_barrier
	s_add_i32 s53, s53, s28
	v_lshl_add_u64 v[178:179], s[14:15], 0, v[166:167]
	s_mov_b32 m0, s53
	ds_read_b128 v[162:165], v181 offset:16384
	ds_read_b128 v[174:177], v181 offset:17408
	ds_read_b128 v[188:191], v181 offset:18432
	ds_read_b128 v[192:195], v181 offset:19456
	ds_read_b128 v[196:199], v181 offset:20480
	ds_read_b128 v[200:203], v181 offset:21504
	ds_read_b128 v[204:207], v181 offset:22528
	ds_read_b128 v[208:211], v181 offset:23552
	global_load_lds_dwordx4 v[178:179], off nt
	s_add_i32 m0, s53, 0x2000
	s_add_u32 s64, s14, 0x80000
	v_lshl_add_u64 v[184:185], s[14:15], 0, v[168:169]
	s_addc_u32 s65, s15, 0
	s_add_i32 s53, s69, s28
	global_load_lds_dwordx4 v[184:185], off nt
	v_lshl_add_u64 v[212:213], s[64:65], 0, v[166:167]
	s_mov_b32 m0, s53
	v_lshl_add_u64 v[214:215], s[26:27], 0, v[168:169]
	global_load_lds_dwordx4 v[212:213], off nt
	v_lshl_add_u64 v[212:213], s[64:65], 0, v[168:169]
	s_add_i32 m0, s53, 0x2000
	s_nop 0
	global_load_lds_dwordx4 v[212:213], off nt
	v_lshl_add_u64 v[212:213], s[26:27], 0, v[166:167]
	s_mov_b32 m0, s23
	s_nop 0
	global_load_lds_dwordx4 v[212:213], off
	s_mov_b32 m0, s29
	s_nop 0
	global_load_lds_dwordx4 v[214:215], off
	s_waitcnt vmcnt(8)
	s_waitcnt lgkmcnt(0)
	s_barrier
; #define PG8_STAGE(bufoff, gbase, voff) do { _Pragma("unroll") for (int _i = 0; _i < 2; ++_i) \
;         __builtin_amdgcn_global_load_lds((const unsigned*)((const char*)(gbase) + (voff)[_i]), (LAS unsigned*)(lds + (bufoff) + ldsw + _i * 8192), 16, 0, 0); } while (0)
; #define PG8_LDA(dst, b, h) do { _Pragma("unroll") for (int m = 0; m < 4; ++m) _Pragma("unroll") for (int k = 0; k < 2; ++k) dst[m][k] = *(const LAS bf16x8*)(lds + PG8_SA(b, h) + aoff + m * 2048 + k * 1024); } while (0)
; #define PG8_LDB(dst, b, h) do { _Pragma("unroll") for (int n = 0; n < 2; ++n) _Pragma("unroll") for (int k = 0; k < 2; ++k) dst[n][k] = *(const LAS bf16x8*)(lds + PG8_SB(b, h) + boff + n * 2048 + k * 1024); } while (0)
; #define PG8_MMA(ai, bj, At, Bt) do { __builtin_amdgcn_s_setprio(1); _Pragma("unroll") for (int m = 0; m < 4; ++m) _Pragma("unroll") for (int n = 0; n < 2; ++n) _Pragma("unroll") for (int k = 0; k < 2; ++k) \
;         acc[ai][bj][m][n] = __builtin_amdgcn_mfma_f32_16x16x32_bf16(Bt[n][k], At[m][k], acc[ai][bj][m][n], 0, 0, 0); __builtin_amdgcn_s_setprio(0); } while (0)
; #define PG8_WAIT_V(n) asm volatile("s_waitcnt vmcnt(" #n ")" ::: "memory")
; #define PG8_WAIT_L(n) asm volatile("s_waitcnt lgkmcnt(" #n ")" ::: "memory")
; #define PG8_BAR __builtin_amdgcn_s_barrier()
; #define PG8_SCHED __builtin_amdgcn_sched_barrier(0)
; template <class Epi>
; __device__ __forceinline__ void gemm_phase(LAS unsigned char* lds, const Gemm g, const StaticOrder& S, const Epi& E) {
;     ...
;             PG8_WAIT_V(8); PG8_WAIT_L(0); PG8_BAR; PG8_MMA(1, 0, At, B0); PG8_MMA(1, 1, At, B1); PG8_BAR; PG8_SCHED;
;             PG8_LDB(B0, 1, 0); PG8_LDB(B1, 1, 1); PG8_SCHED; PG8_LDA(At, 1, 0); PG8_STAGE(PG8_SA(0, 1), a2 + hstepA, voffA);
;             PG8_WAIT_V(8); PG8_WAIT_L(0); PG8_BAR; PG8_MMA(0, 0, At, B0); PG8_MMA(0, 1, At, B1); PG8_BAR; PG8_SCHED;
	s_setprio 1
	s_waitcnt lgkmcnt(0)
	v_mfma_f32_16x16x32_bf16 v[62:65], v[130:133], v[162:165], v[62:65]
	v_mfma_f32_16x16x32_bf16 v[54:57], v[138:141], v[162:165], v[54:57]
	v_mfma_f32_16x16x32_bf16 v[46:49], v[130:133], v[188:191], v[46:49]
	v_mfma_f32_16x16x32_bf16 v[38:41], v[138:141], v[188:191], v[38:41]
	v_mfma_f32_16x16x32_bf16 v[30:33], v[130:133], v[196:199], v[30:33]
	v_mfma_f32_16x16x32_bf16 v[22:25], v[138:141], v[196:199], v[22:25]
	v_mfma_f32_16x16x32_bf16 v[14:17], v[130:133], v[204:207], v[14:17]
	v_mfma_f32_16x16x32_bf16 v[6:9], v[138:141], v[204:207], v[6:9]
	v_mfma_f32_16x16x32_bf16 v[62:65], v[134:137], v[174:177], v[62:65]
	v_mfma_f32_16x16x32_bf16 v[54:57], v[142:145], v[174:177], v[54:57]
	v_mfma_f32_16x16x32_bf16 v[46:49], v[134:137], v[192:195], v[46:49]
	v_mfma_f32_16x16x32_bf16 v[38:41], v[142:145], v[192:195], v[38:41]
	v_mfma_f32_16x16x32_bf16 v[30:33], v[134:137], v[200:203], v[30:33]
	v_mfma_f32_16x16x32_bf16 v[22:25], v[142:145], v[200:203], v[22:25]
	v_mfma_f32_16x16x32_bf16 v[14:17], v[134:137], v[208:211], v[14:17]
	v_mfma_f32_16x16x32_bf16 v[6:9], v[142:145], v[208:211], v[6:9]
	s_setprio 0
	s_setprio 1
	v_mfma_f32_16x16x32_bf16 v[58:61], v[146:149], v[162:165], v[58:61]
	v_mfma_f32_16x16x32_bf16 v[50:53], v[154:157], v[162:165], v[50:53]
	v_mfma_f32_16x16x32_bf16 v[42:45], v[146:149], v[188:191], v[42:45]
	v_mfma_f32_16x16x32_bf16 v[34:37], v[154:157], v[188:191], v[34:37]
	v_mfma_f32_16x16x32_bf16 v[26:29], v[146:149], v[196:199], v[26:29]
	v_mfma_f32_16x16x32_bf16 v[18:21], v[154:157], v[196:199], v[18:21]
	v_mfma_f32_16x16x32_bf16 v[10:13], v[146:149], v[204:207], v[10:13]
	v_mfma_f32_16x16x32_bf16 v[2:5], v[154:157], v[204:207], v[2:5]
	v_mfma_f32_16x16x32_bf16 v[58:61], v[150:153], v[174:177], v[58:61]
	v_mfma_f32_16x16x32_bf16 v[50:53], v[158:161], v[174:177], v[50:53]
	v_mfma_f32_16x16x32_bf16 v[42:45], v[150:153], v[192:195], v[42:45]
	v_mfma_f32_16x16x32_bf16 v[34:37], v[158:161], v[192:195], v[34:37]
	v_mfma_f32_16x16x32_bf16 v[26:29], v[150:153], v[200:203], v[26:29]
	v_mfma_f32_16x16x32_bf16 v[18:21], v[158:161], v[200:203], v[18:21]
	v_mfma_f32_16x16x32_bf16 v[10:13], v[150:153], v[208:211], v[10:13]
	v_mfma_f32_16x16x32_bf16 v[2:5], v[158:161], v[208:211], v[2:5]
	s_setprio 0
	s_barrier
	s_add_i32 s53, 0, 0x18000
	s_add_i32 s64, 0, 0x1c000
	v_add_u32_e32 v142, s53, v1
	v_add_u32_e32 v158, s64, v1
	ds_read_b128 v[130:133], v142
	ds_read_b128 v[134:137], v142 offset:1024
	ds_read_b128 v[138:141], v142 offset:2048
	ds_read_b128 v[142:145], v142 offset:3072
	ds_read_b128 v[146:149], v158
	ds_read_b128 v[150:153], v158 offset:1024
	ds_read_b128 v[154:157], v158 offset:2048
	ds_read_b128 v[158:161], v158 offset:3072
	s_add_u32 s26, s26, 0x80000
	s_addc_u32 s27, s27, 0
	s_mov_b32 m0, s30
	v_lshl_add_u64 v[216:217], s[26:27], 0, v[166:167]
	ds_read_b128 v[162:165], v181 offset:32768
	ds_read_b128 v[174:177], v181 offset:33792
	ds_read_b128 v[188:191], v181 offset:34816
	ds_read_b128 v[192:195], v181 offset:35840
	ds_read_b128 v[196:199], v181 offset:36864
	ds_read_b128 v[200:203], v181 offset:37888
	ds_read_b128 v[204:207], v181 offset:38912
	ds_read_b128 v[208:211], v181 offset:39936
	global_load_lds_dwordx4 v[216:217], off
	v_lshl_add_u64 v[216:217], s[26:27], 0, v[168:169]
	s_mov_b32 m0, s31
	s_nop 0
	global_load_lds_dwordx4 v[216:217], off
	s_waitcnt vmcnt(8)
	s_waitcnt lgkmcnt(0)
	s_barrier
	s_setprio 1
	s_waitcnt lgkmcnt(0)
	v_mfma_f32_16x16x32_bf16 v[122:125], v[130:133], v[162:165], v[122:125]
	v_mfma_f32_16x16x32_bf16 v[118:121], v[138:141], v[162:165], v[118:121]
	v_mfma_f32_16x16x32_bf16 v[110:113], v[130:133], v[188:191], v[110:113]
	v_mfma_f32_16x16x32_bf16 v[102:105], v[138:141], v[188:191], v[102:105]
	v_mfma_f32_16x16x32_bf16 v[94:97], v[130:133], v[196:199], v[94:97]
	v_mfma_f32_16x16x32_bf16 v[86:89], v[138:141], v[196:199], v[86:89]
	v_mfma_f32_16x16x32_bf16 v[78:81], v[130:133], v[204:207], v[78:81]
	v_mfma_f32_16x16x32_bf16 v[70:73], v[138:141], v[204:207], v[70:73]
	v_mfma_f32_16x16x32_bf16 v[122:125], v[134:137], v[174:177], v[122:125]
	v_mfma_f32_16x16x32_bf16 v[118:121], v[142:145], v[174:177], v[118:121]
	v_mfma_f32_16x16x32_bf16 v[110:113], v[134:137], v[192:195], v[110:113]
	v_mfma_f32_16x16x32_bf16 v[102:105], v[142:145], v[192:195], v[102:105]
	v_mfma_f32_16x16x32_bf16 v[94:97], v[134:137], v[200:203], v[94:97]
	v_mfma_f32_16x16x32_bf16 v[86:89], v[142:145], v[200:203], v[86:89]
	v_mfma_f32_16x16x32_bf16 v[78:81], v[134:137], v[208:211], v[78:81]
	v_mfma_f32_16x16x32_bf16 v[70:73], v[142:145], v[208:211], v[70:73]
	s_setprio 0
	s_setprio 1
	v_mfma_f32_16x16x32_bf16 v[126:129], v[146:149], v[162:165], v[126:129]
	v_mfma_f32_16x16x32_bf16 v[114:117], v[154:157], v[162:165], v[114:117]
	v_mfma_f32_16x16x32_bf16 v[106:109], v[146:149], v[188:191], v[106:109]
	v_mfma_f32_16x16x32_bf16 v[98:101], v[154:157], v[188:191], v[98:101]
	v_mfma_f32_16x16x32_bf16 v[90:93], v[146:149], v[196:199], v[90:93]
	v_mfma_f32_16x16x32_bf16 v[82:85], v[154:157], v[196:199], v[82:85]
	v_mfma_f32_16x16x32_bf16 v[74:77], v[146:149], v[204:207], v[74:77]
	v_mfma_f32_16x16x32_bf16 v[66:69], v[154:157], v[204:207], v[66:69]
	v_mfma_f32_16x16x32_bf16 v[126:129], v[150:153], v[174:177], v[126:129]
	v_mfma_f32_16x16x32_bf16 v[114:117], v[158:161], v[174:177], v[114:117]
	v_mfma_f32_16x16x32_bf16 v[106:109], v[150:153], v[192:195], v[106:109]
	v_mfma_f32_16x16x32_bf16 v[98:101], v[158:161], v[192:195], v[98:101]
	v_mfma_f32_16x16x32_bf16 v[90:93], v[150:153], v[200:203], v[90:93]
	v_mfma_f32_16x16x32_bf16 v[82:85], v[158:161], v[200:203], v[82:85]
	v_mfma_f32_16x16x32_bf16 v[74:77], v[150:153], v[208:211], v[74:77]
	v_mfma_f32_16x16x32_bf16 v[66:69], v[158:161], v[208:211], v[66:69]
	s_setprio 0
	s_barrier
; #define PG8_STAGE(bufoff, gbase, voff) do { _Pragma("unroll") for (int _i = 0; _i < 2; ++_i) \
;         __builtin_amdgcn_global_load_lds((const unsigned*)((const char*)(gbase) + (voff)[_i]), (LAS unsigned*)(lds + (bufoff) + ldsw + _i * 8192), 16, 0, 0); } while (0)
; #define PG8_LDA(dst, b, h) do { _Pragma("unroll") for (int m = 0; m < 4; ++m) _Pragma("unroll") for (int k = 0; k < 2; ++k) dst[m][k] = *(const LAS bf16x8*)(lds + PG8_SA(b, h) + aoff + m * 2048 + k * 1024); } while (0)
; #define PG8_MMA(ai, bj, At, Bt) do { __builtin_amdgcn_s_setprio(1); _Pragma("unroll") for (int m = 0; m < 4; ++m) _Pragma("unroll") for (int n = 0; n < 2; ++n) _Pragma("unroll") for (int k = 0; k < 2; ++k) \
;         acc[ai][bj][m][n] = __builtin_amdgcn_mfma_f32_16x16x32_bf16(Bt[n][k], At[m][k], acc[ai][bj][m][n], 0, 0, 0); __builtin_amdgcn_s_setprio(0); } while (0)
; #define PG8_WAIT_V(n) asm volatile("s_waitcnt vmcnt(" #n ")" ::: "memory")
; #define PG8_WAIT_L(n) asm volatile("s_waitcnt lgkmcnt(" #n ")" ::: "memory")
; #define PG8_BAR __builtin_amdgcn_s_barrier()
; #define PG8_SCHED __builtin_amdgcn_sched_barrier(0)
; template <class Epi>
; __device__ __forceinline__ void gemm_phase(LAS unsigned char* lds, const Gemm g, const StaticOrder& S, const Epi& E) {
;     ...
;             PG8_LDA(At, 1, 1); PG8_STAGE(PG8_SB(1, 0), b3, voffB); PG8_STAGE(PG8_SB(1, 1), b3 + hstepB, voffB); PG8_STAGE(PG8_SA(1, 0), a3, voffA);
;             PG8_WAIT_V(8); PG8_WAIT_L(0); PG8_BAR; PG8_MMA(1, 0, At, B0); PG8_MMA(1, 1, At, B1); PG8_BAR; PG8_SCHED;
;         }
;         if (wr == 0) PG8_BAR;
	s_add_i32 s26, s53, s28
	v_lshl_add_u64 v[178:179], v[178:179], 0, s[84:85]
	s_mov_b32 m0, s26
	ds_read_b128 v[162:165], v181 offset:49152
	ds_read_b128 v[174:177], v181 offset:50176
	ds_read_b128 v[188:191], v181 offset:51200
	ds_read_b128 v[192:195], v181 offset:52224
	ds_read_b128 v[196:199], v181 offset:53248
	ds_read_b128 v[200:203], v181 offset:54272
	ds_read_b128 v[204:207], v181 offset:55296
	ds_read_b128 v[208:211], v181 offset:56320
	global_load_lds_dwordx4 v[178:179], off nt
	s_add_i32 m0, s26, 0x2000
	s_add_u32 s14, s14, 0x80080
	v_lshl_add_u64 v[178:179], v[184:185], 0, s[84:85]
	s_addc_u32 s15, s15, 0
	s_add_i32 s26, s64, s28
	global_load_lds_dwordx4 v[178:179], off nt
	v_lshl_add_u64 v[178:179], s[14:15], 0, v[166:167]
	s_mov_b32 m0, s26
	s_nop 0
	global_load_lds_dwordx4 v[178:179], off nt
	v_lshl_add_u64 v[178:179], s[14:15], 0, v[168:169]
	s_add_i32 m0, s26, 0x2000
	s_nop 0
	global_load_lds_dwordx4 v[178:179], off nt
	v_lshl_add_u64 v[178:179], v[212:213], 0, s[84:85]
	s_mov_b32 m0, s35
	s_nop 0
	global_load_lds_dwordx4 v[178:179], off
	v_lshl_add_u64 v[178:179], v[214:215], 0, s[84:85]
	s_mov_b32 m0, s42
	s_nop 0
	global_load_lds_dwordx4 v[178:179], off
	s_waitcnt vmcnt(8)
	s_waitcnt lgkmcnt(0)
	s_barrier
	s_setprio 1
	s_waitcnt lgkmcnt(0)
	v_mfma_f32_16x16x32_bf16 v[62:65], v[130:133], v[162:165], v[62:65]
	v_mfma_f32_16x16x32_bf16 v[54:57], v[138:141], v[162:165], v[54:57]
	v_mfma_f32_16x16x32_bf16 v[46:49], v[130:133], v[188:191], v[46:49]
	v_mfma_f32_16x16x32_bf16 v[38:41], v[138:141], v[188:191], v[38:41]
	v_mfma_f32_16x16x32_bf16 v[30:33], v[130:133], v[196:199], v[30:33]
	v_mfma_f32_16x16x32_bf16 v[22:25], v[138:141], v[196:199], v[22:25]
	v_mfma_f32_16x16x32_bf16 v[14:17], v[130:133], v[204:207], v[14:17]
	v_mfma_f32_16x16x32_bf16 v[6:9], v[138:141], v[204:207], v[6:9]
	v_mfma_f32_16x16x32_bf16 v[62:65], v[134:137], v[174:177], v[62:65]
	v_mfma_f32_16x16x32_bf16 v[54:57], v[142:145], v[174:177], v[54:57]
	v_mfma_f32_16x16x32_bf16 v[46:49], v[134:137], v[192:195], v[46:49]
	v_mfma_f32_16x16x32_bf16 v[38:41], v[142:145], v[192:195], v[38:41]
	v_mfma_f32_16x16x32_bf16 v[30:33], v[134:137], v[200:203], v[30:33]
	v_mfma_f32_16x16x32_bf16 v[22:25], v[142:145], v[200:203], v[22:25]
	v_mfma_f32_16x16x32_bf16 v[14:17], v[134:137], v[208:211], v[14:17]
	v_mfma_f32_16x16x32_bf16 v[6:9], v[142:145], v[208:211], v[6:9]
	s_setprio 0
	s_setprio 1
	v_mfma_f32_16x16x32_bf16 v[58:61], v[146:149], v[162:165], v[58:61]
	v_mfma_f32_16x16x32_bf16 v[50:53], v[154:157], v[162:165], v[50:53]
	v_mfma_f32_16x16x32_bf16 v[42:45], v[146:149], v[188:191], v[42:45]
	v_mfma_f32_16x16x32_bf16 v[34:37], v[154:157], v[188:191], v[34:37]
	v_mfma_f32_16x16x32_bf16 v[26:29], v[146:149], v[196:199], v[26:29]
	v_mfma_f32_16x16x32_bf16 v[18:21], v[154:157], v[196:199], v[18:21]
	v_mfma_f32_16x16x32_bf16 v[10:13], v[146:149], v[204:207], v[10:13]
	v_mfma_f32_16x16x32_bf16 v[2:5], v[154:157], v[204:207], v[2:5]
	v_mfma_f32_16x16x32_bf16 v[58:61], v[150:153], v[174:177], v[58:61]
	v_mfma_f32_16x16x32_bf16 v[50:53], v[158:161], v[174:177], v[50:53]
	v_mfma_f32_16x16x32_bf16 v[42:45], v[150:153], v[192:195], v[42:45]
	v_mfma_f32_16x16x32_bf16 v[34:37], v[158:161], v[192:195], v[34:37]
	v_mfma_f32_16x16x32_bf16 v[26:29], v[150:153], v[200:203], v[26:29]
	v_mfma_f32_16x16x32_bf16 v[18:21], v[158:161], v[200:203], v[18:21]
	v_mfma_f32_16x16x32_bf16 v[10:13], v[150:153], v[208:211], v[10:13]
	v_mfma_f32_16x16x32_bf16 v[2:5], v[158:161], v[208:211], v[2:5]
	s_setprio 0
	s_barrier
	s_add_i32 s41, s41, 2
	s_add_u32 s24, s24, 0x100
	s_addc_u32 s25, s25, 0
	s_add_u32 s40, s40, 0x100
	s_addc_u32 s52, s52, 0
	s_cmp_gt_u32 s41, 29
	s_cbranch_scc0 .LBB0_1324
	s_and_b64 vcc, exec, s[10:11]
	s_cbranch_vccz .LBB0_1327
	s_barrier

; #define PG8_STAGE(bufoff, gbase, voff) do { _Pragma("unroll") for (int _i = 0; _i < 2; ++_i) \
;         __builtin_amdgcn_global_load_lds((const unsigned*)((const char*)(gbase) + (voff)[_i]), (LAS unsigned*)(lds + (bufoff) + ldsw + _i * 8192), 16, 0, 0); } while (0)
; #define PG8_LDA(dst, b, h) do { _Pragma("unroll") for (int m = 0; m < 4; ++m) _Pragma("unroll") for (int k = 0; k < 2; ++k) dst[m][k] = *(const LAS bf16x8*)(lds + PG8_SA(b, h) + aoff + m * 2048 + k * 1024); } while (0)
; #define PG8_LDB(dst, b, h) do { _Pragma("unroll") for (int n = 0; n < 2; ++n) _Pragma("unroll") for (int k = 0; k < 2; ++k) dst[n][k] = *(const LAS bf16x8*)(lds + PG8_SB(b, h) + boff + n * 2048 + k * 1024); } while (0)
; #define PG8_MMA(ai, bj, At, Bt) do { __builtin_amdgcn_s_setprio(1); _Pragma("unroll") for (int m = 0; m < 4; ++m) _Pragma("unroll") for (int n = 0; n < 2; ++n) _Pragma("unroll") for (int k = 0; k < 2; ++k) \
;         acc[ai][bj][m][n] = __builtin_amdgcn_mfma_f32_16x16x32_bf16(Bt[n][k], At[m][k], acc[ai][bj][m][n], 0, 0, 0); __builtin_amdgcn_s_setprio(0); } while (0)
; #define PG8_WAIT_V(n) asm volatile("s_waitcnt vmcnt(" #n ")" ::: "memory")
; #define PG8_WAIT_L(n) asm volatile("s_waitcnt lgkmcnt(" #n ")" ::: "memory")
; #define PG8_BAR __builtin_amdgcn_s_barrier()
; #define PG8_SCHED __builtin_amdgcn_sched_barrier(0)
; template <class Epi>
; __device__ __forceinline__ void gemm_phase(LAS unsigned char* lds, const Gemm g, const StaticOrder& S, const Epi& E) {
;     ...
;             const bool last = (t == nt - 2);
;             const char* a1 = cA + (size_t)(t + 1) * kstep;
;             const char* a2 = last ? nA : cA + (size_t)(t + 2) * kstep; const char* b2 = last ? nB : cB + (size_t)(t + 2) * kstep;
;             const char* a3 = a2 + kstep; const char* b3 = b2 + kstep;
;             PG8_LDB(B0, 0, 0); PG8_LDB(B1, 0, 1); PG8_SCHED; PG8_LDA(At, 0, 0); PG8_STAGE(PG8_SA(1, 1), a1 + hstepA, voffA);
;             PG8_WAIT_V(8); PG8_WAIT_L(0); PG8_BAR; PG8_MMA(0, 0, At, B0); PG8_MMA(0, 1, At, B1); PG8_BAR; PG8_SCHED;
;             PG8_LDA(At, 0, 1); PG8_STAGE(PG8_SB(0, 0), b2, voffB); PG8_STAGE(PG8_SB(0, 1), b2 + hstepB, voffB); PG8_STAGE(PG8_SA(0, 0), a2, voffA);
.LBB0_1412:
	s_add_u32 s14, s22, 0xfff80080
	s_addc_u32 s15, s23, -1
	s_add_i32 s41, 0, 0x10000
	s_cmp_eq_u32 s64, 28
	s_cselect_b32 s25, s3, s15
	s_cselect_b32 s24, s7, s14
	s_cselect_b32 s15, s13, s63
	s_cselect_b32 s14, s17, s40
	s_add_i32 s65, 0, 0x14000
	v_add_u32_e32 v142, s41, v1
	v_add_u32_e32 v163, s65, v1
	ds_read_b128 v[130:133], v142
	ds_read_b128 v[134:137], v142 offset:1024
	ds_read_b128 v[138:141], v142 offset:2048
	ds_read_b128 v[142:145], v142 offset:3072
	ds_read_b128 v[158:161], v163
	ds_read_b128 v[164:167], v163 offset:1024
	ds_read_b128 v[168:171], v163 offset:2048
	ds_read_b128 v[172:175], v163 offset:3072
	v_lshl_add_u64 v[184:185], s[22:23], 0, v[154:155]
	s_add_i32 m0, s30, 0xc000
	ds_read_b128 v[176:179], v162
	ds_read_b128 v[188:191], v162 offset:1024
	ds_read_b128 v[192:195], v162 offset:2048
	ds_read_b128 v[196:199], v162 offset:3072
	ds_read_b128 v[200:203], v162 offset:4096
	ds_read_b128 v[204:207], v162 offset:5120
	ds_read_b128 v[208:211], v162 offset:6144
	ds_read_b128 v[212:215], v162 offset:7168
	global_load_lds_dwordx4 v[184:185], off
	v_lshl_add_u64 v[184:185], s[22:23], 0, v[156:157]
	s_add_i32 m0, s30, 0xe000
	s_nop 0
	global_load_lds_dwordx4 v[184:185], off
	s_waitcnt vmcnt(8)
	s_waitcnt lgkmcnt(0)
	s_barrier
	s_setprio 1
	s_waitcnt lgkmcnt(0)
	v_mfma_f32_16x16x32_bf16 v[126:129], v[130:133], v[176:179], v[126:129]
	v_mfma_f32_16x16x32_bf16 v[122:125], v[138:141], v[176:179], v[122:125]
	v_mfma_f32_16x16x32_bf16 v[118:121], v[130:133], v[192:195], v[118:121]
	v_mfma_f32_16x16x32_bf16 v[110:113], v[138:141], v[192:195], v[110:113]
	v_mfma_f32_16x16x32_bf16 v[102:105], v[130:133], v[200:203], v[102:105]
	v_mfma_f32_16x16x32_bf16 v[94:97], v[138:141], v[200:203], v[94:97]
	v_mfma_f32_16x16x32_bf16 v[86:89], v[130:133], v[208:211], v[86:89]
	v_mfma_f32_16x16x32_bf16 v[78:81], v[138:141], v[208:211], v[78:81]
	v_mfma_f32_16x16x32_bf16 v[126:129], v[134:137], v[188:191], v[126:129]
	v_mfma_f32_16x16x32_bf16 v[122:125], v[142:145], v[188:191], v[122:125]
	v_mfma_f32_16x16x32_bf16 v[118:121], v[134:137], v[196:199], v[118:121]
	v_mfma_f32_16x16x32_bf16 v[110:113], v[142:145], v[196:199], v[110:113]
	v_mfma_f32_16x16x32_bf16 v[102:105], v[134:137], v[204:207], v[102:105]
	v_mfma_f32_16x16x32_bf16 v[94:97], v[142:145], v[204:207], v[94:97]
	v_mfma_f32_16x16x32_bf16 v[86:89], v[134:137], v[212:215], v[86:89]
	v_mfma_f32_16x16x32_bf16 v[78:81], v[142:145], v[212:215], v[78:81]
	s_setprio 0
	s_setprio 1
	v_mfma_f32_16x16x32_bf16 v[114:117], v[158:161], v[176:179], v[114:117]
	v_mfma_f32_16x16x32_bf16 v[106:109], v[168:171], v[176:179], v[106:109]
	v_mfma_f32_16x16x32_bf16 v[98:101], v[158:161], v[192:195], v[98:101]
	v_mfma_f32_16x16x32_bf16 v[90:93], v[168:171], v[192:195], v[90:93]
	v_mfma_f32_16x16x32_bf16 v[82:85], v[158:161], v[200:203], v[82:85]
	v_mfma_f32_16x16x32_bf16 v[74:77], v[168:171], v[200:203], v[74:77]
	v_mfma_f32_16x16x32_bf16 v[70:73], v[158:161], v[208:211], v[70:73]
	v_mfma_f32_16x16x32_bf16 v[66:69], v[168:171], v[208:211], v[66:69]
	v_mfma_f32_16x16x32_bf16 v[114:117], v[164:167], v[188:191], v[114:117]
	v_mfma_f32_16x16x32_bf16 v[106:109], v[172:175], v[188:191], v[106:109]
	v_mfma_f32_16x16x32_bf16 v[98:101], v[164:167], v[196:199], v[98:101]
	v_mfma_f32_16x16x32_bf16 v[90:93], v[172:175], v[196:199], v[90:93]
	v_mfma_f32_16x16x32_bf16 v[82:85], v[164:167], v[204:207], v[82:85]
	v_mfma_f32_16x16x32_bf16 v[74:77], v[172:175], v[204:207], v[74:77]
	v_mfma_f32_16x16x32_bf16 v[70:73], v[164:167], v[212:215], v[70:73]
	v_mfma_f32_16x16x32_bf16 v[66:69], v[172:175], v[212:215], v[66:69]
	s_setprio 0
	s_barrier
	s_add_i32 s41, s41, s28
	v_lshl_add_u64 v[184:185], s[14:15], 0, v[150:151]
	s_mov_b32 m0, s41
	ds_read_b128 v[176:179], v162 offset:16384
	ds_read_b128 v[188:191], v162 offset:17408
	ds_read_b128 v[192:195], v162 offset:18432
	ds_read_b128 v[196:199], v162 offset:19456
	ds_read_b128 v[200:203], v162 offset:20480
	ds_read_b128 v[204:207], v162 offset:21504
	ds_read_b128 v[208:211], v162 offset:22528
	ds_read_b128 v[212:215], v162 offset:23552
	global_load_lds_dwordx4 v[184:185], off nt
	s_add_i32 m0, s41, 0x2000
	s_add_u32 s68, s14, 0x80000
	v_lshl_add_u64 v[216:217], s[14:15], 0, v[146:147]
	s_addc_u32 s69, s15, 0
	s_add_i32 s41, s65, s28
	global_load_lds_dwordx4 v[216:217], off nt
	v_lshl_add_u64 v[218:219], s[68:69], 0, v[150:151]
	s_mov_b32 m0, s41
	v_lshl_add_u64 v[220:221], s[24:25], 0, v[148:149]
	global_load_lds_dwordx4 v[218:219], off nt
	v_lshl_add_u64 v[218:219], s[68:69], 0, v[146:147]
	s_add_i32 m0, s41, 0x2000
	s_nop 0
	global_load_lds_dwordx4 v[218:219], off nt
	v_lshl_add_u64 v[218:219], s[24:25], 0, v[152:153]
	s_mov_b32 m0, s30
	s_nop 0
	global_load_lds_dwordx4 v[218:219], off
	s_mov_b32 m0, s31
	s_nop 0
	global_load_lds_dwordx4 v[220:221], off
	s_waitcnt vmcnt(8)
	s_waitcnt lgkmcnt(0)
	s_barrier
; #define PG8_STAGE(bufoff, gbase, voff) do { _Pragma("unroll") for (int _i = 0; _i < 2; ++_i) \
;         __builtin_amdgcn_global_load_lds((const unsigned*)((const char*)(gbase) + (voff)[_i]), (LAS unsigned*)(lds + (bufoff) + ldsw + _i * 8192), 16, 0, 0); } while (0)
; #define PG8_LDA(dst, b, h) do { _Pragma("unroll") for (int m = 0; m < 4; ++m) _Pragma("unroll") for (int k = 0; k < 2; ++k) dst[m][k] = *(const LAS bf16x8*)(lds + PG8_SA(b, h) + aoff + m * 2048 + k * 1024); } while (0)
; #define PG8_LDB(dst, b, h) do { _Pragma("unroll") for (int n = 0; n < 2; ++n) _Pragma("unroll") for (int k = 0; k < 2; ++k) dst[n][k] = *(const LAS bf16x8*)(lds + PG8_SB(b, h) + boff + n * 2048 + k * 1024); } while (0)
; #define PG8_MMA(ai, bj, At, Bt) do { __builtin_amdgcn_s_setprio(1); _Pragma("unroll") for (int m = 0; m < 4; ++m) _Pragma("unroll") for (int n = 0; n < 2; ++n) _Pragma("unroll") for (int k = 0; k < 2; ++k) \
;         acc[ai][bj][m][n] = __builtin_amdgcn_mfma_f32_16x16x32_bf16(Bt[n][k], At[m][k], acc[ai][bj][m][n], 0, 0, 0); __builtin_amdgcn_s_setprio(0); } while (0)
; #define PG8_WAIT_V(n) asm volatile("s_waitcnt vmcnt(" #n ")" ::: "memory")
; #define PG8_WAIT_L(n) asm volatile("s_waitcnt lgkmcnt(" #n ")" ::: "memory")
; #define PG8_BAR __builtin_amdgcn_s_barrier()
; #define PG8_SCHED __builtin_amdgcn_sched_barrier(0)
; template <class Epi>
; __device__ __forceinline__ void gemm_phase(LAS unsigned char* lds, const Gemm g, const StaticOrder& S, const Epi& E) {
;     ...
;             PG8_WAIT_V(8); PG8_WAIT_L(0); PG8_BAR; PG8_MMA(1, 0, At, B0); PG8_MMA(1, 1, At, B1); PG8_BAR; PG8_SCHED;
;             PG8_LDB(B0, 1, 0); PG8_LDB(B1, 1, 1); PG8_SCHED; PG8_LDA(At, 1, 0); PG8_STAGE(PG8_SA(0, 1), a2 + hstepA, voffA);
;             PG8_WAIT_V(8); PG8_WAIT_L(0); PG8_BAR; PG8_MMA(0, 0, At, B0); PG8_MMA(0, 1, At, B1); PG8_BAR; PG8_SCHED;
	s_setprio 1
	s_waitcnt lgkmcnt(0)
	v_mfma_f32_16x16x32_bf16 v[62:65], v[130:133], v[176:179], v[62:65]
	v_mfma_f32_16x16x32_bf16 v[58:61], v[138:141], v[176:179], v[58:61]
	v_mfma_f32_16x16x32_bf16 v[54:57], v[130:133], v[192:195], v[54:57]
	v_mfma_f32_16x16x32_bf16 v[46:49], v[138:141], v[192:195], v[46:49]
	v_mfma_f32_16x16x32_bf16 v[38:41], v[130:133], v[200:203], v[38:41]
	v_mfma_f32_16x16x32_bf16 v[30:33], v[138:141], v[200:203], v[30:33]
	v_mfma_f32_16x16x32_bf16 v[22:25], v[130:133], v[208:211], v[22:25]
	v_mfma_f32_16x16x32_bf16 v[14:17], v[138:141], v[208:211], v[14:17]
	v_mfma_f32_16x16x32_bf16 v[62:65], v[134:137], v[188:191], v[62:65]
	v_mfma_f32_16x16x32_bf16 v[58:61], v[142:145], v[188:191], v[58:61]
	v_mfma_f32_16x16x32_bf16 v[54:57], v[134:137], v[196:199], v[54:57]
	v_mfma_f32_16x16x32_bf16 v[46:49], v[142:145], v[196:199], v[46:49]
	v_mfma_f32_16x16x32_bf16 v[38:41], v[134:137], v[204:207], v[38:41]
	v_mfma_f32_16x16x32_bf16 v[30:33], v[142:145], v[204:207], v[30:33]
	v_mfma_f32_16x16x32_bf16 v[22:25], v[134:137], v[212:215], v[22:25]
	v_mfma_f32_16x16x32_bf16 v[14:17], v[142:145], v[212:215], v[14:17]
	s_setprio 0
	s_setprio 1
	v_mfma_f32_16x16x32_bf16 v[50:53], v[158:161], v[176:179], v[50:53]
	v_mfma_f32_16x16x32_bf16 v[42:45], v[168:171], v[176:179], v[42:45]
	v_mfma_f32_16x16x32_bf16 v[34:37], v[158:161], v[192:195], v[34:37]
	v_mfma_f32_16x16x32_bf16 v[26:29], v[168:171], v[192:195], v[26:29]
	v_mfma_f32_16x16x32_bf16 v[18:21], v[158:161], v[200:203], v[18:21]
	v_mfma_f32_16x16x32_bf16 v[10:13], v[168:171], v[200:203], v[10:13]
	v_mfma_f32_16x16x32_bf16 v[6:9], v[158:161], v[208:211], v[6:9]
	v_mfma_f32_16x16x32_bf16 v[2:5], v[168:171], v[208:211], v[2:5]
	v_mfma_f32_16x16x32_bf16 v[50:53], v[164:167], v[188:191], v[50:53]
	v_mfma_f32_16x16x32_bf16 v[42:45], v[172:175], v[188:191], v[42:45]
	v_mfma_f32_16x16x32_bf16 v[34:37], v[164:167], v[196:199], v[34:37]
	v_mfma_f32_16x16x32_bf16 v[26:29], v[172:175], v[196:199], v[26:29]
	v_mfma_f32_16x16x32_bf16 v[18:21], v[164:167], v[204:207], v[18:21]
	v_mfma_f32_16x16x32_bf16 v[10:13], v[172:175], v[204:207], v[10:13]
	v_mfma_f32_16x16x32_bf16 v[6:9], v[164:167], v[212:215], v[6:9]
	v_mfma_f32_16x16x32_bf16 v[2:5], v[172:175], v[212:215], v[2:5]
	s_setprio 0
	s_barrier
	s_add_i32 s41, 0, 0x18000
	s_add_i32 s65, 0, 0x1c000
	v_add_u32_e32 v142, s41, v1
	v_add_u32_e32 v163, s65, v1
	ds_read_b128 v[130:133], v142
	ds_read_b128 v[134:137], v142 offset:1024
	ds_read_b128 v[138:141], v142 offset:2048
	ds_read_b128 v[142:145], v142 offset:3072
	ds_read_b128 v[158:161], v163
	ds_read_b128 v[164:167], v163 offset:1024
	ds_read_b128 v[168:171], v163 offset:2048
	ds_read_b128 v[172:175], v163 offset:3072
	s_add_u32 s24, s24, 0x80000
	s_addc_u32 s25, s25, 0
	s_mov_b32 m0, s33
	v_lshl_add_u64 v[222:223], s[24:25], 0, v[152:153]
	ds_read_b128 v[176:179], v162 offset:32768
	ds_read_b128 v[188:191], v162 offset:33792
	ds_read_b128 v[192:195], v162 offset:34816
	ds_read_b128 v[196:199], v162 offset:35840
	ds_read_b128 v[200:203], v162 offset:36864
	ds_read_b128 v[204:207], v162 offset:37888
	ds_read_b128 v[208:211], v162 offset:38912
	ds_read_b128 v[212:215], v162 offset:39936
	global_load_lds_dwordx4 v[222:223], off
	v_lshl_add_u64 v[222:223], s[24:25], 0, v[148:149]
	s_mov_b32 m0, s34
	s_nop 0
	global_load_lds_dwordx4 v[222:223], off
	s_waitcnt vmcnt(8)
	s_waitcnt lgkmcnt(0)
	s_barrier
	s_setprio 1
	s_waitcnt lgkmcnt(0)
	v_mfma_f32_16x16x32_bf16 v[126:129], v[130:133], v[176:179], v[126:129]
	v_mfma_f32_16x16x32_bf16 v[122:125], v[138:141], v[176:179], v[122:125]
	v_mfma_f32_16x16x32_bf16 v[118:121], v[130:133], v[192:195], v[118:121]
	v_mfma_f32_16x16x32_bf16 v[110:113], v[138:141], v[192:195], v[110:113]
	v_mfma_f32_16x16x32_bf16 v[102:105], v[130:133], v[200:203], v[102:105]
	v_mfma_f32_16x16x32_bf16 v[94:97], v[138:141], v[200:203], v[94:97]
	v_mfma_f32_16x16x32_bf16 v[86:89], v[130:133], v[208:211], v[86:89]
	v_mfma_f32_16x16x32_bf16 v[78:81], v[138:141], v[208:211], v[78:81]
	v_mfma_f32_16x16x32_bf16 v[126:129], v[134:137], v[188:191], v[126:129]
	v_mfma_f32_16x16x32_bf16 v[122:125], v[142:145], v[188:191], v[122:125]
	v_mfma_f32_16x16x32_bf16 v[118:121], v[134:137], v[196:199], v[118:121]
	v_mfma_f32_16x16x32_bf16 v[110:113], v[142:145], v[196:199], v[110:113]
	v_mfma_f32_16x16x32_bf16 v[102:105], v[134:137], v[204:207], v[102:105]
	v_mfma_f32_16x16x32_bf16 v[94:97], v[142:145], v[204:207], v[94:97]
	v_mfma_f32_16x16x32_bf16 v[86:89], v[134:137], v[212:215], v[86:89]
	v_mfma_f32_16x16x32_bf16 v[78:81], v[142:145], v[212:215], v[78:81]
	s_setprio 0
	s_setprio 1
	v_mfma_f32_16x16x32_bf16 v[114:117], v[158:161], v[176:179], v[114:117]
	v_mfma_f32_16x16x32_bf16 v[106:109], v[168:171], v[176:179], v[106:109]
	v_mfma_f32_16x16x32_bf16 v[98:101], v[158:161], v[192:195], v[98:101]
	v_mfma_f32_16x16x32_bf16 v[90:93], v[168:171], v[192:195], v[90:93]
	v_mfma_f32_16x16x32_bf16 v[82:85], v[158:161], v[200:203], v[82:85]
	v_mfma_f32_16x16x32_bf16 v[74:77], v[168:171], v[200:203], v[74:77]
	v_mfma_f32_16x16x32_bf16 v[70:73], v[158:161], v[208:211], v[70:73]
	v_mfma_f32_16x16x32_bf16 v[66:69], v[168:171], v[208:211], v[66:69]
	v_mfma_f32_16x16x32_bf16 v[114:117], v[164:167], v[188:191], v[114:117]
	v_mfma_f32_16x16x32_bf16 v[106:109], v[172:175], v[188:191], v[106:109]
	v_mfma_f32_16x16x32_bf16 v[98:101], v[164:167], v[196:199], v[98:101]
	v_mfma_f32_16x16x32_bf16 v[90:93], v[172:175], v[196:199], v[90:93]
	v_mfma_f32_16x16x32_bf16 v[82:85], v[164:167], v[204:207], v[82:85]
	v_mfma_f32_16x16x32_bf16 v[74:77], v[172:175], v[204:207], v[74:77]
	v_mfma_f32_16x16x32_bf16 v[70:73], v[164:167], v[212:215], v[70:73]
	v_mfma_f32_16x16x32_bf16 v[66:69], v[172:175], v[212:215], v[66:69]
	s_setprio 0
	s_barrier
; #define PG8_STAGE(bufoff, gbase, voff) do { _Pragma("unroll") for (int _i = 0; _i < 2; ++_i) \
;         __builtin_amdgcn_global_load_lds((const unsigned*)((const char*)(gbase) + (voff)[_i]), (LAS unsigned*)(lds + (bufoff) + ldsw + _i * 8192), 16, 0, 0); } while (0)
; #define PG8_LDA(dst, b, h) do { _Pragma("unroll") for (int m = 0; m < 4; ++m) _Pragma("unroll") for (int k = 0; k < 2; ++k) dst[m][k] = *(const LAS bf16x8*)(lds + PG8_SA(b, h) + aoff + m * 2048 + k * 1024); } while (0)
; #define PG8_MMA(ai, bj, At, Bt) do { __builtin_amdgcn_s_setprio(1); _Pragma("unroll") for (int m = 0; m < 4; ++m) _Pragma("unroll") for (int n = 0; n < 2; ++n) _Pragma("unroll") for (int k = 0; k < 2; ++k) \
;         acc[ai][bj][m][n] = __builtin_amdgcn_mfma_f32_16x16x32_bf16(Bt[n][k], At[m][k], acc[ai][bj][m][n], 0, 0, 0); __builtin_amdgcn_s_setprio(0); } while (0)
; #define PG8_WAIT_V(n) asm volatile("s_waitcnt vmcnt(" #n ")" ::: "memory")
; #define PG8_WAIT_L(n) asm volatile("s_waitcnt lgkmcnt(" #n ")" ::: "memory")
; #define PG8_BAR __builtin_amdgcn_s_barrier()
; #define PG8_SCHED __builtin_amdgcn_sched_barrier(0)
; template <class Epi>
; __device__ __forceinline__ void gemm_phase(LAS unsigned char* lds, const Gemm g, const StaticOrder& S, const Epi& E) {
;     ...
;             PG8_LDA(At, 1, 1); PG8_STAGE(PG8_SB(1, 0), b3, voffB); PG8_STAGE(PG8_SB(1, 1), b3 + hstepB, voffB); PG8_STAGE(PG8_SA(1, 0), a3, voffA);
;             PG8_WAIT_V(8); PG8_WAIT_L(0); PG8_BAR; PG8_MMA(1, 0, At, B0); PG8_MMA(1, 1, At, B1); PG8_BAR; PG8_SCHED;
;         }
;         if (wr == 0) PG8_BAR;
	s_add_i32 s24, s41, s28
	v_lshl_add_u64 v[184:185], v[184:185], 0, s[84:85]
	s_mov_b32 m0, s24
	ds_read_b128 v[176:179], v162 offset:49152
	ds_read_b128 v[188:191], v162 offset:50176
	ds_read_b128 v[192:195], v162 offset:51200
	ds_read_b128 v[196:199], v162 offset:52224
	ds_read_b128 v[200:203], v162 offset:53248
	ds_read_b128 v[204:207], v162 offset:54272
	ds_read_b128 v[208:211], v162 offset:55296
	ds_read_b128 v[212:215], v162 offset:56320
	global_load_lds_dwordx4 v[184:185], off nt
	s_add_i32 m0, s24, 0x2000
	s_add_u32 s14, s14, 0x80080
	v_lshl_add_u64 v[184:185], v[216:217], 0, s[84:85]
	s_addc_u32 s15, s15, 0
	s_add_i32 s24, s65, s28
	global_load_lds_dwordx4 v[184:185], off nt
	v_lshl_add_u64 v[184:185], s[14:15], 0, v[150:151]
	s_mov_b32 m0, s24
	s_nop 0
	global_load_lds_dwordx4 v[184:185], off nt
	v_lshl_add_u64 v[184:185], s[14:15], 0, v[146:147]
	s_add_i32 m0, s24, 0x2000
	s_nop 0
	global_load_lds_dwordx4 v[184:185], off nt
	v_lshl_add_u64 v[184:185], v[218:219], 0, s[84:85]
	s_mov_b32 m0, s44
	s_nop 0
	global_load_lds_dwordx4 v[184:185], off
	v_lshl_add_u64 v[184:185], v[220:221], 0, s[84:85]
	s_mov_b32 m0, s45
	s_nop 0
	global_load_lds_dwordx4 v[184:185], off
	s_waitcnt vmcnt(8)
	s_waitcnt lgkmcnt(0)
	s_barrier
	s_setprio 1
	s_waitcnt lgkmcnt(0)
	v_mfma_f32_16x16x32_bf16 v[62:65], v[130:133], v[176:179], v[62:65]
	v_mfma_f32_16x16x32_bf16 v[58:61], v[138:141], v[176:179], v[58:61]
	v_mfma_f32_16x16x32_bf16 v[54:57], v[130:133], v[192:195], v[54:57]
	v_mfma_f32_16x16x32_bf16 v[46:49], v[138:141], v[192:195], v[46:49]
	v_mfma_f32_16x16x32_bf16 v[38:41], v[130:133], v[200:203], v[38:41]
	v_mfma_f32_16x16x32_bf16 v[30:33], v[138:141], v[200:203], v[30:33]
	v_mfma_f32_16x16x32_bf16 v[22:25], v[130:133], v[208:211], v[22:25]
	v_mfma_f32_16x16x32_bf16 v[14:17], v[138:141], v[208:211], v[14:17]
	v_mfma_f32_16x16x32_bf16 v[62:65], v[134:137], v[188:191], v[62:65]
	v_mfma_f32_16x16x32_bf16 v[58:61], v[142:145], v[188:191], v[58:61]
	v_mfma_f32_16x16x32_bf16 v[54:57], v[134:137], v[196:199], v[54:57]
	v_mfma_f32_16x16x32_bf16 v[46:49], v[142:145], v[196:199], v[46:49]
	v_mfma_f32_16x16x32_bf16 v[38:41], v[134:137], v[204:207], v[38:41]
	v_mfma_f32_16x16x32_bf16 v[30:33], v[142:145], v[204:207], v[30:33]
	v_mfma_f32_16x16x32_bf16 v[22:25], v[134:137], v[212:215], v[22:25]
	v_mfma_f32_16x16x32_bf16 v[14:17], v[142:145], v[212:215], v[14:17]
	s_setprio 0
	s_setprio 1
	v_mfma_f32_16x16x32_bf16 v[50:53], v[158:161], v[176:179], v[50:53]
	v_mfma_f32_16x16x32_bf16 v[42:45], v[168:171], v[176:179], v[42:45]
	v_mfma_f32_16x16x32_bf16 v[34:37], v[158:161], v[192:195], v[34:37]
	v_mfma_f32_16x16x32_bf16 v[26:29], v[168:171], v[192:195], v[26:29]
	v_mfma_f32_16x16x32_bf16 v[18:21], v[158:161], v[200:203], v[18:21]
	v_mfma_f32_16x16x32_bf16 v[10:13], v[168:171], v[200:203], v[10:13]
	v_mfma_f32_16x16x32_bf16 v[6:9], v[158:161], v[208:211], v[6:9]
	v_mfma_f32_16x16x32_bf16 v[2:5], v[168:171], v[208:211], v[2:5]
	v_mfma_f32_16x16x32_bf16 v[50:53], v[164:167], v[188:191], v[50:53]
	v_mfma_f32_16x16x32_bf16 v[42:45], v[172:175], v[188:191], v[42:45]
	v_mfma_f32_16x16x32_bf16 v[34:37], v[164:167], v[196:199], v[34:37]
	v_mfma_f32_16x16x32_bf16 v[26:29], v[172:175], v[196:199], v[26:29]
	v_mfma_f32_16x16x32_bf16 v[18:21], v[164:167], v[204:207], v[18:21]
	v_mfma_f32_16x16x32_bf16 v[10:13], v[172:175], v[204:207], v[10:13]
	v_mfma_f32_16x16x32_bf16 v[6:9], v[164:167], v[212:215], v[6:9]
	v_mfma_f32_16x16x32_bf16 v[2:5], v[172:175], v[212:215], v[2:5]
	s_setprio 0
	s_barrier
	s_add_i32 s64, s64, 2
	s_add_u32 s22, s22, 0x100
	s_addc_u32 s23, s23, 0
	s_add_u32 s40, s40, 0x100
	s_addc_u32 s63, s63, 0
	s_cmp_gt_u32 s64, 29
	s_cbranch_scc0 .LBB0_1412
	s_and_b64 vcc, exec, s[10:11]
	s_cbranch_vccz .LBB0_1415
	s_barrier

; #define PG8_STAGE(bufoff, gbase, voff) do { _Pragma("unroll") for (int _i = 0; _i < 2; ++_i) \
;         __builtin_amdgcn_global_load_lds((const unsigned*)((const char*)(gbase) + (voff)[_i]), (LAS unsigned*)(lds + (bufoff) + ldsw + _i * 8192), 16, 0, 0); } while (0)
; #define PG8_LDA(dst, b, h) do { _Pragma("unroll") for (int m = 0; m < 4; ++m) _Pragma("unroll") for (int k = 0; k < 2; ++k) dst[m][k] = *(const LAS bf16x8*)(lds + PG8_SA(b, h) + aoff + m * 2048 + k * 1024); } while (0)
; #define PG8_LDB(dst, b, h) do { _Pragma("unroll") for (int n = 0; n < 2; ++n) _Pragma("unroll") for (int k = 0; k < 2; ++k) dst[n][k] = *(const LAS bf16x8*)(lds + PG8_SB(b, h) + boff + n * 2048 + k * 1024); } while (0)
; #define PG8_MMA(ai, bj, At, Bt) do { __builtin_amdgcn_s_setprio(1); _Pragma("unroll") for (int m = 0; m < 4; ++m) _Pragma("unroll") for (int n = 0; n < 2; ++n) _Pragma("unroll") for (int k = 0; k < 2; ++k) \
;         acc[ai][bj][m][n] = __builtin_amdgcn_mfma_f32_16x16x32_bf16(Bt[n][k], At[m][k], acc[ai][bj][m][n], 0, 0, 0); __builtin_amdgcn_s_setprio(0); } while (0)
; #define PG8_WAIT_V(n) asm volatile("s_waitcnt vmcnt(" #n ")" ::: "memory")
; #define PG8_WAIT_L(n) asm volatile("s_waitcnt lgkmcnt(" #n ")" ::: "memory")
; #define PG8_BAR __builtin_amdgcn_s_barrier()
; #define PG8_SCHED __builtin_amdgcn_sched_barrier(0)
; template <class Epi>
; __device__ __forceinline__ void gemm_phase(LAS unsigned char* lds, const Gemm g, const StaticOrder& S, const Epi& E) {
;     ...
;             const bool last = (t == nt - 2);
;             const char* a1 = cA + (size_t)(t + 1) * kstep;
;             const char* a2 = last ? nA : cA + (size_t)(t + 2) * kstep; const char* b2 = last ? nB : cB + (size_t)(t + 2) * kstep;
;             const char* a3 = a2 + kstep; const char* b3 = b2 + kstep;
;             PG8_LDB(B0, 0, 0); PG8_LDB(B1, 0, 1); PG8_SCHED; PG8_LDA(At, 0, 0); PG8_STAGE(PG8_SA(1, 1), a1 + hstepA, voffA);
;             PG8_WAIT_V(8); PG8_WAIT_L(0); PG8_BAR; PG8_MMA(0, 0, At, B0); PG8_MMA(0, 1, At, B1); PG8_BAR; PG8_SCHED;
;             PG8_LDA(At, 0, 1); PG8_STAGE(PG8_SB(0, 0), b2, voffB); PG8_STAGE(PG8_SB(0, 1), b2 + hstepB, voffB); PG8_STAGE(PG8_SA(0, 0), a2, voffA);
.LBB0_1440:
	s_add_u32 s41, s20, s14
	s_addc_u32 s44, s21, 0
	s_add_u32 s15, s41, 0x100
	s_addc_u32 s34, s44, 0
	s_and_b64 s[30:31], s[28:29], exec
	s_cselect_b32 s31, s19, s34
	s_cselect_b32 s30, s3, s15
	s_add_u32 s14, s12, s14
	s_addc_u32 s15, s13, 0
	s_add_u32 s34, s14, 0x100
	s_addc_u32 s35, s15, 0
	s_add_i32 s81, 0, 0x10000
	s_and_b64 s[14:15], s[28:29], exec
	s_cselect_b32 s35, s17, s35
	s_cselect_b32 s34, s40, s34
	s_add_i32 s29, 0, 0x14000
	s_add_u32 s68, s41, 0x10080
	s_addc_u32 s69, s44, 0
	s_add_i32 s77, s81, s63
	s_add_i32 m0, s11, 0xc000
	s_add_i32 s83, s11, 0xe000
	s_add_i32 s80, s77, 0x2000
	v_add_u32_e32 v139, s81, v1
	s_add_u32 s44, s34, 0x10000
	ds_read_b128 v[140:143], v139
	ds_read_b128 v[144:147], v139 offset:1024
	ds_read_b128 v[148:151], v139 offset:2048
	ds_read_b128 v[152:155], v139 offset:3072
	v_add_u32_e32 v139, s29, v1
	s_addc_u32 s45, s35, 0
	s_add_i32 s79, s29, s63
	ds_read_b128 v[156:159], v139
	ds_read_b128 v[160:163], v139 offset:1024
	ds_read_b128 v[164:167], v139 offset:2048
	ds_read_b128 v[168:171], v139 offset:3072
	s_add_i32 s78, s79, 0x2000
	s_add_i32 vcc_lo, 0, 0x18000
	s_add_i32 vcc_hi, 0, 0x1c000
	s_add_u32 s14, s30, 0x10000
	s_addc_u32 s15, s31, 0
	s_add_i32 s41, vcc_lo, s63
	s_add_i32 s76, s41, 0x2000
	s_add_u32 s28, s34, 0x10080
	s_addc_u32 s29, s35, 0
	s_add_i32 s81, vcc_hi, s63
	s_add_i32 s82, s81, 0x2000
	v_lshl_add_u64 v[184:185], s[68:69], 0, v[130:131]
	ds_read_b128 v[172:175], v138
	ds_read_b128 v[176:179], v138 offset:1024
	ds_read_b128 v[188:191], v138 offset:2048
	ds_read_b128 v[192:195], v138 offset:3072
	ds_read_b128 v[196:199], v138 offset:4096
	ds_read_b128 v[200:203], v138 offset:5120
	ds_read_b128 v[204:207], v138 offset:6144
	ds_read_b128 v[208:211], v138 offset:7168
	global_load_lds_dwordx4 v[184:185], off
	v_lshl_add_u64 v[184:185], s[68:69], 0, v[134:135]
	s_mov_b32 m0, s83
	s_nop 0
	global_load_lds_dwordx4 v[184:185], off
	s_waitcnt vmcnt(8)
	s_waitcnt lgkmcnt(0)
	s_barrier
	s_setprio 1
	s_waitcnt lgkmcnt(0)
	v_mfma_f32_16x16x32_bf16 v[126:129], v[140:143], v[172:175], v[126:129]
	v_mfma_f32_16x16x32_bf16 v[122:125], v[148:151], v[172:175], v[122:125]
	v_mfma_f32_16x16x32_bf16 v[118:121], v[140:143], v[188:191], v[118:121]
	v_mfma_f32_16x16x32_bf16 v[114:117], v[148:151], v[188:191], v[114:117]
	v_mfma_f32_16x16x32_bf16 v[102:105], v[140:143], v[196:199], v[102:105]
	v_mfma_f32_16x16x32_bf16 v[98:101], v[148:151], v[196:199], v[98:101]
	v_mfma_f32_16x16x32_bf16 v[86:89], v[140:143], v[204:207], v[86:89]
	v_mfma_f32_16x16x32_bf16 v[82:85], v[148:151], v[204:207], v[82:85]
	v_mfma_f32_16x16x32_bf16 v[126:129], v[144:147], v[176:179], v[126:129]
	v_mfma_f32_16x16x32_bf16 v[122:125], v[152:155], v[176:179], v[122:125]
	v_mfma_f32_16x16x32_bf16 v[118:121], v[144:147], v[192:195], v[118:121]
	v_mfma_f32_16x16x32_bf16 v[114:117], v[152:155], v[192:195], v[114:117]
	v_mfma_f32_16x16x32_bf16 v[102:105], v[144:147], v[200:203], v[102:105]
	v_mfma_f32_16x16x32_bf16 v[98:101], v[152:155], v[200:203], v[98:101]
	v_mfma_f32_16x16x32_bf16 v[86:89], v[144:147], v[208:211], v[86:89]
	v_mfma_f32_16x16x32_bf16 v[82:85], v[152:155], v[208:211], v[82:85]
	s_setprio 0
	s_setprio 1
	v_mfma_f32_16x16x32_bf16 v[110:113], v[156:159], v[172:175], v[110:113]
	v_mfma_f32_16x16x32_bf16 v[106:109], v[164:167], v[172:175], v[106:109]
	v_mfma_f32_16x16x32_bf16 v[94:97], v[156:159], v[188:191], v[94:97]
	v_mfma_f32_16x16x32_bf16 v[90:93], v[164:167], v[188:191], v[90:93]
	v_mfma_f32_16x16x32_bf16 v[78:81], v[156:159], v[196:199], v[78:81]
	v_mfma_f32_16x16x32_bf16 v[74:77], v[164:167], v[196:199], v[74:77]
	v_mfma_f32_16x16x32_bf16 v[70:73], v[156:159], v[204:207], v[70:73]
	v_mfma_f32_16x16x32_bf16 v[66:69], v[164:167], v[204:207], v[66:69]
	v_mfma_f32_16x16x32_bf16 v[110:113], v[160:163], v[176:179], v[110:113]
	v_mfma_f32_16x16x32_bf16 v[106:109], v[168:171], v[176:179], v[106:109]
	v_mfma_f32_16x16x32_bf16 v[94:97], v[160:163], v[192:195], v[94:97]
	v_mfma_f32_16x16x32_bf16 v[90:93], v[168:171], v[192:195], v[90:93]
	v_mfma_f32_16x16x32_bf16 v[78:81], v[160:163], v[200:203], v[78:81]
	v_mfma_f32_16x16x32_bf16 v[74:77], v[168:171], v[200:203], v[74:77]
	v_mfma_f32_16x16x32_bf16 v[70:73], v[160:163], v[208:211], v[70:73]
	v_mfma_f32_16x16x32_bf16 v[66:69], v[168:171], v[208:211], v[66:69]
	s_setprio 0
	s_barrier
	s_mov_b32 m0, s77
	v_lshl_add_u64 v[184:185], s[34:35], 0, v[132:133]
	ds_read_b128 v[172:175], v138 offset:16384
	ds_read_b128 v[176:179], v138 offset:17408
	ds_read_b128 v[188:191], v138 offset:18432
	ds_read_b128 v[192:195], v138 offset:19456
	ds_read_b128 v[196:199], v138 offset:20480
	ds_read_b128 v[200:203], v138 offset:21504
	ds_read_b128 v[204:207], v138 offset:22528
	ds_read_b128 v[208:211], v138 offset:23552
	global_load_lds_dwordx4 v[184:185], off nt
	v_lshl_add_u64 v[212:213], s[34:35], 0, v[136:137]
	s_mov_b32 m0, s80
	v_lshl_add_u64 v[214:215], s[44:45], 0, v[132:133]
	global_load_lds_dwordx4 v[212:213], off nt
	s_mov_b32 m0, s79
	v_lshl_add_u64 v[216:217], s[30:31], 0, v[134:135]
	global_load_lds_dwordx4 v[214:215], off nt
	v_lshl_add_u64 v[214:215], s[44:45], 0, v[136:137]
	s_mov_b32 m0, s78
	s_nop 0
	global_load_lds_dwordx4 v[214:215], off nt
	v_lshl_add_u64 v[214:215], s[30:31], 0, v[130:131]
	s_mov_b32 m0, s11
	s_nop 0
	global_load_lds_dwordx4 v[214:215], off
	s_mov_b32 m0, s64
	s_nop 0
	global_load_lds_dwordx4 v[216:217], off
	s_waitcnt vmcnt(8)
	s_waitcnt lgkmcnt(0)
	s_barrier
; #define PG8_STAGE(bufoff, gbase, voff) do { _Pragma("unroll") for (int _i = 0; _i < 2; ++_i) \
;         __builtin_amdgcn_global_load_lds((const unsigned*)((const char*)(gbase) + (voff)[_i]), (LAS unsigned*)(lds + (bufoff) + ldsw + _i * 8192), 16, 0, 0); } while (0)
; #define PG8_LDA(dst, b, h) do { _Pragma("unroll") for (int m = 0; m < 4; ++m) _Pragma("unroll") for (int k = 0; k < 2; ++k) dst[m][k] = *(const LAS bf16x8*)(lds + PG8_SA(b, h) + aoff + m * 2048 + k * 1024); } while (0)
; #define PG8_LDB(dst, b, h) do { _Pragma("unroll") for (int n = 0; n < 2; ++n) _Pragma("unroll") for (int k = 0; k < 2; ++k) dst[n][k] = *(const LAS bf16x8*)(lds + PG8_SB(b, h) + boff + n * 2048 + k * 1024); } while (0)
; #define PG8_MMA(ai, bj, At, Bt) do { __builtin_amdgcn_s_setprio(1); _Pragma("unroll") for (int m = 0; m < 4; ++m) _Pragma("unroll") for (int n = 0; n < 2; ++n) _Pragma("unroll") for (int k = 0; k < 2; ++k) \
;         acc[ai][bj][m][n] = __builtin_amdgcn_mfma_f32_16x16x32_bf16(Bt[n][k], At[m][k], acc[ai][bj][m][n], 0, 0, 0); __builtin_amdgcn_s_setprio(0); } while (0)
; #define PG8_WAIT_V(n) asm volatile("s_waitcnt vmcnt(" #n ")" ::: "memory")
; #define PG8_WAIT_L(n) asm volatile("s_waitcnt lgkmcnt(" #n ")" ::: "memory")
; #define PG8_BAR __builtin_amdgcn_s_barrier()
; #define PG8_SCHED __builtin_amdgcn_sched_barrier(0)
; template <class Epi>
; __device__ __forceinline__ void gemm_phase(LAS unsigned char* lds, const Gemm g, const StaticOrder& S, const Epi& E) {
;     ...
;             PG8_WAIT_V(8); PG8_WAIT_L(0); PG8_BAR; PG8_MMA(1, 0, At, B0); PG8_MMA(1, 1, At, B1); PG8_BAR; PG8_SCHED;
;             PG8_LDB(B0, 1, 0); PG8_LDB(B1, 1, 1); PG8_SCHED; PG8_LDA(At, 1, 0); PG8_STAGE(PG8_SA(0, 1), a2 + hstepA, voffA);
;             PG8_WAIT_V(8); PG8_WAIT_L(0); PG8_BAR; PG8_MMA(0, 0, At, B0); PG8_MMA(0, 1, At, B1); PG8_BAR; PG8_SCHED;
	s_setprio 1
	s_waitcnt lgkmcnt(0)
	v_mfma_f32_16x16x32_bf16 v[62:65], v[140:143], v[172:175], v[62:65]
	v_mfma_f32_16x16x32_bf16 v[58:61], v[148:151], v[172:175], v[58:61]
	v_mfma_f32_16x16x32_bf16 v[54:57], v[140:143], v[188:191], v[54:57]
	v_mfma_f32_16x16x32_bf16 v[50:53], v[148:151], v[188:191], v[50:53]
	v_mfma_f32_16x16x32_bf16 v[38:41], v[140:143], v[196:199], v[38:41]
	v_mfma_f32_16x16x32_bf16 v[34:37], v[148:151], v[196:199], v[34:37]
	v_mfma_f32_16x16x32_bf16 v[22:25], v[140:143], v[204:207], v[22:25]
	v_mfma_f32_16x16x32_bf16 v[18:21], v[148:151], v[204:207], v[18:21]
	v_mfma_f32_16x16x32_bf16 v[62:65], v[144:147], v[176:179], v[62:65]
	v_mfma_f32_16x16x32_bf16 v[58:61], v[152:155], v[176:179], v[58:61]
	v_mfma_f32_16x16x32_bf16 v[54:57], v[144:147], v[192:195], v[54:57]
	v_mfma_f32_16x16x32_bf16 v[50:53], v[152:155], v[192:195], v[50:53]
	v_mfma_f32_16x16x32_bf16 v[38:41], v[144:147], v[200:203], v[38:41]
	v_mfma_f32_16x16x32_bf16 v[34:37], v[152:155], v[200:203], v[34:37]
	v_mfma_f32_16x16x32_bf16 v[22:25], v[144:147], v[208:211], v[22:25]
	v_mfma_f32_16x16x32_bf16 v[18:21], v[152:155], v[208:211], v[18:21]
	s_setprio 0
	s_setprio 1
	v_mfma_f32_16x16x32_bf16 v[46:49], v[156:159], v[172:175], v[46:49]
	v_mfma_f32_16x16x32_bf16 v[42:45], v[164:167], v[172:175], v[42:45]
	v_mfma_f32_16x16x32_bf16 v[30:33], v[156:159], v[188:191], v[30:33]
	v_mfma_f32_16x16x32_bf16 v[26:29], v[164:167], v[188:191], v[26:29]
	v_mfma_f32_16x16x32_bf16 v[14:17], v[156:159], v[196:199], v[14:17]
	v_mfma_f32_16x16x32_bf16 v[10:13], v[164:167], v[196:199], v[10:13]
	v_mfma_f32_16x16x32_bf16 v[6:9], v[156:159], v[204:207], v[6:9]
	v_mfma_f32_16x16x32_bf16 v[2:5], v[164:167], v[204:207], v[2:5]
	v_mfma_f32_16x16x32_bf16 v[46:49], v[160:163], v[176:179], v[46:49]
	v_mfma_f32_16x16x32_bf16 v[42:45], v[168:171], v[176:179], v[42:45]
	v_mfma_f32_16x16x32_bf16 v[30:33], v[160:163], v[192:195], v[30:33]
	v_mfma_f32_16x16x32_bf16 v[26:29], v[168:171], v[192:195], v[26:29]
	v_mfma_f32_16x16x32_bf16 v[14:17], v[160:163], v[200:203], v[14:17]
	v_mfma_f32_16x16x32_bf16 v[10:13], v[168:171], v[200:203], v[10:13]
	v_mfma_f32_16x16x32_bf16 v[6:9], v[160:163], v[208:211], v[6:9]
	v_mfma_f32_16x16x32_bf16 v[2:5], v[168:171], v[208:211], v[2:5]
	s_setprio 0
	s_barrier
	v_add_u32_e32 v139, vcc_lo, v1
	ds_read_b128 v[140:143], v139
	ds_read_b128 v[144:147], v139 offset:1024
	ds_read_b128 v[148:151], v139 offset:2048
	ds_read_b128 v[152:155], v139 offset:3072
	v_add_u32_e32 v139, vcc_hi, v1
	ds_read_b128 v[156:159], v139
	ds_read_b128 v[160:163], v139 offset:1024
	ds_read_b128 v[164:167], v139 offset:2048
	ds_read_b128 v[168:171], v139 offset:3072
	s_mov_b32 m0, s65
	v_lshl_add_u64 v[218:219], s[14:15], 0, v[130:131]
	ds_read_b128 v[172:175], v138 offset:32768
	ds_read_b128 v[176:179], v138 offset:33792
	ds_read_b128 v[188:191], v138 offset:34816
	ds_read_b128 v[192:195], v138 offset:35840
	ds_read_b128 v[196:199], v138 offset:36864
	ds_read_b128 v[200:203], v138 offset:37888
	ds_read_b128 v[204:207], v138 offset:38912
	ds_read_b128 v[208:211], v138 offset:39936
	global_load_lds_dwordx4 v[218:219], off
	v_lshl_add_u64 v[218:219], s[14:15], 0, v[134:135]
	s_mov_b32 m0, s70
	s_nop 0
	global_load_lds_dwordx4 v[218:219], off
	s_waitcnt vmcnt(8)
	s_waitcnt lgkmcnt(0)
	s_barrier
	s_setprio 1
	s_waitcnt lgkmcnt(0)
	v_mfma_f32_16x16x32_bf16 v[126:129], v[140:143], v[172:175], v[126:129]
	v_mfma_f32_16x16x32_bf16 v[122:125], v[148:151], v[172:175], v[122:125]
	v_mfma_f32_16x16x32_bf16 v[118:121], v[140:143], v[188:191], v[118:121]
	v_mfma_f32_16x16x32_bf16 v[114:117], v[148:151], v[188:191], v[114:117]
	v_mfma_f32_16x16x32_bf16 v[102:105], v[140:143], v[196:199], v[102:105]
	v_mfma_f32_16x16x32_bf16 v[98:101], v[148:151], v[196:199], v[98:101]
	v_mfma_f32_16x16x32_bf16 v[86:89], v[140:143], v[204:207], v[86:89]
	v_mfma_f32_16x16x32_bf16 v[82:85], v[148:151], v[204:207], v[82:85]
	v_mfma_f32_16x16x32_bf16 v[126:129], v[144:147], v[176:179], v[126:129]
	v_mfma_f32_16x16x32_bf16 v[122:125], v[152:155], v[176:179], v[122:125]
	v_mfma_f32_16x16x32_bf16 v[118:121], v[144:147], v[192:195], v[118:121]
	v_mfma_f32_16x16x32_bf16 v[114:117], v[152:155], v[192:195], v[114:117]
	v_mfma_f32_16x16x32_bf16 v[102:105], v[144:147], v[200:203], v[102:105]
	v_mfma_f32_16x16x32_bf16 v[98:101], v[152:155], v[200:203], v[98:101]
	v_mfma_f32_16x16x32_bf16 v[86:89], v[144:147], v[208:211], v[86:89]
	v_mfma_f32_16x16x32_bf16 v[82:85], v[152:155], v[208:211], v[82:85]
	s_setprio 0
	s_setprio 1
	v_mfma_f32_16x16x32_bf16 v[110:113], v[156:159], v[172:175], v[110:113]
	v_mfma_f32_16x16x32_bf16 v[106:109], v[164:167], v[172:175], v[106:109]
	v_mfma_f32_16x16x32_bf16 v[94:97], v[156:159], v[188:191], v[94:97]
	v_mfma_f32_16x16x32_bf16 v[90:93], v[164:167], v[188:191], v[90:93]
	v_mfma_f32_16x16x32_bf16 v[78:81], v[156:159], v[196:199], v[78:81]
	v_mfma_f32_16x16x32_bf16 v[74:77], v[164:167], v[196:199], v[74:77]
	v_mfma_f32_16x16x32_bf16 v[70:73], v[156:159], v[204:207], v[70:73]
	v_mfma_f32_16x16x32_bf16 v[66:69], v[164:167], v[204:207], v[66:69]
	v_mfma_f32_16x16x32_bf16 v[110:113], v[160:163], v[176:179], v[110:113]
	v_mfma_f32_16x16x32_bf16 v[106:109], v[168:171], v[176:179], v[106:109]
	v_mfma_f32_16x16x32_bf16 v[94:97], v[160:163], v[192:195], v[94:97]
	v_mfma_f32_16x16x32_bf16 v[90:93], v[168:171], v[192:195], v[90:93]
	v_mfma_f32_16x16x32_bf16 v[78:81], v[160:163], v[200:203], v[78:81]
	v_mfma_f32_16x16x32_bf16 v[74:77], v[168:171], v[200:203], v[74:77]
	v_mfma_f32_16x16x32_bf16 v[70:73], v[160:163], v[208:211], v[70:73]
	v_mfma_f32_16x16x32_bf16 v[66:69], v[168:171], v[208:211], v[66:69]
	s_setprio 0
	s_barrier
; #define PG8_STAGE(bufoff, gbase, voff) do { _Pragma("unroll") for (int _i = 0; _i < 2; ++_i) \
;         __builtin_amdgcn_global_load_lds((const unsigned*)((const char*)(gbase) + (voff)[_i]), (LAS unsigned*)(lds + (bufoff) + ldsw + _i * 8192), 16, 0, 0); } while (0)
; #define PG8_LDA(dst, b, h) do { _Pragma("unroll") for (int m = 0; m < 4; ++m) _Pragma("unroll") for (int k = 0; k < 2; ++k) dst[m][k] = *(const LAS bf16x8*)(lds + PG8_SA(b, h) + aoff + m * 2048 + k * 1024); } while (0)
; #define PG8_MMA(ai, bj, At, Bt) do { __builtin_amdgcn_s_setprio(1); _Pragma("unroll") for (int m = 0; m < 4; ++m) _Pragma("unroll") for (int n = 0; n < 2; ++n) _Pragma("unroll") for (int k = 0; k < 2; ++k) \
;         acc[ai][bj][m][n] = __builtin_amdgcn_mfma_f32_16x16x32_bf16(Bt[n][k], At[m][k], acc[ai][bj][m][n], 0, 0, 0); __builtin_amdgcn_s_setprio(0); } while (0)
; #define PG8_WAIT_V(n) asm volatile("s_waitcnt vmcnt(" #n ")" ::: "memory")
; #define PG8_WAIT_L(n) asm volatile("s_waitcnt lgkmcnt(" #n ")" ::: "memory")
; #define PG8_BAR __builtin_amdgcn_s_barrier()
; #define PG8_SCHED __builtin_amdgcn_sched_barrier(0)
; template <class Epi>
; __device__ __forceinline__ void gemm_phase(LAS unsigned char* lds, const Gemm g, const StaticOrder& S, const Epi& E) {
;     ...
;             PG8_LDA(At, 1, 1); PG8_STAGE(PG8_SB(1, 0), b3, voffB); PG8_STAGE(PG8_SB(1, 1), b3 + hstepB, voffB); PG8_STAGE(PG8_SA(1, 0), a3, voffA);
;             PG8_WAIT_V(8); PG8_WAIT_L(0); PG8_BAR; PG8_MMA(1, 0, At, B0); PG8_MMA(1, 1, At, B1); PG8_BAR; PG8_SCHED;
;         }
;         if (wr == 0) PG8_BAR;
	s_mov_b32 m0, s41
	v_lshl_add_u64 v[184:185], v[184:185], 0, s[84:85]
	ds_read_b128 v[172:175], v138 offset:49152
	ds_read_b128 v[176:179], v138 offset:50176
	ds_read_b128 v[188:191], v138 offset:51200
	ds_read_b128 v[192:195], v138 offset:52224
	ds_read_b128 v[196:199], v138 offset:53248
	ds_read_b128 v[200:203], v138 offset:54272
	ds_read_b128 v[204:207], v138 offset:55296
	ds_read_b128 v[208:211], v138 offset:56320
	global_load_lds_dwordx4 v[184:185], off nt
	v_lshl_add_u64 v[184:185], v[212:213], 0, s[84:85]
	s_mov_b32 m0, s76
	s_nop 0
	global_load_lds_dwordx4 v[184:185], off nt
	v_lshl_add_u64 v[184:185], s[28:29], 0, v[132:133]
	s_mov_b32 m0, s81
	s_nop 0
	global_load_lds_dwordx4 v[184:185], off nt
	v_lshl_add_u64 v[184:185], s[28:29], 0, v[136:137]
	s_mov_b32 m0, s82
	s_nop 0
	global_load_lds_dwordx4 v[184:185], off nt
	v_lshl_add_u64 v[184:185], v[214:215], 0, s[84:85]
	s_mov_b32 m0, s86
	s_nop 0
	global_load_lds_dwordx4 v[184:185], off
	v_lshl_add_u64 v[184:185], v[216:217], 0, s[84:85]
	s_mov_b32 m0, s87
	s_nop 0
	global_load_lds_dwordx4 v[184:185], off
	s_waitcnt vmcnt(8)
	s_waitcnt lgkmcnt(0)
	s_barrier
	s_setprio 1
	s_waitcnt lgkmcnt(0)
	v_mfma_f32_16x16x32_bf16 v[62:65], v[140:143], v[172:175], v[62:65]
	v_mfma_f32_16x16x32_bf16 v[58:61], v[148:151], v[172:175], v[58:61]
	v_mfma_f32_16x16x32_bf16 v[54:57], v[140:143], v[188:191], v[54:57]
	v_mfma_f32_16x16x32_bf16 v[50:53], v[148:151], v[188:191], v[50:53]
	v_mfma_f32_16x16x32_bf16 v[38:41], v[140:143], v[196:199], v[38:41]
	v_mfma_f32_16x16x32_bf16 v[34:37], v[148:151], v[196:199], v[34:37]
	v_mfma_f32_16x16x32_bf16 v[22:25], v[140:143], v[204:207], v[22:25]
	v_mfma_f32_16x16x32_bf16 v[18:21], v[148:151], v[204:207], v[18:21]
	v_mfma_f32_16x16x32_bf16 v[62:65], v[144:147], v[176:179], v[62:65]
	v_mfma_f32_16x16x32_bf16 v[58:61], v[152:155], v[176:179], v[58:61]
	v_mfma_f32_16x16x32_bf16 v[54:57], v[144:147], v[192:195], v[54:57]
	v_mfma_f32_16x16x32_bf16 v[50:53], v[152:155], v[192:195], v[50:53]
	v_mfma_f32_16x16x32_bf16 v[38:41], v[144:147], v[200:203], v[38:41]
	v_mfma_f32_16x16x32_bf16 v[34:37], v[152:155], v[200:203], v[34:37]
	v_mfma_f32_16x16x32_bf16 v[22:25], v[144:147], v[208:211], v[22:25]
	v_mfma_f32_16x16x32_bf16 v[18:21], v[152:155], v[208:211], v[18:21]
	s_setprio 0
	s_setprio 1
	v_mfma_f32_16x16x32_bf16 v[46:49], v[156:159], v[172:175], v[46:49]
	v_mfma_f32_16x16x32_bf16 v[42:45], v[164:167], v[172:175], v[42:45]
	v_mfma_f32_16x16x32_bf16 v[30:33], v[156:159], v[188:191], v[30:33]
	v_mfma_f32_16x16x32_bf16 v[26:29], v[164:167], v[188:191], v[26:29]
	v_mfma_f32_16x16x32_bf16 v[14:17], v[156:159], v[196:199], v[14:17]
	v_mfma_f32_16x16x32_bf16 v[10:13], v[164:167], v[196:199], v[10:13]
	v_mfma_f32_16x16x32_bf16 v[6:9], v[156:159], v[204:207], v[6:9]
	v_mfma_f32_16x16x32_bf16 v[2:5], v[164:167], v[204:207], v[2:5]
	v_mfma_f32_16x16x32_bf16 v[46:49], v[160:163], v[176:179], v[46:49]
	v_mfma_f32_16x16x32_bf16 v[42:45], v[168:171], v[176:179], v[42:45]
	v_mfma_f32_16x16x32_bf16 v[30:33], v[160:163], v[192:195], v[30:33]
	v_mfma_f32_16x16x32_bf16 v[26:29], v[168:171], v[192:195], v[26:29]
	v_mfma_f32_16x16x32_bf16 v[14:17], v[160:163], v[200:203], v[14:17]
	v_mfma_f32_16x16x32_bf16 v[10:13], v[168:171], v[200:203], v[10:13]
	v_mfma_f32_16x16x32_bf16 v[6:9], v[160:163], v[208:211], v[6:9]
	v_mfma_f32_16x16x32_bf16 v[2:5], v[168:171], v[208:211], v[2:5]
	s_setprio 0
	s_barrier
	s_movk_i32 s14, 0x100
	s_andn2_b64 vcc, exec, s[26:27]
	s_mov_b64 s[28:29], -1
	s_mov_b64 s[26:27], 0
	s_cbranch_vccz .LBB0_1440
	v_readlane_b32 s28, v255, 28
	s_and_b64 vcc, exec, s[8:9]
	v_readlane_b32 s29, v255, 29
	s_cbranch_vccz .LBB0_1443
	s_barrier

; #define PG8_STAGE(bufoff, gbase, voff) do { _Pragma("unroll") for (int _i = 0; _i < 2; ++_i) \
;         __builtin_amdgcn_global_load_lds((const unsigned*)((const char*)(gbase) + (voff)[_i]), (LAS unsigned*)(lds + (bufoff) + ldsw + _i * 8192), 16, 0, 0); } while (0)
; #define PG8_LDA(dst, b, h) do { _Pragma("unroll") for (int m = 0; m < 4; ++m) _Pragma("unroll") for (int k = 0; k < 2; ++k) dst[m][k] = *(const LAS bf16x8*)(lds + PG8_SA(b, h) + aoff + m * 2048 + k * 1024); } while (0)
; #define PG8_LDB(dst, b, h) do { _Pragma("unroll") for (int n = 0; n < 2; ++n) _Pragma("unroll") for (int k = 0; k < 2; ++k) dst[n][k] = *(const LAS bf16x8*)(lds + PG8_SB(b, h) + boff + n * 2048 + k * 1024); } while (0)
; #define PG8_MMA(ai, bj, At, Bt) do { __builtin_amdgcn_s_setprio(1); _Pragma("unroll") for (int m = 0; m < 4; ++m) _Pragma("unroll") for (int n = 0; n < 2; ++n) _Pragma("unroll") for (int k = 0; k < 2; ++k) \
;         acc[ai][bj][m][n] = __builtin_amdgcn_mfma_f32_16x16x32_bf16(Bt[n][k], At[m][k], acc[ai][bj][m][n], 0, 0, 0); __builtin_amdgcn_s_setprio(0); } while (0)
; #define PG8_WAIT_V(n) asm volatile("s_waitcnt vmcnt(" #n ")" ::: "memory")
; #define PG8_WAIT_L(n) asm volatile("s_waitcnt lgkmcnt(" #n ")" ::: "memory")
; #define PG8_BAR __builtin_amdgcn_s_barrier()
; #define PG8_SCHED __builtin_amdgcn_sched_barrier(0)
; template <class Epi>
; __device__ __forceinline__ void gemm_phase(LAS unsigned char* lds, const Gemm g, const StaticOrder& S, const Epi& E) {
;     ...
;             const bool last = (t == nt - 2);
;             const char* a1 = cA + (size_t)(t + 1) * kstep;
;             const char* a2 = last ? nA : cA + (size_t)(t + 2) * kstep; const char* b2 = last ? nB : cB + (size_t)(t + 2) * kstep;
;             const char* a3 = a2 + kstep; const char* b3 = b2 + kstep;
;             PG8_LDB(B0, 0, 0); PG8_LDB(B1, 0, 1); PG8_SCHED; PG8_LDA(At, 0, 0); PG8_STAGE(PG8_SA(1, 1), a1 + hstepA, voffA);
;             PG8_WAIT_V(8); PG8_WAIT_L(0); PG8_BAR; PG8_MMA(0, 0, At, B0); PG8_MMA(0, 1, At, B1); PG8_BAR; PG8_SCHED;
;             PG8_LDA(At, 0, 1); PG8_STAGE(PG8_SB(0, 0), b2, voffB); PG8_STAGE(PG8_SB(0, 1), b2 + hstepB, voffB); PG8_STAGE(PG8_SA(0, 0), a2, voffA);
.LBB0_2035:
	s_add_u32 s14, s24, 0xfff80080
	s_addc_u32 s15, s25, -1
	s_add_i32 s41, 0, 0x10000
	s_cmp_eq_u32 s52, 28
	s_cselect_b32 s27, s1, s15
	s_cselect_b32 s26, s3, s14
	s_cselect_b32 s15, s7, s40
	s_cselect_b32 s14, s13, s17
	s_add_i32 s53, 0, 0x14000
	v_add_u32_e32 v142, s41, v1
	v_add_u32_e32 v158, s53, v1
	ds_read_b128 v[130:133], v142
	ds_read_b128 v[134:137], v142 offset:1024
	ds_read_b128 v[138:141], v142 offset:2048
	ds_read_b128 v[142:145], v142 offset:3072
	ds_read_b128 v[146:149], v158
	ds_read_b128 v[150:153], v158 offset:1024
	ds_read_b128 v[154:157], v158 offset:2048
	ds_read_b128 v[158:161], v158 offset:3072
	v_lshl_add_u64 v[178:179], s[24:25], 0, v[196:197]
	s_add_i32 m0, s23, 0xc000
	ds_read_b128 v[162:165], v181
	ds_read_b128 v[166:169], v181 offset:1024
	ds_read_b128 v[170:173], v181 offset:2048
	ds_read_b128 v[174:177], v181 offset:3072
	ds_read_b128 v[200:203], v181 offset:4096
	ds_read_b128 v[204:207], v181 offset:5120
	ds_read_b128 v[208:211], v181 offset:6144
	ds_read_b128 v[212:215], v181 offset:7168
	global_load_lds_dwordx4 v[178:179], off
	v_lshl_add_u64 v[178:179], s[24:25], 0, v[198:199]
	s_add_i32 m0, s23, 0xe000
	s_nop 0
	global_load_lds_dwordx4 v[178:179], off
	s_waitcnt vmcnt(8)
	s_waitcnt lgkmcnt(0)
	s_barrier
	s_setprio 1
	s_waitcnt lgkmcnt(0)
	v_mfma_f32_16x16x32_bf16 v[126:129], v[130:133], v[162:165], v[126:129]
	v_mfma_f32_16x16x32_bf16 v[122:125], v[138:141], v[162:165], v[122:125]
	v_mfma_f32_16x16x32_bf16 v[110:113], v[130:133], v[170:173], v[110:113]
	v_mfma_f32_16x16x32_bf16 v[106:109], v[138:141], v[170:173], v[106:109]
	v_mfma_f32_16x16x32_bf16 v[94:97], v[130:133], v[200:203], v[94:97]
	v_mfma_f32_16x16x32_bf16 v[90:93], v[138:141], v[200:203], v[90:93]
	v_mfma_f32_16x16x32_bf16 v[82:85], v[130:133], v[208:211], v[82:85]
	v_mfma_f32_16x16x32_bf16 v[74:77], v[138:141], v[208:211], v[74:77]
	v_mfma_f32_16x16x32_bf16 v[126:129], v[134:137], v[166:169], v[126:129]
	v_mfma_f32_16x16x32_bf16 v[122:125], v[142:145], v[166:169], v[122:125]
	v_mfma_f32_16x16x32_bf16 v[110:113], v[134:137], v[174:177], v[110:113]
	v_mfma_f32_16x16x32_bf16 v[106:109], v[142:145], v[174:177], v[106:109]
	v_mfma_f32_16x16x32_bf16 v[94:97], v[134:137], v[204:207], v[94:97]
	v_mfma_f32_16x16x32_bf16 v[90:93], v[142:145], v[204:207], v[90:93]
	v_mfma_f32_16x16x32_bf16 v[82:85], v[134:137], v[212:215], v[82:85]
	v_mfma_f32_16x16x32_bf16 v[74:77], v[142:145], v[212:215], v[74:77]
	s_setprio 0
	s_setprio 1
	v_mfma_f32_16x16x32_bf16 v[118:121], v[146:149], v[162:165], v[118:121]
	v_mfma_f32_16x16x32_bf16 v[114:117], v[154:157], v[162:165], v[114:117]
	v_mfma_f32_16x16x32_bf16 v[102:105], v[146:149], v[170:173], v[102:105]
	v_mfma_f32_16x16x32_bf16 v[98:101], v[154:157], v[170:173], v[98:101]
	v_mfma_f32_16x16x32_bf16 v[86:89], v[146:149], v[200:203], v[86:89]
	v_mfma_f32_16x16x32_bf16 v[78:81], v[154:157], v[200:203], v[78:81]
	v_mfma_f32_16x16x32_bf16 v[70:73], v[146:149], v[208:211], v[70:73]
	v_mfma_f32_16x16x32_bf16 v[66:69], v[154:157], v[208:211], v[66:69]
	v_mfma_f32_16x16x32_bf16 v[118:121], v[150:153], v[166:169], v[118:121]
	v_mfma_f32_16x16x32_bf16 v[114:117], v[158:161], v[166:169], v[114:117]
	v_mfma_f32_16x16x32_bf16 v[102:105], v[150:153], v[174:177], v[102:105]
	v_mfma_f32_16x16x32_bf16 v[98:101], v[158:161], v[174:177], v[98:101]
	v_mfma_f32_16x16x32_bf16 v[86:89], v[150:153], v[204:207], v[86:89]
	v_mfma_f32_16x16x32_bf16 v[78:81], v[158:161], v[204:207], v[78:81]
	v_mfma_f32_16x16x32_bf16 v[70:73], v[150:153], v[212:215], v[70:73]
	v_mfma_f32_16x16x32_bf16 v[66:69], v[158:161], v[212:215], v[66:69]
	s_setprio 0
	s_barrier
	s_add_i32 s41, s41, s30
	v_lshl_add_u64 v[178:179], s[14:15], 0, v[190:191]
	s_mov_b32 m0, s41
	ds_read_b128 v[162:165], v181 offset:16384
	ds_read_b128 v[166:169], v181 offset:17408
	ds_read_b128 v[170:173], v181 offset:18432
	ds_read_b128 v[174:177], v181 offset:19456
	ds_read_b128 v[200:203], v181 offset:20480
	ds_read_b128 v[204:207], v181 offset:21504
	ds_read_b128 v[208:211], v181 offset:22528
	ds_read_b128 v[212:215], v181 offset:23552
	global_load_lds_dwordx4 v[178:179], off nt
	s_add_i32 m0, s41, 0x2000
	s_add_u32 s62, s14, 0x80000
	v_lshl_add_u64 v[184:185], s[14:15], 0, v[194:195]
	s_addc_u32 s63, s15, 0
	s_add_i32 s41, s53, s30
	global_load_lds_dwordx4 v[184:185], off nt
	v_lshl_add_u64 v[216:217], s[62:63], 0, v[190:191]
	s_mov_b32 m0, s41
	v_lshl_add_u64 v[218:219], s[26:27], 0, v[192:193]
	global_load_lds_dwordx4 v[216:217], off nt
	v_lshl_add_u64 v[216:217], s[62:63], 0, v[194:195]
	s_add_i32 m0, s41, 0x2000
	s_nop 0
	global_load_lds_dwordx4 v[216:217], off nt
	v_lshl_add_u64 v[216:217], s[26:27], 0, v[188:189]
	s_mov_b32 m0, s23
	s_nop 0
	global_load_lds_dwordx4 v[216:217], off
	s_mov_b32 m0, s34
	s_nop 0
	global_load_lds_dwordx4 v[218:219], off
	s_waitcnt vmcnt(8)
	s_waitcnt lgkmcnt(0)
	s_barrier
; #define PG8_STAGE(bufoff, gbase, voff) do { _Pragma("unroll") for (int _i = 0; _i < 2; ++_i) \
;         __builtin_amdgcn_global_load_lds((const unsigned*)((const char*)(gbase) + (voff)[_i]), (LAS unsigned*)(lds + (bufoff) + ldsw + _i * 8192), 16, 0, 0); } while (0)
; #define PG8_LDA(dst, b, h) do { _Pragma("unroll") for (int m = 0; m < 4; ++m) _Pragma("unroll") for (int k = 0; k < 2; ++k) dst[m][k] = *(const LAS bf16x8*)(lds + PG8_SA(b, h) + aoff + m * 2048 + k * 1024); } while (0)
; #define PG8_LDB(dst, b, h) do { _Pragma("unroll") for (int n = 0; n < 2; ++n) _Pragma("unroll") for (int k = 0; k < 2; ++k) dst[n][k] = *(const LAS bf16x8*)(lds + PG8_SB(b, h) + boff + n * 2048 + k * 1024); } while (0)
; #define PG8_MMA(ai, bj, At, Bt) do { __builtin_amdgcn_s_setprio(1); _Pragma("unroll") for (int m = 0; m < 4; ++m) _Pragma("unroll") for (int n = 0; n < 2; ++n) _Pragma("unroll") for (int k = 0; k < 2; ++k) \
;         acc[ai][bj][m][n] = __builtin_amdgcn_mfma_f32_16x16x32_bf16(Bt[n][k], At[m][k], acc[ai][bj][m][n], 0, 0, 0); __builtin_amdgcn_s_setprio(0); } while (0)
; #define PG8_WAIT_V(n) asm volatile("s_waitcnt vmcnt(" #n ")" ::: "memory")
; #define PG8_WAIT_L(n) asm volatile("s_waitcnt lgkmcnt(" #n ")" ::: "memory")
; #define PG8_BAR __builtin_amdgcn_s_barrier()
; #define PG8_SCHED __builtin_amdgcn_sched_barrier(0)
; template <class Epi>
; __device__ __forceinline__ void gemm_phase(LAS unsigned char* lds, const Gemm g, const StaticOrder& S, const Epi& E) {
;     ...
;             PG8_WAIT_V(8); PG8_WAIT_L(0); PG8_BAR; PG8_MMA(1, 0, At, B0); PG8_MMA(1, 1, At, B1); PG8_BAR; PG8_SCHED;
;             PG8_LDB(B0, 1, 0); PG8_LDB(B1, 1, 1); PG8_SCHED; PG8_LDA(At, 1, 0); PG8_STAGE(PG8_SA(0, 1), a2 + hstepA, voffA);
;             PG8_WAIT_V(8); PG8_WAIT_L(0); PG8_BAR; PG8_MMA(0, 0, At, B0); PG8_MMA(0, 1, At, B1); PG8_BAR; PG8_SCHED;
	s_setprio 1
	s_waitcnt lgkmcnt(0)
	v_mfma_f32_16x16x32_bf16 v[62:65], v[130:133], v[162:165], v[62:65]
	v_mfma_f32_16x16x32_bf16 v[58:61], v[138:141], v[162:165], v[58:61]
	v_mfma_f32_16x16x32_bf16 v[50:53], v[130:133], v[170:173], v[50:53]
	v_mfma_f32_16x16x32_bf16 v[42:45], v[138:141], v[170:173], v[42:45]
	v_mfma_f32_16x16x32_bf16 v[30:33], v[130:133], v[200:203], v[30:33]
	v_mfma_f32_16x16x32_bf16 v[26:29], v[138:141], v[200:203], v[26:29]
	v_mfma_f32_16x16x32_bf16 v[18:21], v[130:133], v[208:211], v[18:21]
	v_mfma_f32_16x16x32_bf16 v[10:13], v[138:141], v[208:211], v[10:13]
	v_mfma_f32_16x16x32_bf16 v[62:65], v[134:137], v[166:169], v[62:65]
	v_mfma_f32_16x16x32_bf16 v[58:61], v[142:145], v[166:169], v[58:61]
	v_mfma_f32_16x16x32_bf16 v[50:53], v[134:137], v[174:177], v[50:53]
	v_mfma_f32_16x16x32_bf16 v[42:45], v[142:145], v[174:177], v[42:45]
	v_mfma_f32_16x16x32_bf16 v[30:33], v[134:137], v[204:207], v[30:33]
	v_mfma_f32_16x16x32_bf16 v[26:29], v[142:145], v[204:207], v[26:29]
	v_mfma_f32_16x16x32_bf16 v[18:21], v[134:137], v[212:215], v[18:21]
	v_mfma_f32_16x16x32_bf16 v[10:13], v[142:145], v[212:215], v[10:13]
	s_setprio 0
	s_setprio 1
	v_mfma_f32_16x16x32_bf16 v[54:57], v[146:149], v[162:165], v[54:57]
	v_mfma_f32_16x16x32_bf16 v[46:49], v[154:157], v[162:165], v[46:49]
	v_mfma_f32_16x16x32_bf16 v[38:41], v[146:149], v[170:173], v[38:41]
	v_mfma_f32_16x16x32_bf16 v[34:37], v[154:157], v[170:173], v[34:37]
	v_mfma_f32_16x16x32_bf16 v[22:25], v[146:149], v[200:203], v[22:25]
	v_mfma_f32_16x16x32_bf16 v[14:17], v[154:157], v[200:203], v[14:17]
	v_mfma_f32_16x16x32_bf16 v[6:9], v[146:149], v[208:211], v[6:9]
	v_mfma_f32_16x16x32_bf16 v[2:5], v[154:157], v[208:211], v[2:5]
	v_mfma_f32_16x16x32_bf16 v[54:57], v[150:153], v[166:169], v[54:57]
	v_mfma_f32_16x16x32_bf16 v[46:49], v[158:161], v[166:169], v[46:49]
	v_mfma_f32_16x16x32_bf16 v[38:41], v[150:153], v[174:177], v[38:41]
	v_mfma_f32_16x16x32_bf16 v[34:37], v[158:161], v[174:177], v[34:37]
	v_mfma_f32_16x16x32_bf16 v[22:25], v[150:153], v[204:207], v[22:25]
	v_mfma_f32_16x16x32_bf16 v[14:17], v[158:161], v[204:207], v[14:17]
	v_mfma_f32_16x16x32_bf16 v[6:9], v[150:153], v[212:215], v[6:9]
	v_mfma_f32_16x16x32_bf16 v[2:5], v[158:161], v[212:215], v[2:5]
	s_setprio 0
	s_barrier
	s_add_i32 s41, 0, 0x18000
	s_add_i32 s53, 0, 0x1c000
	v_add_u32_e32 v142, s41, v1
	v_add_u32_e32 v158, s53, v1
	ds_read_b128 v[130:133], v142
	ds_read_b128 v[134:137], v142 offset:1024
	ds_read_b128 v[138:141], v142 offset:2048
	ds_read_b128 v[142:145], v142 offset:3072
	ds_read_b128 v[146:149], v158
	ds_read_b128 v[150:153], v158 offset:1024
	ds_read_b128 v[154:157], v158 offset:2048
	ds_read_b128 v[158:161], v158 offset:3072
	s_add_u32 s26, s26, 0x80000
	s_addc_u32 s27, s27, 0
	s_mov_b32 m0, s35
	v_lshl_add_u64 v[220:221], s[26:27], 0, v[188:189]
	ds_read_b128 v[162:165], v181 offset:32768
	ds_read_b128 v[166:169], v181 offset:33792
	ds_read_b128 v[170:173], v181 offset:34816
	ds_read_b128 v[174:177], v181 offset:35840
	ds_read_b128 v[200:203], v181 offset:36864
	ds_read_b128 v[204:207], v181 offset:37888
	ds_read_b128 v[208:211], v181 offset:38912
	ds_read_b128 v[212:215], v181 offset:39936
	global_load_lds_dwordx4 v[220:221], off
	v_lshl_add_u64 v[220:221], s[26:27], 0, v[192:193]
	s_mov_b32 m0, s42
	s_nop 0
	global_load_lds_dwordx4 v[220:221], off
	s_waitcnt vmcnt(8)
	s_waitcnt lgkmcnt(0)
	s_barrier
	s_setprio 1
	s_waitcnt lgkmcnt(0)
	v_mfma_f32_16x16x32_bf16 v[126:129], v[130:133], v[162:165], v[126:129]
	v_mfma_f32_16x16x32_bf16 v[122:125], v[138:141], v[162:165], v[122:125]
	v_mfma_f32_16x16x32_bf16 v[110:113], v[130:133], v[170:173], v[110:113]
	v_mfma_f32_16x16x32_bf16 v[106:109], v[138:141], v[170:173], v[106:109]
	v_mfma_f32_16x16x32_bf16 v[94:97], v[130:133], v[200:203], v[94:97]
	v_mfma_f32_16x16x32_bf16 v[90:93], v[138:141], v[200:203], v[90:93]
	v_mfma_f32_16x16x32_bf16 v[82:85], v[130:133], v[208:211], v[82:85]
	v_mfma_f32_16x16x32_bf16 v[74:77], v[138:141], v[208:211], v[74:77]
	v_mfma_f32_16x16x32_bf16 v[126:129], v[134:137], v[166:169], v[126:129]
	v_mfma_f32_16x16x32_bf16 v[122:125], v[142:145], v[166:169], v[122:125]
	v_mfma_f32_16x16x32_bf16 v[110:113], v[134:137], v[174:177], v[110:113]
	v_mfma_f32_16x16x32_bf16 v[106:109], v[142:145], v[174:177], v[106:109]
	v_mfma_f32_16x16x32_bf16 v[94:97], v[134:137], v[204:207], v[94:97]
	v_mfma_f32_16x16x32_bf16 v[90:93], v[142:145], v[204:207], v[90:93]
	v_mfma_f32_16x16x32_bf16 v[82:85], v[134:137], v[212:215], v[82:85]
	v_mfma_f32_16x16x32_bf16 v[74:77], v[142:145], v[212:215], v[74:77]
	s_setprio 0
	s_setprio 1
	v_mfma_f32_16x16x32_bf16 v[118:121], v[146:149], v[162:165], v[118:121]
	v_mfma_f32_16x16x32_bf16 v[114:117], v[154:157], v[162:165], v[114:117]
	v_mfma_f32_16x16x32_bf16 v[102:105], v[146:149], v[170:173], v[102:105]
	v_mfma_f32_16x16x32_bf16 v[98:101], v[154:157], v[170:173], v[98:101]
	v_mfma_f32_16x16x32_bf16 v[86:89], v[146:149], v[200:203], v[86:89]
	v_mfma_f32_16x16x32_bf16 v[78:81], v[154:157], v[200:203], v[78:81]
	v_mfma_f32_16x16x32_bf16 v[70:73], v[146:149], v[208:211], v[70:73]
	v_mfma_f32_16x16x32_bf16 v[66:69], v[154:157], v[208:211], v[66:69]
	v_mfma_f32_16x16x32_bf16 v[118:121], v[150:153], v[166:169], v[118:121]
	v_mfma_f32_16x16x32_bf16 v[114:117], v[158:161], v[166:169], v[114:117]
	v_mfma_f32_16x16x32_bf16 v[102:105], v[150:153], v[174:177], v[102:105]
	v_mfma_f32_16x16x32_bf16 v[98:101], v[158:161], v[174:177], v[98:101]
	v_mfma_f32_16x16x32_bf16 v[86:89], v[150:153], v[204:207], v[86:89]
	v_mfma_f32_16x16x32_bf16 v[78:81], v[158:161], v[204:207], v[78:81]
	v_mfma_f32_16x16x32_bf16 v[70:73], v[150:153], v[212:215], v[70:73]
	v_mfma_f32_16x16x32_bf16 v[66:69], v[158:161], v[212:215], v[66:69]
	s_setprio 0
	s_barrier
; #define PG8_STAGE(bufoff, gbase, voff) do { _Pragma("unroll") for (int _i = 0; _i < 2; ++_i) \
;         __builtin_amdgcn_global_load_lds((const unsigned*)((const char*)(gbase) + (voff)[_i]), (LAS unsigned*)(lds + (bufoff) + ldsw + _i * 8192), 16, 0, 0); } while (0)
; #define PG8_LDA(dst, b, h) do { _Pragma("unroll") for (int m = 0; m < 4; ++m) _Pragma("unroll") for (int k = 0; k < 2; ++k) dst[m][k] = *(const LAS bf16x8*)(lds + PG8_SA(b, h) + aoff + m * 2048 + k * 1024); } while (0)
; #define PG8_MMA(ai, bj, At, Bt) do { __builtin_amdgcn_s_setprio(1); _Pragma("unroll") for (int m = 0; m < 4; ++m) _Pragma("unroll") for (int n = 0; n < 2; ++n) _Pragma("unroll") for (int k = 0; k < 2; ++k) \
;         acc[ai][bj][m][n] = __builtin_amdgcn_mfma_f32_16x16x32_bf16(Bt[n][k], At[m][k], acc[ai][bj][m][n], 0, 0, 0); __builtin_amdgcn_s_setprio(0); } while (0)
; #define PG8_WAIT_V(n) asm volatile("s_waitcnt vmcnt(" #n ")" ::: "memory")
; #define PG8_WAIT_L(n) asm volatile("s_waitcnt lgkmcnt(" #n ")" ::: "memory")
; #define PG8_BAR __builtin_amdgcn_s_barrier()
; #define PG8_SCHED __builtin_amdgcn_sched_barrier(0)
; template <class Epi>
; __device__ __forceinline__ void gemm_phase(LAS unsigned char* lds, const Gemm g, const StaticOrder& S, const Epi& E) {
;     ...
;             PG8_LDA(At, 1, 1); PG8_STAGE(PG8_SB(1, 0), b3, voffB); PG8_STAGE(PG8_SB(1, 1), b3 + hstepB, voffB); PG8_STAGE(PG8_SA(1, 0), a3, voffA);
;             PG8_WAIT_V(8); PG8_WAIT_L(0); PG8_BAR; PG8_MMA(1, 0, At, B0); PG8_MMA(1, 1, At, B1); PG8_BAR; PG8_SCHED;
;         }
;         if (wr == 0) PG8_BAR;
	s_add_i32 s26, s41, s30
	v_lshl_add_u64 v[178:179], v[178:179], 0, s[84:85]
	s_mov_b32 m0, s26
	ds_read_b128 v[162:165], v181 offset:49152
	ds_read_b128 v[166:169], v181 offset:50176
	ds_read_b128 v[170:173], v181 offset:51200
	ds_read_b128 v[174:177], v181 offset:52224
	ds_read_b128 v[200:203], v181 offset:53248
	ds_read_b128 v[204:207], v181 offset:54272
	ds_read_b128 v[208:211], v181 offset:55296
	ds_read_b128 v[212:215], v181 offset:56320
	global_load_lds_dwordx4 v[178:179], off nt
	s_add_i32 m0, s26, 0x2000
	s_add_u32 s14, s14, 0x80080
	v_lshl_add_u64 v[178:179], v[184:185], 0, s[84:85]
	s_addc_u32 s15, s15, 0
	s_add_i32 s26, s53, s30
	global_load_lds_dwordx4 v[178:179], off nt
	v_lshl_add_u64 v[178:179], s[14:15], 0, v[190:191]
	s_mov_b32 m0, s26
	s_nop 0
	global_load_lds_dwordx4 v[178:179], off nt
	v_lshl_add_u64 v[178:179], s[14:15], 0, v[194:195]
	s_add_i32 m0, s26, 0x2000
	s_nop 0
	global_load_lds_dwordx4 v[178:179], off nt
	v_lshl_add_u64 v[178:179], v[216:217], 0, s[84:85]
	s_mov_b32 m0, s68
	s_nop 0
	global_load_lds_dwordx4 v[178:179], off
	v_lshl_add_u64 v[178:179], v[218:219], 0, s[84:85]
	s_mov_b32 m0, s69
	s_nop 0
	global_load_lds_dwordx4 v[178:179], off
	s_waitcnt vmcnt(8)
	s_waitcnt lgkmcnt(0)
	s_barrier
	s_setprio 1
	s_waitcnt lgkmcnt(0)
	v_mfma_f32_16x16x32_bf16 v[62:65], v[130:133], v[162:165], v[62:65]
	v_mfma_f32_16x16x32_bf16 v[58:61], v[138:141], v[162:165], v[58:61]
	v_mfma_f32_16x16x32_bf16 v[50:53], v[130:133], v[170:173], v[50:53]
	v_mfma_f32_16x16x32_bf16 v[42:45], v[138:141], v[170:173], v[42:45]
	v_mfma_f32_16x16x32_bf16 v[30:33], v[130:133], v[200:203], v[30:33]
	v_mfma_f32_16x16x32_bf16 v[26:29], v[138:141], v[200:203], v[26:29]
	v_mfma_f32_16x16x32_bf16 v[18:21], v[130:133], v[208:211], v[18:21]
	v_mfma_f32_16x16x32_bf16 v[10:13], v[138:141], v[208:211], v[10:13]
	v_mfma_f32_16x16x32_bf16 v[62:65], v[134:137], v[166:169], v[62:65]
	v_mfma_f32_16x16x32_bf16 v[58:61], v[142:145], v[166:169], v[58:61]
	v_mfma_f32_16x16x32_bf16 v[50:53], v[134:137], v[174:177], v[50:53]
	v_mfma_f32_16x16x32_bf16 v[42:45], v[142:145], v[174:177], v[42:45]
	v_mfma_f32_16x16x32_bf16 v[30:33], v[134:137], v[204:207], v[30:33]
	v_mfma_f32_16x16x32_bf16 v[26:29], v[142:145], v[204:207], v[26:29]
	v_mfma_f32_16x16x32_bf16 v[18:21], v[134:137], v[212:215], v[18:21]
	v_mfma_f32_16x16x32_bf16 v[10:13], v[142:145], v[212:215], v[10:13]
	s_setprio 0
	s_setprio 1
	v_mfma_f32_16x16x32_bf16 v[54:57], v[146:149], v[162:165], v[54:57]
	v_mfma_f32_16x16x32_bf16 v[46:49], v[154:157], v[162:165], v[46:49]
	v_mfma_f32_16x16x32_bf16 v[38:41], v[146:149], v[170:173], v[38:41]
	v_mfma_f32_16x16x32_bf16 v[34:37], v[154:157], v[170:173], v[34:37]
	v_mfma_f32_16x16x32_bf16 v[22:25], v[146:149], v[200:203], v[22:25]
	v_mfma_f32_16x16x32_bf16 v[14:17], v[154:157], v[200:203], v[14:17]
	v_mfma_f32_16x16x32_bf16 v[6:9], v[146:149], v[208:211], v[6:9]
	v_mfma_f32_16x16x32_bf16 v[2:5], v[154:157], v[208:211], v[2:5]
	v_mfma_f32_16x16x32_bf16 v[54:57], v[150:153], v[166:169], v[54:57]
	v_mfma_f32_16x16x32_bf16 v[46:49], v[158:161], v[166:169], v[46:49]
	v_mfma_f32_16x16x32_bf16 v[38:41], v[150:153], v[174:177], v[38:41]
	v_mfma_f32_16x16x32_bf16 v[34:37], v[158:161], v[174:177], v[34:37]
	v_mfma_f32_16x16x32_bf16 v[22:25], v[150:153], v[204:207], v[22:25]
	v_mfma_f32_16x16x32_bf16 v[14:17], v[158:161], v[204:207], v[14:17]
	v_mfma_f32_16x16x32_bf16 v[6:9], v[150:153], v[212:215], v[6:9]
	v_mfma_f32_16x16x32_bf16 v[2:5], v[158:161], v[212:215], v[2:5]
	s_setprio 0
	s_barrier
	s_add_i32 s52, s52, 2
	s_add_u32 s24, s24, 0x100
	s_addc_u32 s25, s25, 0
	s_add_u32 s17, s17, 0x100
	s_addc_u32 s40, s40, 0
	s_cmp_gt_u32 s52, 29
	s_cbranch_scc0 .LBB0_2035
	s_and_b64 vcc, exec, s[10:11]
	s_cbranch_vccz .LBB0_2038
	s_barrier

; #define PG8_STAGE(bufoff, gbase, voff) do { _Pragma("unroll") for (int _i = 0; _i < 2; ++_i) \
;         __builtin_amdgcn_global_load_lds((const unsigned*)((const char*)(gbase) + (voff)[_i]), (LAS unsigned*)(lds + (bufoff) + ldsw + _i * 8192), 16, 0, 0); } while (0)
; #define PG8_LDA(dst, b, h) do { _Pragma("unroll") for (int m = 0; m < 4; ++m) _Pragma("unroll") for (int k = 0; k < 2; ++k) dst[m][k] = *(const LAS bf16x8*)(lds + PG8_SA(b, h) + aoff + m * 2048 + k * 1024); } while (0)
; #define PG8_LDB(dst, b, h) do { _Pragma("unroll") for (int n = 0; n < 2; ++n) _Pragma("unroll") for (int k = 0; k < 2; ++k) dst[n][k] = *(const LAS bf16x8*)(lds + PG8_SB(b, h) + boff + n * 2048 + k * 1024); } while (0)
; #define PG8_MMA(ai, bj, At, Bt) do { __builtin_amdgcn_s_setprio(1); _Pragma("unroll") for (int m = 0; m < 4; ++m) _Pragma("unroll") for (int n = 0; n < 2; ++n) _Pragma("unroll") for (int k = 0; k < 2; ++k) \
;         acc[ai][bj][m][n] = __builtin_amdgcn_mfma_f32_16x16x32_bf16(Bt[n][k], At[m][k], acc[ai][bj][m][n], 0, 0, 0); __builtin_amdgcn_s_setprio(0); } while (0)
; #define PG8_WAIT_V(n) asm volatile("s_waitcnt vmcnt(" #n ")" ::: "memory")
; #define PG8_WAIT_L(n) asm volatile("s_waitcnt lgkmcnt(" #n ")" ::: "memory")
; #define PG8_BAR __builtin_amdgcn_s_barrier()
; #define PG8_SCHED __builtin_amdgcn_sched_barrier(0)
; template <class Epi>
; __device__ __forceinline__ void gemm_phase(LAS unsigned char* lds, const Gemm g, const StaticOrder& S, const Epi& E) {
;     ...
;             const bool last = (t == nt - 2);
;             const char* a1 = cA + (size_t)(t + 1) * kstep;
;             const char* a2 = last ? nA : cA + (size_t)(t + 2) * kstep; const char* b2 = last ? nB : cB + (size_t)(t + 2) * kstep;
;             const char* a3 = a2 + kstep; const char* b3 = b2 + kstep;
;             PG8_LDB(B0, 0, 0); PG8_LDB(B1, 0, 1); PG8_SCHED; PG8_LDA(At, 0, 0); PG8_STAGE(PG8_SA(1, 1), a1 + hstepA, voffA);
;             PG8_WAIT_V(8); PG8_WAIT_L(0); PG8_BAR; PG8_MMA(0, 0, At, B0); PG8_MMA(0, 1, At, B1); PG8_BAR; PG8_SCHED;
;             PG8_LDA(At, 0, 1); PG8_STAGE(PG8_SB(0, 0), b2, voffB); PG8_STAGE(PG8_SB(0, 1), b2 + hstepB, voffB); PG8_STAGE(PG8_SA(0, 0), a2, voffA);
.LBB0_2130:
	s_add_u32 s14, s20, 0xfff80080
	s_addc_u32 s15, s21, -1
	s_add_i32 s62, 0, 0x10000
	s_cmp_eq_u32 s41, 28
	s_cselect_b32 s23, s3, s15
	s_cselect_b32 s22, s11, s14
	v_add_u32_e32 v142, s62, v1
	s_cselect_b32 s15, s9, s53
	s_cselect_b32 s14, s40, s52
	s_add_i32 s64, 0, 0x14000
	ds_read_b128 v[146:149], v142
	ds_read_b128 v[150:153], v142 offset:1024
	ds_read_b128 v[154:157], v142 offset:2048
	ds_read_b128 v[158:161], v142 offset:3072
	v_add_u32_e32 v142, s64, v1
	ds_read_b128 v[162:165], v142
	ds_read_b128 v[166:169], v142 offset:1024
	ds_read_b128 v[170:173], v142 offset:2048
	ds_read_b128 v[174:177], v142 offset:3072
	v_lshl_add_u64 v[142:143], s[20:21], 0, v[138:139]
	s_add_i32 m0, s19, 0xc000
	ds_read_b128 v[188:191], v144
	ds_read_b128 v[192:195], v144 offset:1024
	ds_read_b128 v[196:199], v144 offset:2048
	ds_read_b128 v[200:203], v144 offset:3072
	ds_read_b128 v[204:207], v144 offset:4096
	ds_read_b128 v[208:211], v144 offset:5120
	ds_read_b128 v[212:215], v144 offset:6144
	ds_read_b128 v[216:219], v144 offset:7168
	global_load_lds_dwordx4 v[142:143], off
	v_lshl_add_u64 v[142:143], s[20:21], 0, v[140:141]
	s_add_i32 m0, s19, 0xe000
	s_nop 0
	global_load_lds_dwordx4 v[142:143], off
	s_waitcnt vmcnt(8)
	s_waitcnt lgkmcnt(0)
	s_barrier
	s_setprio 1
	s_waitcnt lgkmcnt(0)
	v_mfma_f32_16x16x32_bf16 v[126:129], v[146:149], v[188:191], v[126:129]
	v_mfma_f32_16x16x32_bf16 v[122:125], v[154:157], v[188:191], v[122:125]
	v_mfma_f32_16x16x32_bf16 v[110:113], v[146:149], v[196:199], v[110:113]
	v_mfma_f32_16x16x32_bf16 v[106:109], v[154:157], v[196:199], v[106:109]
	v_mfma_f32_16x16x32_bf16 v[94:97], v[146:149], v[204:207], v[94:97]
	v_mfma_f32_16x16x32_bf16 v[90:93], v[154:157], v[204:207], v[90:93]
	v_mfma_f32_16x16x32_bf16 v[78:81], v[146:149], v[212:215], v[78:81]
	v_mfma_f32_16x16x32_bf16 v[74:77], v[154:157], v[212:215], v[74:77]
	v_mfma_f32_16x16x32_bf16 v[126:129], v[150:153], v[192:195], v[126:129]
	v_mfma_f32_16x16x32_bf16 v[122:125], v[158:161], v[192:195], v[122:125]
	v_mfma_f32_16x16x32_bf16 v[110:113], v[150:153], v[200:203], v[110:113]
	v_mfma_f32_16x16x32_bf16 v[106:109], v[158:161], v[200:203], v[106:109]
	v_mfma_f32_16x16x32_bf16 v[94:97], v[150:153], v[208:211], v[94:97]
	v_mfma_f32_16x16x32_bf16 v[90:93], v[158:161], v[208:211], v[90:93]
	v_mfma_f32_16x16x32_bf16 v[78:81], v[150:153], v[216:219], v[78:81]
	v_mfma_f32_16x16x32_bf16 v[74:77], v[158:161], v[216:219], v[74:77]
	s_setprio 0
	s_setprio 1
	v_mfma_f32_16x16x32_bf16 v[118:121], v[162:165], v[188:191], v[118:121]
	v_mfma_f32_16x16x32_bf16 v[114:117], v[170:173], v[188:191], v[114:117]
	v_mfma_f32_16x16x32_bf16 v[102:105], v[162:165], v[196:199], v[102:105]
	v_mfma_f32_16x16x32_bf16 v[98:101], v[170:173], v[196:199], v[98:101]
	v_mfma_f32_16x16x32_bf16 v[86:89], v[162:165], v[204:207], v[86:89]
	v_mfma_f32_16x16x32_bf16 v[82:85], v[170:173], v[204:207], v[82:85]
	v_mfma_f32_16x16x32_bf16 v[70:73], v[162:165], v[212:215], v[70:73]
	v_mfma_f32_16x16x32_bf16 v[66:69], v[170:173], v[212:215], v[66:69]
	v_mfma_f32_16x16x32_bf16 v[118:121], v[166:169], v[192:195], v[118:121]
	v_mfma_f32_16x16x32_bf16 v[114:117], v[174:177], v[192:195], v[114:117]
	v_mfma_f32_16x16x32_bf16 v[102:105], v[166:169], v[200:203], v[102:105]
	v_mfma_f32_16x16x32_bf16 v[98:101], v[174:177], v[200:203], v[98:101]
	v_mfma_f32_16x16x32_bf16 v[86:89], v[166:169], v[208:211], v[86:89]
	v_mfma_f32_16x16x32_bf16 v[82:85], v[174:177], v[208:211], v[82:85]
	v_mfma_f32_16x16x32_bf16 v[70:73], v[166:169], v[216:219], v[70:73]
	v_mfma_f32_16x16x32_bf16 v[66:69], v[174:177], v[216:219], v[66:69]
	s_setprio 0
	s_barrier
	s_add_i32 s62, s62, s27
	v_lshl_add_u64 v[142:143], s[14:15], 0, v[132:133]
	s_mov_b32 m0, s62
	ds_read_b128 v[188:191], v144 offset:16384
	ds_read_b128 v[192:195], v144 offset:17408
	ds_read_b128 v[196:199], v144 offset:18432
	ds_read_b128 v[200:203], v144 offset:19456
	ds_read_b128 v[204:207], v144 offset:20480
	ds_read_b128 v[208:211], v144 offset:21504
	ds_read_b128 v[212:215], v144 offset:22528
	ds_read_b128 v[216:219], v144 offset:23552
	global_load_lds_dwordx4 v[142:143], off nt
	s_add_i32 m0, s62, 0x2000
	s_add_u32 s62, s14, 0x80000
	v_lshl_add_u64 v[178:179], s[14:15], 0, v[136:137]
	s_addc_u32 s63, s15, 0
	s_add_i32 s64, s64, s27
	global_load_lds_dwordx4 v[178:179], off nt
	v_lshl_add_u64 v[184:185], s[62:63], 0, v[132:133]
	s_mov_b32 m0, s64
	v_lshl_add_u64 v[220:221], s[22:23], 0, v[134:135]
	global_load_lds_dwordx4 v[184:185], off nt
	v_lshl_add_u64 v[184:185], s[62:63], 0, v[136:137]
	s_add_i32 m0, s64, 0x2000
	s_nop 0
	global_load_lds_dwordx4 v[184:185], off nt
	v_lshl_add_u64 v[184:185], s[22:23], 0, v[130:131]
	s_mov_b32 m0, s19
	s_nop 0
	global_load_lds_dwordx4 v[184:185], off
	s_mov_b32 m0, s28
	s_nop 0
	global_load_lds_dwordx4 v[220:221], off
	s_waitcnt vmcnt(8)
	s_waitcnt lgkmcnt(0)
	s_barrier
; #define PG8_STAGE(bufoff, gbase, voff) do { _Pragma("unroll") for (int _i = 0; _i < 2; ++_i) \
;         __builtin_amdgcn_global_load_lds((const unsigned*)((const char*)(gbase) + (voff)[_i]), (LAS unsigned*)(lds + (bufoff) + ldsw + _i * 8192), 16, 0, 0); } while (0)
; #define PG8_LDA(dst, b, h) do { _Pragma("unroll") for (int m = 0; m < 4; ++m) _Pragma("unroll") for (int k = 0; k < 2; ++k) dst[m][k] = *(const LAS bf16x8*)(lds + PG8_SA(b, h) + aoff + m * 2048 + k * 1024); } while (0)
; #define PG8_LDB(dst, b, h) do { _Pragma("unroll") for (int n = 0; n < 2; ++n) _Pragma("unroll") for (int k = 0; k < 2; ++k) dst[n][k] = *(const LAS bf16x8*)(lds + PG8_SB(b, h) + boff + n * 2048 + k * 1024); } while (0)
; #define PG8_MMA(ai, bj, At, Bt) do { __builtin_amdgcn_s_setprio(1); _Pragma("unroll") for (int m = 0; m < 4; ++m) _Pragma("unroll") for (int n = 0; n < 2; ++n) _Pragma("unroll") for (int k = 0; k < 2; ++k) \
;         acc[ai][bj][m][n] = __builtin_amdgcn_mfma_f32_16x16x32_bf16(Bt[n][k], At[m][k], acc[ai][bj][m][n], 0, 0, 0); __builtin_amdgcn_s_setprio(0); } while (0)
; #define PG8_WAIT_V(n) asm volatile("s_waitcnt vmcnt(" #n ")" ::: "memory")
; #define PG8_WAIT_L(n) asm volatile("s_waitcnt lgkmcnt(" #n ")" ::: "memory")
; #define PG8_BAR __builtin_amdgcn_s_barrier()
; #define PG8_SCHED __builtin_amdgcn_sched_barrier(0)
; template <class Epi>
; __device__ __forceinline__ void gemm_phase(LAS unsigned char* lds, const Gemm g, const StaticOrder& S, const Epi& E) {
;     ...
;             PG8_WAIT_V(8); PG8_WAIT_L(0); PG8_BAR; PG8_MMA(1, 0, At, B0); PG8_MMA(1, 1, At, B1); PG8_BAR; PG8_SCHED;
;             PG8_LDB(B0, 1, 0); PG8_LDB(B1, 1, 1); PG8_SCHED; PG8_LDA(At, 1, 0); PG8_STAGE(PG8_SA(0, 1), a2 + hstepA, voffA);
;             PG8_WAIT_V(8); PG8_WAIT_L(0); PG8_BAR; PG8_MMA(0, 0, At, B0); PG8_MMA(0, 1, At, B1); PG8_BAR; PG8_SCHED;
	s_setprio 1
	s_waitcnt lgkmcnt(0)
	v_mfma_f32_16x16x32_bf16 v[62:65], v[146:149], v[188:191], v[62:65]
	v_mfma_f32_16x16x32_bf16 v[58:61], v[154:157], v[188:191], v[58:61]
	v_mfma_f32_16x16x32_bf16 v[46:49], v[146:149], v[196:199], v[46:49]
	v_mfma_f32_16x16x32_bf16 v[42:45], v[154:157], v[196:199], v[42:45]
	v_mfma_f32_16x16x32_bf16 v[30:33], v[146:149], v[204:207], v[30:33]
	v_mfma_f32_16x16x32_bf16 v[26:29], v[154:157], v[204:207], v[26:29]
	v_mfma_f32_16x16x32_bf16 v[14:17], v[146:149], v[212:215], v[14:17]
	v_mfma_f32_16x16x32_bf16 v[10:13], v[154:157], v[212:215], v[10:13]
	v_mfma_f32_16x16x32_bf16 v[62:65], v[150:153], v[192:195], v[62:65]
	v_mfma_f32_16x16x32_bf16 v[58:61], v[158:161], v[192:195], v[58:61]
	v_mfma_f32_16x16x32_bf16 v[46:49], v[150:153], v[200:203], v[46:49]
	v_mfma_f32_16x16x32_bf16 v[42:45], v[158:161], v[200:203], v[42:45]
	v_mfma_f32_16x16x32_bf16 v[30:33], v[150:153], v[208:211], v[30:33]
	v_mfma_f32_16x16x32_bf16 v[26:29], v[158:161], v[208:211], v[26:29]
	v_mfma_f32_16x16x32_bf16 v[14:17], v[150:153], v[216:219], v[14:17]
	v_mfma_f32_16x16x32_bf16 v[10:13], v[158:161], v[216:219], v[10:13]
	s_setprio 0
	s_setprio 1
	v_mfma_f32_16x16x32_bf16 v[54:57], v[162:165], v[188:191], v[54:57]
	v_mfma_f32_16x16x32_bf16 v[50:53], v[170:173], v[188:191], v[50:53]
	v_mfma_f32_16x16x32_bf16 v[38:41], v[162:165], v[196:199], v[38:41]
	v_mfma_f32_16x16x32_bf16 v[34:37], v[170:173], v[196:199], v[34:37]
	v_mfma_f32_16x16x32_bf16 v[22:25], v[162:165], v[204:207], v[22:25]
	v_mfma_f32_16x16x32_bf16 v[18:21], v[170:173], v[204:207], v[18:21]
	v_mfma_f32_16x16x32_bf16 v[6:9], v[162:165], v[212:215], v[6:9]
	v_mfma_f32_16x16x32_bf16 v[2:5], v[170:173], v[212:215], v[2:5]
	v_mfma_f32_16x16x32_bf16 v[54:57], v[166:169], v[192:195], v[54:57]
	v_mfma_f32_16x16x32_bf16 v[50:53], v[174:177], v[192:195], v[50:53]
	v_mfma_f32_16x16x32_bf16 v[38:41], v[166:169], v[200:203], v[38:41]
	v_mfma_f32_16x16x32_bf16 v[34:37], v[174:177], v[200:203], v[34:37]
	v_mfma_f32_16x16x32_bf16 v[22:25], v[166:169], v[208:211], v[22:25]
	v_mfma_f32_16x16x32_bf16 v[18:21], v[174:177], v[208:211], v[18:21]
	v_mfma_f32_16x16x32_bf16 v[6:9], v[166:169], v[216:219], v[6:9]
	v_mfma_f32_16x16x32_bf16 v[2:5], v[174:177], v[216:219], v[2:5]
	s_setprio 0
	s_barrier
	s_add_i32 s62, 0, 0x18000
	v_add_u32_e32 v145, s62, v1
	s_add_i32 s63, 0, 0x1c000
	ds_read_b128 v[146:149], v145
	ds_read_b128 v[150:153], v145 offset:1024
	ds_read_b128 v[154:157], v145 offset:2048
	ds_read_b128 v[158:161], v145 offset:3072
	v_add_u32_e32 v145, s63, v1
	ds_read_b128 v[162:165], v145
	ds_read_b128 v[166:169], v145 offset:1024
	ds_read_b128 v[170:173], v145 offset:2048
	ds_read_b128 v[174:177], v145 offset:3072
	s_add_u32 s22, s22, 0x80000
	s_addc_u32 s23, s23, 0
	s_mov_b32 m0, s29
	v_lshl_add_u64 v[222:223], s[22:23], 0, v[130:131]
	ds_read_b128 v[188:191], v144 offset:32768
	ds_read_b128 v[192:195], v144 offset:33792
	ds_read_b128 v[196:199], v144 offset:34816
	ds_read_b128 v[200:203], v144 offset:35840
	ds_read_b128 v[204:207], v144 offset:36864
	ds_read_b128 v[208:211], v144 offset:37888
	ds_read_b128 v[212:215], v144 offset:38912
	ds_read_b128 v[216:219], v144 offset:39936
	global_load_lds_dwordx4 v[222:223], off
	v_lshl_add_u64 v[222:223], s[22:23], 0, v[134:135]
	s_mov_b32 m0, s30
	s_nop 0
	global_load_lds_dwordx4 v[222:223], off
	s_waitcnt vmcnt(8)
	s_waitcnt lgkmcnt(0)
	s_barrier
	s_setprio 1
	s_waitcnt lgkmcnt(0)
	v_mfma_f32_16x16x32_bf16 v[126:129], v[146:149], v[188:191], v[126:129]
	v_mfma_f32_16x16x32_bf16 v[122:125], v[154:157], v[188:191], v[122:125]
	v_mfma_f32_16x16x32_bf16 v[110:113], v[146:149], v[196:199], v[110:113]
	v_mfma_f32_16x16x32_bf16 v[106:109], v[154:157], v[196:199], v[106:109]
	v_mfma_f32_16x16x32_bf16 v[94:97], v[146:149], v[204:207], v[94:97]
	v_mfma_f32_16x16x32_bf16 v[90:93], v[154:157], v[204:207], v[90:93]
	v_mfma_f32_16x16x32_bf16 v[78:81], v[146:149], v[212:215], v[78:81]
	v_mfma_f32_16x16x32_bf16 v[74:77], v[154:157], v[212:215], v[74:77]
	v_mfma_f32_16x16x32_bf16 v[126:129], v[150:153], v[192:195], v[126:129]
	v_mfma_f32_16x16x32_bf16 v[122:125], v[158:161], v[192:195], v[122:125]
	v_mfma_f32_16x16x32_bf16 v[110:113], v[150:153], v[200:203], v[110:113]
	v_mfma_f32_16x16x32_bf16 v[106:109], v[158:161], v[200:203], v[106:109]
	v_mfma_f32_16x16x32_bf16 v[94:97], v[150:153], v[208:211], v[94:97]
	v_mfma_f32_16x16x32_bf16 v[90:93], v[158:161], v[208:211], v[90:93]
	v_mfma_f32_16x16x32_bf16 v[78:81], v[150:153], v[216:219], v[78:81]
	v_mfma_f32_16x16x32_bf16 v[74:77], v[158:161], v[216:219], v[74:77]
	s_setprio 0
	s_setprio 1
	v_mfma_f32_16x16x32_bf16 v[118:121], v[162:165], v[188:191], v[118:121]
	v_mfma_f32_16x16x32_bf16 v[114:117], v[170:173], v[188:191], v[114:117]
	v_mfma_f32_16x16x32_bf16 v[102:105], v[162:165], v[196:199], v[102:105]
	v_mfma_f32_16x16x32_bf16 v[98:101], v[170:173], v[196:199], v[98:101]
	v_mfma_f32_16x16x32_bf16 v[86:89], v[162:165], v[204:207], v[86:89]
	v_mfma_f32_16x16x32_bf16 v[82:85], v[170:173], v[204:207], v[82:85]
	v_mfma_f32_16x16x32_bf16 v[70:73], v[162:165], v[212:215], v[70:73]
	v_mfma_f32_16x16x32_bf16 v[66:69], v[170:173], v[212:215], v[66:69]
	v_mfma_f32_16x16x32_bf16 v[118:121], v[166:169], v[192:195], v[118:121]
	v_mfma_f32_16x16x32_bf16 v[114:117], v[174:177], v[192:195], v[114:117]
	v_mfma_f32_16x16x32_bf16 v[102:105], v[166:169], v[200:203], v[102:105]
	v_mfma_f32_16x16x32_bf16 v[98:101], v[174:177], v[200:203], v[98:101]
	v_mfma_f32_16x16x32_bf16 v[86:89], v[166:169], v[208:211], v[86:89]
	v_mfma_f32_16x16x32_bf16 v[82:85], v[174:177], v[208:211], v[82:85]
	v_mfma_f32_16x16x32_bf16 v[70:73], v[166:169], v[216:219], v[70:73]
	v_mfma_f32_16x16x32_bf16 v[66:69], v[174:177], v[216:219], v[66:69]
	s_setprio 0
	s_barrier
; #define PG8_STAGE(bufoff, gbase, voff) do { _Pragma("unroll") for (int _i = 0; _i < 2; ++_i) \
;         __builtin_amdgcn_global_load_lds((const unsigned*)((const char*)(gbase) + (voff)[_i]), (LAS unsigned*)(lds + (bufoff) + ldsw + _i * 8192), 16, 0, 0); } while (0)
; #define PG8_LDA(dst, b, h) do { _Pragma("unroll") for (int m = 0; m < 4; ++m) _Pragma("unroll") for (int k = 0; k < 2; ++k) dst[m][k] = *(const LAS bf16x8*)(lds + PG8_SA(b, h) + aoff + m * 2048 + k * 1024); } while (0)
; #define PG8_MMA(ai, bj, At, Bt) do { __builtin_amdgcn_s_setprio(1); _Pragma("unroll") for (int m = 0; m < 4; ++m) _Pragma("unroll") for (int n = 0; n < 2; ++n) _Pragma("unroll") for (int k = 0; k < 2; ++k) \
;         acc[ai][bj][m][n] = __builtin_amdgcn_mfma_f32_16x16x32_bf16(Bt[n][k], At[m][k], acc[ai][bj][m][n], 0, 0, 0); __builtin_amdgcn_s_setprio(0); } while (0)
; #define PG8_WAIT_V(n) asm volatile("s_waitcnt vmcnt(" #n ")" ::: "memory")
; #define PG8_WAIT_L(n) asm volatile("s_waitcnt lgkmcnt(" #n ")" ::: "memory")
; #define PG8_BAR __builtin_amdgcn_s_barrier()
; #define PG8_SCHED __builtin_amdgcn_sched_barrier(0)
; template <class Epi>
; __device__ __forceinline__ void gemm_phase(LAS unsigned char* lds, const Gemm g, const StaticOrder& S, const Epi& E) {
;     ...
;             PG8_LDA(At, 1, 1); PG8_STAGE(PG8_SB(1, 0), b3, voffB); PG8_STAGE(PG8_SB(1, 1), b3 + hstepB, voffB); PG8_STAGE(PG8_SA(1, 0), a3, voffA);
;             PG8_WAIT_V(8); PG8_WAIT_L(0); PG8_BAR; PG8_MMA(1, 0, At, B0); PG8_MMA(1, 1, At, B1); PG8_BAR; PG8_SCHED;
;         }
;         if (wr == 0) PG8_BAR;
	s_add_i32 s22, s62, s27
	v_lshl_add_u64 v[142:143], v[142:143], 0, s[84:85]
	s_mov_b32 m0, s22
	ds_read_b128 v[188:191], v144 offset:49152
	ds_read_b128 v[192:195], v144 offset:50176
	ds_read_b128 v[196:199], v144 offset:51200
	ds_read_b128 v[200:203], v144 offset:52224
	ds_read_b128 v[204:207], v144 offset:53248
	ds_read_b128 v[208:211], v144 offset:54272
	ds_read_b128 v[212:215], v144 offset:55296
	ds_read_b128 v[216:219], v144 offset:56320
	global_load_lds_dwordx4 v[142:143], off nt
	s_add_i32 m0, s22, 0x2000
	s_add_u32 s14, s14, 0x80080
	v_lshl_add_u64 v[142:143], v[178:179], 0, s[84:85]
	s_addc_u32 s15, s15, 0
	s_add_i32 s22, s63, s27
	global_load_lds_dwordx4 v[142:143], off nt
	v_lshl_add_u64 v[142:143], s[14:15], 0, v[132:133]
	s_mov_b32 m0, s22
	s_nop 0
	global_load_lds_dwordx4 v[142:143], off nt
	v_lshl_add_u64 v[142:143], s[14:15], 0, v[136:137]
	s_add_i32 m0, s22, 0x2000
	s_nop 0
	global_load_lds_dwordx4 v[142:143], off nt
	v_lshl_add_u64 v[142:143], v[184:185], 0, s[84:85]
	s_mov_b32 m0, s34
	s_nop 0
	global_load_lds_dwordx4 v[142:143], off
	v_lshl_add_u64 v[142:143], v[220:221], 0, s[84:85]
	s_mov_b32 m0, s35
	s_nop 0
	global_load_lds_dwordx4 v[142:143], off
	s_waitcnt vmcnt(8)
	s_waitcnt lgkmcnt(0)
	s_barrier
	s_setprio 1
	s_waitcnt lgkmcnt(0)
	v_mfma_f32_16x16x32_bf16 v[62:65], v[146:149], v[188:191], v[62:65]
	v_mfma_f32_16x16x32_bf16 v[58:61], v[154:157], v[188:191], v[58:61]
	v_mfma_f32_16x16x32_bf16 v[46:49], v[146:149], v[196:199], v[46:49]
	v_mfma_f32_16x16x32_bf16 v[42:45], v[154:157], v[196:199], v[42:45]
	v_mfma_f32_16x16x32_bf16 v[30:33], v[146:149], v[204:207], v[30:33]
	v_mfma_f32_16x16x32_bf16 v[26:29], v[154:157], v[204:207], v[26:29]
	v_mfma_f32_16x16x32_bf16 v[14:17], v[146:149], v[212:215], v[14:17]
	v_mfma_f32_16x16x32_bf16 v[10:13], v[154:157], v[212:215], v[10:13]
	v_mfma_f32_16x16x32_bf16 v[62:65], v[150:153], v[192:195], v[62:65]
	v_mfma_f32_16x16x32_bf16 v[58:61], v[158:161], v[192:195], v[58:61]
	v_mfma_f32_16x16x32_bf16 v[46:49], v[150:153], v[200:203], v[46:49]
	v_mfma_f32_16x16x32_bf16 v[42:45], v[158:161], v[200:203], v[42:45]
	v_mfma_f32_16x16x32_bf16 v[30:33], v[150:153], v[208:211], v[30:33]
	v_mfma_f32_16x16x32_bf16 v[26:29], v[158:161], v[208:211], v[26:29]
	v_mfma_f32_16x16x32_bf16 v[14:17], v[150:153], v[216:219], v[14:17]
	v_mfma_f32_16x16x32_bf16 v[10:13], v[158:161], v[216:219], v[10:13]
	s_setprio 0
	s_setprio 1
	v_mfma_f32_16x16x32_bf16 v[54:57], v[162:165], v[188:191], v[54:57]
	v_mfma_f32_16x16x32_bf16 v[50:53], v[170:173], v[188:191], v[50:53]
	v_mfma_f32_16x16x32_bf16 v[38:41], v[162:165], v[196:199], v[38:41]
	v_mfma_f32_16x16x32_bf16 v[34:37], v[170:173], v[196:199], v[34:37]
	v_mfma_f32_16x16x32_bf16 v[22:25], v[162:165], v[204:207], v[22:25]
	v_mfma_f32_16x16x32_bf16 v[18:21], v[170:173], v[204:207], v[18:21]
	v_mfma_f32_16x16x32_bf16 v[6:9], v[162:165], v[212:215], v[6:9]
	v_mfma_f32_16x16x32_bf16 v[2:5], v[170:173], v[212:215], v[2:5]
	v_mfma_f32_16x16x32_bf16 v[54:57], v[166:169], v[192:195], v[54:57]
	v_mfma_f32_16x16x32_bf16 v[50:53], v[174:177], v[192:195], v[50:53]
	v_mfma_f32_16x16x32_bf16 v[38:41], v[166:169], v[200:203], v[38:41]
	v_mfma_f32_16x16x32_bf16 v[34:37], v[174:177], v[200:203], v[34:37]
	v_mfma_f32_16x16x32_bf16 v[22:25], v[166:169], v[208:211], v[22:25]
	v_mfma_f32_16x16x32_bf16 v[18:21], v[174:177], v[208:211], v[18:21]
	v_mfma_f32_16x16x32_bf16 v[6:9], v[166:169], v[216:219], v[6:9]
	v_mfma_f32_16x16x32_bf16 v[2:5], v[174:177], v[216:219], v[2:5]
	s_setprio 0
	s_barrier
	s_add_i32 s41, s41, 2
	s_add_u32 s20, s20, 0x100
	s_addc_u32 s21, s21, 0
	s_add_u32 s52, s52, 0x100
	s_addc_u32 s53, s53, 0
	s_cmp_gt_u32 s41, 29
	s_cbranch_scc0 .LBB0_2130
	s_and_b64 vcc, exec, s[6:7]
	s_cbranch_vccz .LBB0_2133
	s_barrier

; #define PG8_STAGE(bufoff, gbase, voff) do { _Pragma("unroll") for (int _i = 0; _i < 2; ++_i) \
;         __builtin_amdgcn_global_load_lds((const unsigned*)((const char*)(gbase) + (voff)[_i]), (LAS unsigned*)(lds + (bufoff) + ldsw + _i * 8192), 16, 0, 0); } while (0)
; #define PG8_LDA(dst, b, h) do { _Pragma("unroll") for (int m = 0; m < 4; ++m) _Pragma("unroll") for (int k = 0; k < 2; ++k) dst[m][k] = *(const LAS bf16x8*)(lds + PG8_SA(b, h) + aoff + m * 2048 + k * 1024); } while (0)
; #define PG8_LDB(dst, b, h) do { _Pragma("unroll") for (int n = 0; n < 2; ++n) _Pragma("unroll") for (int k = 0; k < 2; ++k) dst[n][k] = *(const LAS bf16x8*)(lds + PG8_SB(b, h) + boff + n * 2048 + k * 1024); } while (0)
; #define PG8_MMA(ai, bj, At, Bt) do { __builtin_amdgcn_s_setprio(1); _Pragma("unroll") for (int m = 0; m < 4; ++m) _Pragma("unroll") for (int n = 0; n < 2; ++n) _Pragma("unroll") for (int k = 0; k < 2; ++k) \
;         acc[ai][bj][m][n] = __builtin_amdgcn_mfma_f32_16x16x32_bf16(Bt[n][k], At[m][k], acc[ai][bj][m][n], 0, 0, 0); __builtin_amdgcn_s_setprio(0); } while (0)
; #define PG8_WAIT_V(n) asm volatile("s_waitcnt vmcnt(" #n ")" ::: "memory")
; #define PG8_WAIT_L(n) asm volatile("s_waitcnt lgkmcnt(" #n ")" ::: "memory")
; #define PG8_BAR __builtin_amdgcn_s_barrier()
; #define PG8_SCHED __builtin_amdgcn_sched_barrier(0)
; template <class Epi>
; __device__ __forceinline__ void gemm_phase(LAS unsigned char* lds, const Gemm g, const StaticOrder& S, const Epi& E) {
;     ...
;             const bool last = (t == nt - 2);
;             const char* a1 = cA + (size_t)(t + 1) * kstep;
;             const char* a2 = last ? nA : cA + (size_t)(t + 2) * kstep; const char* b2 = last ? nB : cB + (size_t)(t + 2) * kstep;
;             const char* a3 = a2 + kstep; const char* b3 = b2 + kstep;
;             PG8_LDB(B0, 0, 0); PG8_LDB(B1, 0, 1); PG8_SCHED; PG8_LDA(At, 0, 0); PG8_STAGE(PG8_SA(1, 1), a1 + hstepA, voffA);
;             PG8_WAIT_V(8); PG8_WAIT_L(0); PG8_BAR; PG8_MMA(0, 0, At, B0); PG8_MMA(0, 1, At, B1); PG8_BAR; PG8_SCHED;
;             PG8_LDA(At, 0, 1); PG8_STAGE(PG8_SB(0, 0), b2, voffB); PG8_STAGE(PG8_SB(0, 1), b2 + hstepB, voffB); PG8_STAGE(PG8_SA(0, 0), a2, voffA);
.LBB0_2155:
	s_add_u32 s41, s20, s14
	s_addc_u32 s44, s21, 0
	s_add_u32 s15, s41, 0x100
	s_addc_u32 s34, s44, 0
	s_and_b64 s[30:31], s[28:29], exec
	s_cselect_b32 s31, s19, s34
	s_cselect_b32 s30, s3, s15
	s_add_u32 s14, s12, s14
	s_addc_u32 s15, s13, 0
	s_add_u32 s34, s14, 0x100
	s_addc_u32 s35, s15, 0
	s_add_i32 s81, 0, 0x10000
	s_and_b64 s[14:15], s[28:29], exec
	s_cselect_b32 s35, s17, s35
	s_cselect_b32 s34, s40, s34
	s_add_i32 s29, 0, 0x14000
	s_add_u32 s68, s41, 0x10080
	s_addc_u32 s69, s44, 0
	s_add_i32 s80, s81, s63
	s_add_i32 m0, s11, 0xc000
	s_add_i32 s83, s11, 0xe000
	s_add_i32 s77, s80, 0x2000
	v_add_u32_e32 v139, s81, v1
	s_add_u32 s44, s34, 0x10000
	ds_read_b128 v[140:143], v139
	ds_read_b128 v[144:147], v139 offset:1024
	ds_read_b128 v[148:151], v139 offset:2048
	ds_read_b128 v[152:155], v139 offset:3072
	v_add_u32_e32 v139, s29, v1
	s_addc_u32 s45, s35, 0
	s_add_i32 s79, s29, s63
	ds_read_b128 v[156:159], v139
	ds_read_b128 v[160:163], v139 offset:1024
	ds_read_b128 v[164:167], v139 offset:2048
	ds_read_b128 v[168:171], v139 offset:3072
	s_add_i32 s78, s79, 0x2000
	s_add_i32 s76, 0, 0x18000
	s_add_i32 vcc_hi, 0, 0x1c000
	s_add_u32 s14, s30, 0x10000
	s_addc_u32 s15, s31, 0
	s_add_i32 vcc_lo, s76, s63
	s_add_i32 s41, vcc_lo, 0x2000
	s_add_u32 s28, s34, 0x10080
	s_addc_u32 s29, s35, 0
	s_add_i32 s82, vcc_hi, s63
	s_add_i32 s81, s82, 0x2000
	v_lshl_add_u64 v[184:185], s[68:69], 0, v[130:131]
	ds_read_b128 v[172:175], v138
	ds_read_b128 v[176:179], v138 offset:1024
	ds_read_b128 v[188:191], v138 offset:2048
	ds_read_b128 v[192:195], v138 offset:3072
	ds_read_b128 v[196:199], v138 offset:4096
	ds_read_b128 v[200:203], v138 offset:5120
	ds_read_b128 v[204:207], v138 offset:6144
	ds_read_b128 v[208:211], v138 offset:7168
	global_load_lds_dwordx4 v[184:185], off
	v_lshl_add_u64 v[184:185], s[68:69], 0, v[134:135]
	s_mov_b32 m0, s83
	s_nop 0
	global_load_lds_dwordx4 v[184:185], off
	s_waitcnt vmcnt(8)
	s_waitcnt lgkmcnt(0)
	s_barrier
	s_setprio 1
	s_waitcnt lgkmcnt(0)
	v_mfma_f32_16x16x32_bf16 v[126:129], v[140:143], v[172:175], v[126:129]
	v_mfma_f32_16x16x32_bf16 v[122:125], v[148:151], v[172:175], v[122:125]
	v_mfma_f32_16x16x32_bf16 v[118:121], v[140:143], v[188:191], v[118:121]
	v_mfma_f32_16x16x32_bf16 v[114:117], v[148:151], v[188:191], v[114:117]
	v_mfma_f32_16x16x32_bf16 v[102:105], v[140:143], v[196:199], v[102:105]
	v_mfma_f32_16x16x32_bf16 v[98:101], v[148:151], v[196:199], v[98:101]
	v_mfma_f32_16x16x32_bf16 v[86:89], v[140:143], v[204:207], v[86:89]
	v_mfma_f32_16x16x32_bf16 v[82:85], v[148:151], v[204:207], v[82:85]
	v_mfma_f32_16x16x32_bf16 v[126:129], v[144:147], v[176:179], v[126:129]
	v_mfma_f32_16x16x32_bf16 v[122:125], v[152:155], v[176:179], v[122:125]
	v_mfma_f32_16x16x32_bf16 v[118:121], v[144:147], v[192:195], v[118:121]
	v_mfma_f32_16x16x32_bf16 v[114:117], v[152:155], v[192:195], v[114:117]
	v_mfma_f32_16x16x32_bf16 v[102:105], v[144:147], v[200:203], v[102:105]
	v_mfma_f32_16x16x32_bf16 v[98:101], v[152:155], v[200:203], v[98:101]
	v_mfma_f32_16x16x32_bf16 v[86:89], v[144:147], v[208:211], v[86:89]
	v_mfma_f32_16x16x32_bf16 v[82:85], v[152:155], v[208:211], v[82:85]
	s_setprio 0
	s_setprio 1
	v_mfma_f32_16x16x32_bf16 v[110:113], v[156:159], v[172:175], v[110:113]
	v_mfma_f32_16x16x32_bf16 v[106:109], v[164:167], v[172:175], v[106:109]
	v_mfma_f32_16x16x32_bf16 v[94:97], v[156:159], v[188:191], v[94:97]
	v_mfma_f32_16x16x32_bf16 v[90:93], v[164:167], v[188:191], v[90:93]
	v_mfma_f32_16x16x32_bf16 v[78:81], v[156:159], v[196:199], v[78:81]
	v_mfma_f32_16x16x32_bf16 v[74:77], v[164:167], v[196:199], v[74:77]
	v_mfma_f32_16x16x32_bf16 v[70:73], v[156:159], v[204:207], v[70:73]
	v_mfma_f32_16x16x32_bf16 v[66:69], v[164:167], v[204:207], v[66:69]
	v_mfma_f32_16x16x32_bf16 v[110:113], v[160:163], v[176:179], v[110:113]
	v_mfma_f32_16x16x32_bf16 v[106:109], v[168:171], v[176:179], v[106:109]
	v_mfma_f32_16x16x32_bf16 v[94:97], v[160:163], v[192:195], v[94:97]
	v_mfma_f32_16x16x32_bf16 v[90:93], v[168:171], v[192:195], v[90:93]
	v_mfma_f32_16x16x32_bf16 v[78:81], v[160:163], v[200:203], v[78:81]
	v_mfma_f32_16x16x32_bf16 v[74:77], v[168:171], v[200:203], v[74:77]
	v_mfma_f32_16x16x32_bf16 v[70:73], v[160:163], v[208:211], v[70:73]
	v_mfma_f32_16x16x32_bf16 v[66:69], v[168:171], v[208:211], v[66:69]
	s_setprio 0
	s_barrier
	s_mov_b32 m0, s80
	v_lshl_add_u64 v[184:185], s[34:35], 0, v[132:133]
	ds_read_b128 v[172:175], v138 offset:16384
	ds_read_b128 v[176:179], v138 offset:17408
	ds_read_b128 v[188:191], v138 offset:18432
	ds_read_b128 v[192:195], v138 offset:19456
	ds_read_b128 v[196:199], v138 offset:20480
	ds_read_b128 v[200:203], v138 offset:21504
	ds_read_b128 v[204:207], v138 offset:22528
	ds_read_b128 v[208:211], v138 offset:23552
	global_load_lds_dwordx4 v[184:185], off nt
	v_lshl_add_u64 v[212:213], s[34:35], 0, v[136:137]
	s_mov_b32 m0, s77
	v_lshl_add_u64 v[214:215], s[44:45], 0, v[132:133]
	global_load_lds_dwordx4 v[212:213], off nt
	s_mov_b32 m0, s79
	v_lshl_add_u64 v[216:217], s[30:31], 0, v[134:135]
	global_load_lds_dwordx4 v[214:215], off nt
	v_lshl_add_u64 v[214:215], s[44:45], 0, v[136:137]
	s_mov_b32 m0, s78
	s_nop 0
	global_load_lds_dwordx4 v[214:215], off nt
	v_lshl_add_u64 v[214:215], s[30:31], 0, v[130:131]
	s_mov_b32 m0, s11
	s_nop 0
	global_load_lds_dwordx4 v[214:215], off
	s_mov_b32 m0, s64
	s_nop 0
	global_load_lds_dwordx4 v[216:217], off
	s_waitcnt vmcnt(8)
	s_waitcnt lgkmcnt(0)
	s_barrier
; #define PG8_STAGE(bufoff, gbase, voff) do { _Pragma("unroll") for (int _i = 0; _i < 2; ++_i) \
;         __builtin_amdgcn_global_load_lds((const unsigned*)((const char*)(gbase) + (voff)[_i]), (LAS unsigned*)(lds + (bufoff) + ldsw + _i * 8192), 16, 0, 0); } while (0)
; #define PG8_LDA(dst, b, h) do { _Pragma("unroll") for (int m = 0; m < 4; ++m) _Pragma("unroll") for (int k = 0; k < 2; ++k) dst[m][k] = *(const LAS bf16x8*)(lds + PG8_SA(b, h) + aoff + m * 2048 + k * 1024); } while (0)
; #define PG8_LDB(dst, b, h) do { _Pragma("unroll") for (int n = 0; n < 2; ++n) _Pragma("unroll") for (int k = 0; k < 2; ++k) dst[n][k] = *(const LAS bf16x8*)(lds + PG8_SB(b, h) + boff + n * 2048 + k * 1024); } while (0)
; #define PG8_MMA(ai, bj, At, Bt) do { __builtin_amdgcn_s_setprio(1); _Pragma("unroll") for (int m = 0; m < 4; ++m) _Pragma("unroll") for (int n = 0; n < 2; ++n) _Pragma("unroll") for (int k = 0; k < 2; ++k) \
;         acc[ai][bj][m][n] = __builtin_amdgcn_mfma_f32_16x16x32_bf16(Bt[n][k], At[m][k], acc[ai][bj][m][n], 0, 0, 0); __builtin_amdgcn_s_setprio(0); } while (0)
; #define PG8_WAIT_V(n) asm volatile("s_waitcnt vmcnt(" #n ")" ::: "memory")
; #define PG8_WAIT_L(n) asm volatile("s_waitcnt lgkmcnt(" #n ")" ::: "memory")
; #define PG8_BAR __builtin_amdgcn_s_barrier()
; #define PG8_SCHED __builtin_amdgcn_sched_barrier(0)
; template <class Epi>
; __device__ __forceinline__ void gemm_phase(LAS unsigned char* lds, const Gemm g, const StaticOrder& S, const Epi& E) {
;     ...
;             PG8_WAIT_V(8); PG8_WAIT_L(0); PG8_BAR; PG8_MMA(1, 0, At, B0); PG8_MMA(1, 1, At, B1); PG8_BAR; PG8_SCHED;
;             PG8_LDB(B0, 1, 0); PG8_LDB(B1, 1, 1); PG8_SCHED; PG8_LDA(At, 1, 0); PG8_STAGE(PG8_SA(0, 1), a2 + hstepA, voffA);
;             PG8_WAIT_V(8); PG8_WAIT_L(0); PG8_BAR; PG8_MMA(0, 0, At, B0); PG8_MMA(0, 1, At, B1); PG8_BAR; PG8_SCHED;
	s_setprio 1
	s_waitcnt lgkmcnt(0)
	v_mfma_f32_16x16x32_bf16 v[62:65], v[140:143], v[172:175], v[62:65]
	v_mfma_f32_16x16x32_bf16 v[58:61], v[148:151], v[172:175], v[58:61]
	v_mfma_f32_16x16x32_bf16 v[54:57], v[140:143], v[188:191], v[54:57]
	v_mfma_f32_16x16x32_bf16 v[50:53], v[148:151], v[188:191], v[50:53]
	v_mfma_f32_16x16x32_bf16 v[38:41], v[140:143], v[196:199], v[38:41]
	v_mfma_f32_16x16x32_bf16 v[34:37], v[148:151], v[196:199], v[34:37]
	v_mfma_f32_16x16x32_bf16 v[22:25], v[140:143], v[204:207], v[22:25]
	v_mfma_f32_16x16x32_bf16 v[18:21], v[148:151], v[204:207], v[18:21]
	v_mfma_f32_16x16x32_bf16 v[62:65], v[144:147], v[176:179], v[62:65]
	v_mfma_f32_16x16x32_bf16 v[58:61], v[152:155], v[176:179], v[58:61]
	v_mfma_f32_16x16x32_bf16 v[54:57], v[144:147], v[192:195], v[54:57]
	v_mfma_f32_16x16x32_bf16 v[50:53], v[152:155], v[192:195], v[50:53]
	v_mfma_f32_16x16x32_bf16 v[38:41], v[144:147], v[200:203], v[38:41]
	v_mfma_f32_16x16x32_bf16 v[34:37], v[152:155], v[200:203], v[34:37]
	v_mfma_f32_16x16x32_bf16 v[22:25], v[144:147], v[208:211], v[22:25]
	v_mfma_f32_16x16x32_bf16 v[18:21], v[152:155], v[208:211], v[18:21]
	s_setprio 0
	s_setprio 1
	v_mfma_f32_16x16x32_bf16 v[46:49], v[156:159], v[172:175], v[46:49]
	v_mfma_f32_16x16x32_bf16 v[42:45], v[164:167], v[172:175], v[42:45]
	v_mfma_f32_16x16x32_bf16 v[30:33], v[156:159], v[188:191], v[30:33]
	v_mfma_f32_16x16x32_bf16 v[26:29], v[164:167], v[188:191], v[26:29]
	v_mfma_f32_16x16x32_bf16 v[14:17], v[156:159], v[196:199], v[14:17]
	v_mfma_f32_16x16x32_bf16 v[10:13], v[164:167], v[196:199], v[10:13]
	v_mfma_f32_16x16x32_bf16 v[6:9], v[156:159], v[204:207], v[6:9]
	v_mfma_f32_16x16x32_bf16 v[2:5], v[164:167], v[204:207], v[2:5]
	v_mfma_f32_16x16x32_bf16 v[46:49], v[160:163], v[176:179], v[46:49]
	v_mfma_f32_16x16x32_bf16 v[42:45], v[168:171], v[176:179], v[42:45]
	v_mfma_f32_16x16x32_bf16 v[30:33], v[160:163], v[192:195], v[30:33]
	v_mfma_f32_16x16x32_bf16 v[26:29], v[168:171], v[192:195], v[26:29]
	v_mfma_f32_16x16x32_bf16 v[14:17], v[160:163], v[200:203], v[14:17]
	v_mfma_f32_16x16x32_bf16 v[10:13], v[168:171], v[200:203], v[10:13]
	v_mfma_f32_16x16x32_bf16 v[6:9], v[160:163], v[208:211], v[6:9]
	v_mfma_f32_16x16x32_bf16 v[2:5], v[168:171], v[208:211], v[2:5]
	s_setprio 0
	s_barrier
	v_add_u32_e32 v139, s76, v1
	ds_read_b128 v[140:143], v139
	ds_read_b128 v[144:147], v139 offset:1024
	ds_read_b128 v[148:151], v139 offset:2048
	ds_read_b128 v[152:155], v139 offset:3072
	v_add_u32_e32 v139, vcc_hi, v1
	ds_read_b128 v[156:159], v139
	ds_read_b128 v[160:163], v139 offset:1024
	ds_read_b128 v[164:167], v139 offset:2048
	ds_read_b128 v[168:171], v139 offset:3072
	s_mov_b32 m0, s65
	v_lshl_add_u64 v[218:219], s[14:15], 0, v[130:131]
	ds_read_b128 v[172:175], v138 offset:32768
	ds_read_b128 v[176:179], v138 offset:33792
	ds_read_b128 v[188:191], v138 offset:34816
	ds_read_b128 v[192:195], v138 offset:35840
	ds_read_b128 v[196:199], v138 offset:36864
	ds_read_b128 v[200:203], v138 offset:37888
	ds_read_b128 v[204:207], v138 offset:38912
	ds_read_b128 v[208:211], v138 offset:39936
	global_load_lds_dwordx4 v[218:219], off
	v_lshl_add_u64 v[218:219], s[14:15], 0, v[134:135]
	s_mov_b32 m0, s70
	s_nop 0
	global_load_lds_dwordx4 v[218:219], off
	s_waitcnt vmcnt(8)
	s_waitcnt lgkmcnt(0)
	s_barrier
	s_setprio 1
	s_waitcnt lgkmcnt(0)
	v_mfma_f32_16x16x32_bf16 v[126:129], v[140:143], v[172:175], v[126:129]
	v_mfma_f32_16x16x32_bf16 v[122:125], v[148:151], v[172:175], v[122:125]
	v_mfma_f32_16x16x32_bf16 v[118:121], v[140:143], v[188:191], v[118:121]
	v_mfma_f32_16x16x32_bf16 v[114:117], v[148:151], v[188:191], v[114:117]
	v_mfma_f32_16x16x32_bf16 v[102:105], v[140:143], v[196:199], v[102:105]
	v_mfma_f32_16x16x32_bf16 v[98:101], v[148:151], v[196:199], v[98:101]
	v_mfma_f32_16x16x32_bf16 v[86:89], v[140:143], v[204:207], v[86:89]
	v_mfma_f32_16x16x32_bf16 v[82:85], v[148:151], v[204:207], v[82:85]
	v_mfma_f32_16x16x32_bf16 v[126:129], v[144:147], v[176:179], v[126:129]
	v_mfma_f32_16x16x32_bf16 v[122:125], v[152:155], v[176:179], v[122:125]
	v_mfma_f32_16x16x32_bf16 v[118:121], v[144:147], v[192:195], v[118:121]
	v_mfma_f32_16x16x32_bf16 v[114:117], v[152:155], v[192:195], v[114:117]
	v_mfma_f32_16x16x32_bf16 v[102:105], v[144:147], v[200:203], v[102:105]
	v_mfma_f32_16x16x32_bf16 v[98:101], v[152:155], v[200:203], v[98:101]
	v_mfma_f32_16x16x32_bf16 v[86:89], v[144:147], v[208:211], v[86:89]
	v_mfma_f32_16x16x32_bf16 v[82:85], v[152:155], v[208:211], v[82:85]
	s_setprio 0
	s_setprio 1
	v_mfma_f32_16x16x32_bf16 v[110:113], v[156:159], v[172:175], v[110:113]
	v_mfma_f32_16x16x32_bf16 v[106:109], v[164:167], v[172:175], v[106:109]
	v_mfma_f32_16x16x32_bf16 v[94:97], v[156:159], v[188:191], v[94:97]
	v_mfma_f32_16x16x32_bf16 v[90:93], v[164:167], v[188:191], v[90:93]
	v_mfma_f32_16x16x32_bf16 v[78:81], v[156:159], v[196:199], v[78:81]
	v_mfma_f32_16x16x32_bf16 v[74:77], v[164:167], v[196:199], v[74:77]
	v_mfma_f32_16x16x32_bf16 v[70:73], v[156:159], v[204:207], v[70:73]
	v_mfma_f32_16x16x32_bf16 v[66:69], v[164:167], v[204:207], v[66:69]
	v_mfma_f32_16x16x32_bf16 v[110:113], v[160:163], v[176:179], v[110:113]
	v_mfma_f32_16x16x32_bf16 v[106:109], v[168:171], v[176:179], v[106:109]
	v_mfma_f32_16x16x32_bf16 v[94:97], v[160:163], v[192:195], v[94:97]
	v_mfma_f32_16x16x32_bf16 v[90:93], v[168:171], v[192:195], v[90:93]
	v_mfma_f32_16x16x32_bf16 v[78:81], v[160:163], v[200:203], v[78:81]
	v_mfma_f32_16x16x32_bf16 v[74:77], v[168:171], v[200:203], v[74:77]
	v_mfma_f32_16x16x32_bf16 v[70:73], v[160:163], v[208:211], v[70:73]
	v_mfma_f32_16x16x32_bf16 v[66:69], v[168:171], v[208:211], v[66:69]
	s_setprio 0
	s_barrier
; #define PG8_STAGE(bufoff, gbase, voff) do { _Pragma("unroll") for (int _i = 0; _i < 2; ++_i) \
;         __builtin_amdgcn_global_load_lds((const unsigned*)((const char*)(gbase) + (voff)[_i]), (LAS unsigned*)(lds + (bufoff) + ldsw + _i * 8192), 16, 0, 0); } while (0)
; #define PG8_LDA(dst, b, h) do { _Pragma("unroll") for (int m = 0; m < 4; ++m) _Pragma("unroll") for (int k = 0; k < 2; ++k) dst[m][k] = *(const LAS bf16x8*)(lds + PG8_SA(b, h) + aoff + m * 2048 + k * 1024); } while (0)
; #define PG8_MMA(ai, bj, At, Bt) do { __builtin_amdgcn_s_setprio(1); _Pragma("unroll") for (int m = 0; m < 4; ++m) _Pragma("unroll") for (int n = 0; n < 2; ++n) _Pragma("unroll") for (int k = 0; k < 2; ++k) \
;         acc[ai][bj][m][n] = __builtin_amdgcn_mfma_f32_16x16x32_bf16(Bt[n][k], At[m][k], acc[ai][bj][m][n], 0, 0, 0); __builtin_amdgcn_s_setprio(0); } while (0)
; #define PG8_WAIT_V(n) asm volatile("s_waitcnt vmcnt(" #n ")" ::: "memory")
; #define PG8_WAIT_L(n) asm volatile("s_waitcnt lgkmcnt(" #n ")" ::: "memory")
; #define PG8_BAR __builtin_amdgcn_s_barrier()
; #define PG8_SCHED __builtin_amdgcn_sched_barrier(0)
; template <class Epi>
; __device__ __forceinline__ void gemm_phase(LAS unsigned char* lds, const Gemm g, const StaticOrder& S, const Epi& E) {
;     ...
;             PG8_LDA(At, 1, 1); PG8_STAGE(PG8_SB(1, 0), b3, voffB); PG8_STAGE(PG8_SB(1, 1), b3 + hstepB, voffB); PG8_STAGE(PG8_SA(1, 0), a3, voffA);
;             PG8_WAIT_V(8); PG8_WAIT_L(0); PG8_BAR; PG8_MMA(1, 0, At, B0); PG8_MMA(1, 1, At, B1); PG8_BAR; PG8_SCHED;
;         }
;         if (wr == 0) PG8_BAR;
	s_mov_b32 m0, vcc_lo
	v_lshl_add_u64 v[184:185], v[184:185], 0, s[84:85]
	ds_read_b128 v[172:175], v138 offset:49152
	ds_read_b128 v[176:179], v138 offset:50176
	ds_read_b128 v[188:191], v138 offset:51200
	ds_read_b128 v[192:195], v138 offset:52224
	ds_read_b128 v[196:199], v138 offset:53248
	ds_read_b128 v[200:203], v138 offset:54272
	ds_read_b128 v[204:207], v138 offset:55296
	ds_read_b128 v[208:211], v138 offset:56320
	global_load_lds_dwordx4 v[184:185], off nt
	v_lshl_add_u64 v[184:185], v[212:213], 0, s[84:85]
	s_mov_b32 m0, s41
	s_nop 0
	global_load_lds_dwordx4 v[184:185], off nt
	v_lshl_add_u64 v[184:185], s[28:29], 0, v[132:133]
	s_mov_b32 m0, s82
	s_nop 0
	global_load_lds_dwordx4 v[184:185], off nt
	v_lshl_add_u64 v[184:185], s[28:29], 0, v[136:137]
	s_mov_b32 m0, s81
	s_nop 0
	global_load_lds_dwordx4 v[184:185], off nt
	v_lshl_add_u64 v[184:185], v[214:215], 0, s[84:85]
	s_mov_b32 m0, s86
	s_nop 0
	global_load_lds_dwordx4 v[184:185], off
	v_lshl_add_u64 v[184:185], v[216:217], 0, s[84:85]
	s_mov_b32 m0, s87
	s_nop 0
	global_load_lds_dwordx4 v[184:185], off
	s_waitcnt vmcnt(8)
	s_waitcnt lgkmcnt(0)
	s_barrier
	s_setprio 1
	s_waitcnt lgkmcnt(0)
	v_mfma_f32_16x16x32_bf16 v[62:65], v[140:143], v[172:175], v[62:65]
	v_mfma_f32_16x16x32_bf16 v[58:61], v[148:151], v[172:175], v[58:61]
	v_mfma_f32_16x16x32_bf16 v[54:57], v[140:143], v[188:191], v[54:57]
	v_mfma_f32_16x16x32_bf16 v[50:53], v[148:151], v[188:191], v[50:53]
	v_mfma_f32_16x16x32_bf16 v[38:41], v[140:143], v[196:199], v[38:41]
	v_mfma_f32_16x16x32_bf16 v[34:37], v[148:151], v[196:199], v[34:37]
	v_mfma_f32_16x16x32_bf16 v[22:25], v[140:143], v[204:207], v[22:25]
	v_mfma_f32_16x16x32_bf16 v[18:21], v[148:151], v[204:207], v[18:21]
	v_mfma_f32_16x16x32_bf16 v[62:65], v[144:147], v[176:179], v[62:65]
	v_mfma_f32_16x16x32_bf16 v[58:61], v[152:155], v[176:179], v[58:61]
	v_mfma_f32_16x16x32_bf16 v[54:57], v[144:147], v[192:195], v[54:57]
	v_mfma_f32_16x16x32_bf16 v[50:53], v[152:155], v[192:195], v[50:53]
	v_mfma_f32_16x16x32_bf16 v[38:41], v[144:147], v[200:203], v[38:41]
	v_mfma_f32_16x16x32_bf16 v[34:37], v[152:155], v[200:203], v[34:37]
	v_mfma_f32_16x16x32_bf16 v[22:25], v[144:147], v[208:211], v[22:25]
	v_mfma_f32_16x16x32_bf16 v[18:21], v[152:155], v[208:211], v[18:21]
	s_setprio 0
	s_setprio 1
	v_mfma_f32_16x16x32_bf16 v[46:49], v[156:159], v[172:175], v[46:49]
	v_mfma_f32_16x16x32_bf16 v[42:45], v[164:167], v[172:175], v[42:45]
	v_mfma_f32_16x16x32_bf16 v[30:33], v[156:159], v[188:191], v[30:33]
	v_mfma_f32_16x16x32_bf16 v[26:29], v[164:167], v[188:191], v[26:29]
	v_mfma_f32_16x16x32_bf16 v[14:17], v[156:159], v[196:199], v[14:17]
	v_mfma_f32_16x16x32_bf16 v[10:13], v[164:167], v[196:199], v[10:13]
	v_mfma_f32_16x16x32_bf16 v[6:9], v[156:159], v[204:207], v[6:9]
	v_mfma_f32_16x16x32_bf16 v[2:5], v[164:167], v[204:207], v[2:5]
	v_mfma_f32_16x16x32_bf16 v[46:49], v[160:163], v[176:179], v[46:49]
	v_mfma_f32_16x16x32_bf16 v[42:45], v[168:171], v[176:179], v[42:45]
	v_mfma_f32_16x16x32_bf16 v[30:33], v[160:163], v[192:195], v[30:33]
	v_mfma_f32_16x16x32_bf16 v[26:29], v[168:171], v[192:195], v[26:29]
	v_mfma_f32_16x16x32_bf16 v[14:17], v[160:163], v[200:203], v[14:17]
	v_mfma_f32_16x16x32_bf16 v[10:13], v[168:171], v[200:203], v[10:13]
	v_mfma_f32_16x16x32_bf16 v[6:9], v[160:163], v[208:211], v[6:9]
	v_mfma_f32_16x16x32_bf16 v[2:5], v[168:171], v[208:211], v[2:5]
	s_setprio 0
	s_barrier
	s_movk_i32 s14, 0x100
	s_andn2_b64 vcc, exec, s[26:27]
	s_mov_b64 s[28:29], -1
	s_mov_b64 s[26:27], 0
	s_cbranch_vccz .LBB0_2155
	v_readlane_b32 s28, v255, 28
	s_and_b64 vcc, exec, s[8:9]
	v_readlane_b32 s29, v255, 29
	s_cbranch_vccz .LBB0_2158
	s_barrier

; #define PG8_STAGE(bufoff, gbase, voff) do { _Pragma("unroll") for (int _i = 0; _i < 2; ++_i) \
;         __builtin_amdgcn_global_load_lds((const unsigned*)((const char*)(gbase) + (voff)[_i]), (LAS unsigned*)(lds + (bufoff) + ldsw + _i * 8192), 16, 0, 0); } while (0)
; #define PG8_LDA(dst, b, h) do { _Pragma("unroll") for (int m = 0; m < 4; ++m) _Pragma("unroll") for (int k = 0; k < 2; ++k) dst[m][k] = *(const LAS bf16x8*)(lds + PG8_SA(b, h) + aoff + m * 2048 + k * 1024); } while (0)
; #define PG8_LDB(dst, b, h) do { _Pragma("unroll") for (int n = 0; n < 2; ++n) _Pragma("unroll") for (int k = 0; k < 2; ++k) dst[n][k] = *(const LAS bf16x8*)(lds + PG8_SB(b, h) + boff + n * 2048 + k * 1024); } while (0)
; #define PG8_MMA(ai, bj, At, Bt) do { __builtin_amdgcn_s_setprio(1); _Pragma("unroll") for (int m = 0; m < 4; ++m) _Pragma("unroll") for (int n = 0; n < 2; ++n) _Pragma("unroll") for (int k = 0; k < 2; ++k) \
;         acc[ai][bj][m][n] = __builtin_amdgcn_mfma_f32_16x16x32_bf16(Bt[n][k], At[m][k], acc[ai][bj][m][n], 0, 0, 0); __builtin_amdgcn_s_setprio(0); } while (0)
; #define PG8_WAIT_V(n) asm volatile("s_waitcnt vmcnt(" #n ")" ::: "memory")
; #define PG8_WAIT_L(n) asm volatile("s_waitcnt lgkmcnt(" #n ")" ::: "memory")
; #define PG8_BAR __builtin_amdgcn_s_barrier()
; #define PG8_SCHED __builtin_amdgcn_sched_barrier(0)
; template <class Epi>
; __device__ __forceinline__ void gemm_phase(LAS unsigned char* lds, const Gemm g, const StaticOrder& S, const Epi& E) {
;     ...
;             const bool last = (t == nt - 2);
;             const char* a1 = cA + (size_t)(t + 1) * kstep;
;             const char* a2 = last ? nA : cA + (size_t)(t + 2) * kstep; const char* b2 = last ? nB : cB + (size_t)(t + 2) * kstep;
;             const char* a3 = a2 + kstep; const char* b3 = b2 + kstep;
;             PG8_LDB(B0, 0, 0); PG8_LDB(B1, 0, 1); PG8_SCHED; PG8_LDA(At, 0, 0); PG8_STAGE(PG8_SA(1, 1), a1 + hstepA, voffA);
;             PG8_WAIT_V(8); PG8_WAIT_L(0); PG8_BAR; PG8_MMA(0, 0, At, B0); PG8_MMA(0, 1, At, B1); PG8_BAR; PG8_SCHED;
;             PG8_LDA(At, 0, 1); PG8_STAGE(PG8_SB(0, 0), b2, voffB); PG8_STAGE(PG8_SB(0, 1), b2 + hstepB, voffB); PG8_STAGE(PG8_SA(0, 0), a2, voffA);
.LBB0_2233:
	s_add_u32 s14, s24, 0xffe00080
	s_addc_u32 s15, s25, -1
	s_add_i32 s52, 0, 0x10000
	s_cmpk_eq_i32 s41, 0x7c
	s_cselect_b32 s27, s1, s15
	s_cselect_b32 s26, s3, s14
	s_cselect_b32 s15, s9, s40
	s_cselect_b32 s14, s17, s19
	s_add_i32 s62, 0, 0x14000
	v_add_u32_e32 v142, s52, v1
	v_add_u32_e32 v167, s62, v1
	ds_read_b128 v[130:133], v142
	ds_read_b128 v[134:137], v142 offset:1024
	ds_read_b128 v[138:141], v142 offset:2048
	ds_read_b128 v[142:145], v142 offset:3072
	ds_read_b128 v[146:149], v167
	ds_read_b128 v[162:165], v167 offset:1024
	ds_read_b128 v[168:171], v167 offset:2048
	ds_read_b128 v[172:175], v167 offset:3072
	v_lshl_add_u64 v[184:185], s[24:25], 0, v[158:159]
	s_add_i32 m0, s31, 0xc000
	ds_read_b128 v[176:179], v166
	ds_read_b128 v[188:191], v166 offset:1024
	ds_read_b128 v[192:195], v166 offset:2048
	ds_read_b128 v[196:199], v166 offset:3072
	ds_read_b128 v[200:203], v166 offset:4096
	ds_read_b128 v[204:207], v166 offset:5120
	ds_read_b128 v[208:211], v166 offset:6144
	ds_read_b128 v[212:215], v166 offset:7168
	global_load_lds_dwordx4 v[184:185], off
	v_lshl_add_u64 v[184:185], s[24:25], 0, v[160:161]
	s_add_i32 m0, s31, 0xe000
	s_nop 0
	global_load_lds_dwordx4 v[184:185], off
	s_waitcnt vmcnt(8)
	s_waitcnt lgkmcnt(0)
	s_barrier
	s_setprio 1
	s_waitcnt lgkmcnt(0)
	v_mfma_f32_16x16x32_bf16 v[126:129], v[130:133], v[176:179], v[126:129]
	v_mfma_f32_16x16x32_bf16 v[122:125], v[138:141], v[176:179], v[122:125]
	v_mfma_f32_16x16x32_bf16 v[118:121], v[130:133], v[192:195], v[118:121]
	v_mfma_f32_16x16x32_bf16 v[114:117], v[138:141], v[192:195], v[114:117]
	v_mfma_f32_16x16x32_bf16 v[94:97], v[130:133], v[200:203], v[94:97]
	v_mfma_f32_16x16x32_bf16 v[90:93], v[138:141], v[200:203], v[90:93]
	v_mfma_f32_16x16x32_bf16 v[82:85], v[130:133], v[208:211], v[82:85]
	v_mfma_f32_16x16x32_bf16 v[74:77], v[138:141], v[208:211], v[74:77]
	v_mfma_f32_16x16x32_bf16 v[126:129], v[134:137], v[188:191], v[126:129]
	v_mfma_f32_16x16x32_bf16 v[122:125], v[142:145], v[188:191], v[122:125]
	v_mfma_f32_16x16x32_bf16 v[118:121], v[134:137], v[196:199], v[118:121]
	v_mfma_f32_16x16x32_bf16 v[114:117], v[142:145], v[196:199], v[114:117]
	v_mfma_f32_16x16x32_bf16 v[94:97], v[134:137], v[204:207], v[94:97]
	v_mfma_f32_16x16x32_bf16 v[90:93], v[142:145], v[204:207], v[90:93]
	v_mfma_f32_16x16x32_bf16 v[82:85], v[134:137], v[212:215], v[82:85]
	v_mfma_f32_16x16x32_bf16 v[74:77], v[142:145], v[212:215], v[74:77]
	s_setprio 0
	s_setprio 1
	v_mfma_f32_16x16x32_bf16 v[110:113], v[146:149], v[176:179], v[110:113]
	v_mfma_f32_16x16x32_bf16 v[106:109], v[168:171], v[176:179], v[106:109]
	v_mfma_f32_16x16x32_bf16 v[102:105], v[146:149], v[192:195], v[102:105]
	v_mfma_f32_16x16x32_bf16 v[98:101], v[168:171], v[192:195], v[98:101]
	v_mfma_f32_16x16x32_bf16 v[86:89], v[146:149], v[200:203], v[86:89]
	v_mfma_f32_16x16x32_bf16 v[78:81], v[168:171], v[200:203], v[78:81]
	v_mfma_f32_16x16x32_bf16 v[70:73], v[146:149], v[208:211], v[70:73]
	v_mfma_f32_16x16x32_bf16 v[66:69], v[168:171], v[208:211], v[66:69]
	v_mfma_f32_16x16x32_bf16 v[110:113], v[162:165], v[188:191], v[110:113]
	v_mfma_f32_16x16x32_bf16 v[106:109], v[172:175], v[188:191], v[106:109]
	v_mfma_f32_16x16x32_bf16 v[102:105], v[162:165], v[196:199], v[102:105]
	v_mfma_f32_16x16x32_bf16 v[98:101], v[172:175], v[196:199], v[98:101]
	v_mfma_f32_16x16x32_bf16 v[86:89], v[162:165], v[204:207], v[86:89]
	v_mfma_f32_16x16x32_bf16 v[78:81], v[172:175], v[204:207], v[78:81]
	v_mfma_f32_16x16x32_bf16 v[70:73], v[162:165], v[212:215], v[70:73]
	v_mfma_f32_16x16x32_bf16 v[66:69], v[172:175], v[212:215], v[66:69]
	s_setprio 0
	s_barrier
	s_add_i32 s52, s52, s30
	v_lshl_add_u64 v[184:185], s[14:15], 0, v[152:153]
	s_mov_b32 m0, s52
	ds_read_b128 v[176:179], v166 offset:16384
	ds_read_b128 v[188:191], v166 offset:17408
	ds_read_b128 v[192:195], v166 offset:18432
	ds_read_b128 v[196:199], v166 offset:19456
	ds_read_b128 v[200:203], v166 offset:20480
	ds_read_b128 v[204:207], v166 offset:21504
	ds_read_b128 v[208:211], v166 offset:22528
	ds_read_b128 v[212:215], v166 offset:23552
	global_load_lds_dwordx4 v[184:185], off nt
	s_add_i32 m0, s52, 0x2000
	s_add_u32 s52, s14, 0x200000
	v_lshl_add_u64 v[216:217], s[14:15], 0, v[156:157]
	s_addc_u32 s53, s15, 0
	s_add_i32 s62, s62, s30
	global_load_lds_dwordx4 v[216:217], off nt
	v_lshl_add_u64 v[218:219], s[52:53], 0, v[152:153]
	s_mov_b32 m0, s62
	v_lshl_add_u64 v[220:221], s[26:27], 0, v[154:155]
	global_load_lds_dwordx4 v[218:219], off nt
	v_lshl_add_u64 v[218:219], s[52:53], 0, v[156:157]
	s_add_i32 m0, s62, 0x2000
	s_nop 0
	global_load_lds_dwordx4 v[218:219], off nt
	v_lshl_add_u64 v[218:219], s[26:27], 0, v[150:151]
	s_mov_b32 m0, s31
	s_nop 0
	global_load_lds_dwordx4 v[218:219], off
	s_mov_b32 m0, s34
	s_nop 0
	global_load_lds_dwordx4 v[220:221], off
	s_waitcnt vmcnt(8)
	s_waitcnt lgkmcnt(0)
	s_barrier
; #define PG8_STAGE(bufoff, gbase, voff) do { _Pragma("unroll") for (int _i = 0; _i < 2; ++_i) \
;         __builtin_amdgcn_global_load_lds((const unsigned*)((const char*)(gbase) + (voff)[_i]), (LAS unsigned*)(lds + (bufoff) + ldsw + _i * 8192), 16, 0, 0); } while (0)
; #define PG8_LDA(dst, b, h) do { _Pragma("unroll") for (int m = 0; m < 4; ++m) _Pragma("unroll") for (int k = 0; k < 2; ++k) dst[m][k] = *(const LAS bf16x8*)(lds + PG8_SA(b, h) + aoff + m * 2048 + k * 1024); } while (0)
; #define PG8_LDB(dst, b, h) do { _Pragma("unroll") for (int n = 0; n < 2; ++n) _Pragma("unroll") for (int k = 0; k < 2; ++k) dst[n][k] = *(const LAS bf16x8*)(lds + PG8_SB(b, h) + boff + n * 2048 + k * 1024); } while (0)
; #define PG8_MMA(ai, bj, At, Bt) do { __builtin_amdgcn_s_setprio(1); _Pragma("unroll") for (int m = 0; m < 4; ++m) _Pragma("unroll") for (int n = 0; n < 2; ++n) _Pragma("unroll") for (int k = 0; k < 2; ++k) \
;         acc[ai][bj][m][n] = __builtin_amdgcn_mfma_f32_16x16x32_bf16(Bt[n][k], At[m][k], acc[ai][bj][m][n], 0, 0, 0); __builtin_amdgcn_s_setprio(0); } while (0)
; #define PG8_WAIT_V(n) asm volatile("s_waitcnt vmcnt(" #n ")" ::: "memory")
; #define PG8_WAIT_L(n) asm volatile("s_waitcnt lgkmcnt(" #n ")" ::: "memory")
; #define PG8_BAR __builtin_amdgcn_s_barrier()
; #define PG8_SCHED __builtin_amdgcn_sched_barrier(0)
; template <class Epi>
; __device__ __forceinline__ void gemm_phase(LAS unsigned char* lds, const Gemm g, const StaticOrder& S, const Epi& E) {
;     ...
;             PG8_WAIT_V(8); PG8_WAIT_L(0); PG8_BAR; PG8_MMA(1, 0, At, B0); PG8_MMA(1, 1, At, B1); PG8_BAR; PG8_SCHED;
;             PG8_LDB(B0, 1, 0); PG8_LDB(B1, 1, 1); PG8_SCHED; PG8_LDA(At, 1, 0); PG8_STAGE(PG8_SA(0, 1), a2 + hstepA, voffA);
;             PG8_WAIT_V(8); PG8_WAIT_L(0); PG8_BAR; PG8_MMA(0, 0, At, B0); PG8_MMA(0, 1, At, B1); PG8_BAR; PG8_SCHED;
	s_setprio 1
	s_waitcnt lgkmcnt(0)
	v_mfma_f32_16x16x32_bf16 v[62:65], v[130:133], v[176:179], v[62:65]
	v_mfma_f32_16x16x32_bf16 v[58:61], v[138:141], v[176:179], v[58:61]
	v_mfma_f32_16x16x32_bf16 v[50:53], v[130:133], v[192:195], v[50:53]
	v_mfma_f32_16x16x32_bf16 v[42:45], v[138:141], v[192:195], v[42:45]
	v_mfma_f32_16x16x32_bf16 v[30:33], v[130:133], v[200:203], v[30:33]
	v_mfma_f32_16x16x32_bf16 v[26:29], v[138:141], v[200:203], v[26:29]
	v_mfma_f32_16x16x32_bf16 v[18:21], v[130:133], v[208:211], v[18:21]
	v_mfma_f32_16x16x32_bf16 v[10:13], v[138:141], v[208:211], v[10:13]
	v_mfma_f32_16x16x32_bf16 v[62:65], v[134:137], v[188:191], v[62:65]
	v_mfma_f32_16x16x32_bf16 v[58:61], v[142:145], v[188:191], v[58:61]
	v_mfma_f32_16x16x32_bf16 v[50:53], v[134:137], v[196:199], v[50:53]
	v_mfma_f32_16x16x32_bf16 v[42:45], v[142:145], v[196:199], v[42:45]
	v_mfma_f32_16x16x32_bf16 v[30:33], v[134:137], v[204:207], v[30:33]
	v_mfma_f32_16x16x32_bf16 v[26:29], v[142:145], v[204:207], v[26:29]
	v_mfma_f32_16x16x32_bf16 v[18:21], v[134:137], v[212:215], v[18:21]
	v_mfma_f32_16x16x32_bf16 v[10:13], v[142:145], v[212:215], v[10:13]
	s_setprio 0
	s_setprio 1
	v_mfma_f32_16x16x32_bf16 v[54:57], v[146:149], v[176:179], v[54:57]
	v_mfma_f32_16x16x32_bf16 v[46:49], v[168:171], v[176:179], v[46:49]
	v_mfma_f32_16x16x32_bf16 v[38:41], v[146:149], v[192:195], v[38:41]
	v_mfma_f32_16x16x32_bf16 v[34:37], v[168:171], v[192:195], v[34:37]
	v_mfma_f32_16x16x32_bf16 v[22:25], v[146:149], v[200:203], v[22:25]
	v_mfma_f32_16x16x32_bf16 v[14:17], v[168:171], v[200:203], v[14:17]
	v_mfma_f32_16x16x32_bf16 v[6:9], v[146:149], v[208:211], v[6:9]
	v_mfma_f32_16x16x32_bf16 v[2:5], v[168:171], v[208:211], v[2:5]
	v_mfma_f32_16x16x32_bf16 v[54:57], v[162:165], v[188:191], v[54:57]
	v_mfma_f32_16x16x32_bf16 v[46:49], v[172:175], v[188:191], v[46:49]
	v_mfma_f32_16x16x32_bf16 v[38:41], v[162:165], v[196:199], v[38:41]
	v_mfma_f32_16x16x32_bf16 v[34:37], v[172:175], v[196:199], v[34:37]
	v_mfma_f32_16x16x32_bf16 v[22:25], v[162:165], v[204:207], v[22:25]
	v_mfma_f32_16x16x32_bf16 v[14:17], v[172:175], v[204:207], v[14:17]
	v_mfma_f32_16x16x32_bf16 v[6:9], v[162:165], v[212:215], v[6:9]
	v_mfma_f32_16x16x32_bf16 v[2:5], v[172:175], v[212:215], v[2:5]
	s_setprio 0
	s_barrier
	s_add_i32 s52, 0, 0x18000
	s_add_i32 s53, 0, 0x1c000
	v_add_u32_e32 v142, s52, v1
	v_add_u32_e32 v167, s53, v1
	ds_read_b128 v[130:133], v142
	ds_read_b128 v[134:137], v142 offset:1024
	ds_read_b128 v[138:141], v142 offset:2048
	ds_read_b128 v[142:145], v142 offset:3072
	ds_read_b128 v[146:149], v167
	ds_read_b128 v[162:165], v167 offset:1024
	ds_read_b128 v[168:171], v167 offset:2048
	ds_read_b128 v[172:175], v167 offset:3072
	s_add_u32 s26, s26, 0x200000
	s_addc_u32 s27, s27, 0
	s_mov_b32 m0, s35
	v_lshl_add_u64 v[222:223], s[26:27], 0, v[150:151]
	ds_read_b128 v[176:179], v166 offset:32768
	ds_read_b128 v[188:191], v166 offset:33792
	ds_read_b128 v[192:195], v166 offset:34816
	ds_read_b128 v[196:199], v166 offset:35840
	ds_read_b128 v[200:203], v166 offset:36864
	ds_read_b128 v[204:207], v166 offset:37888
	ds_read_b128 v[208:211], v166 offset:38912
	ds_read_b128 v[212:215], v166 offset:39936
	global_load_lds_dwordx4 v[222:223], off
	v_lshl_add_u64 v[222:223], s[26:27], 0, v[154:155]
	s_mov_b32 m0, s42
	s_nop 0
	global_load_lds_dwordx4 v[222:223], off
	s_waitcnt vmcnt(8)
	s_waitcnt lgkmcnt(0)
	s_barrier
	s_setprio 1
	s_waitcnt lgkmcnt(0)
	v_mfma_f32_16x16x32_bf16 v[126:129], v[130:133], v[176:179], v[126:129]
	v_mfma_f32_16x16x32_bf16 v[122:125], v[138:141], v[176:179], v[122:125]
	v_mfma_f32_16x16x32_bf16 v[118:121], v[130:133], v[192:195], v[118:121]
	v_mfma_f32_16x16x32_bf16 v[114:117], v[138:141], v[192:195], v[114:117]
	v_mfma_f32_16x16x32_bf16 v[94:97], v[130:133], v[200:203], v[94:97]
	v_mfma_f32_16x16x32_bf16 v[90:93], v[138:141], v[200:203], v[90:93]
	v_mfma_f32_16x16x32_bf16 v[82:85], v[130:133], v[208:211], v[82:85]
	v_mfma_f32_16x16x32_bf16 v[74:77], v[138:141], v[208:211], v[74:77]
	v_mfma_f32_16x16x32_bf16 v[126:129], v[134:137], v[188:191], v[126:129]
	v_mfma_f32_16x16x32_bf16 v[122:125], v[142:145], v[188:191], v[122:125]
	v_mfma_f32_16x16x32_bf16 v[118:121], v[134:137], v[196:199], v[118:121]
	v_mfma_f32_16x16x32_bf16 v[114:117], v[142:145], v[196:199], v[114:117]
	v_mfma_f32_16x16x32_bf16 v[94:97], v[134:137], v[204:207], v[94:97]
	v_mfma_f32_16x16x32_bf16 v[90:93], v[142:145], v[204:207], v[90:93]
	v_mfma_f32_16x16x32_bf16 v[82:85], v[134:137], v[212:215], v[82:85]
	v_mfma_f32_16x16x32_bf16 v[74:77], v[142:145], v[212:215], v[74:77]
	s_setprio 0
	s_setprio 1
	v_mfma_f32_16x16x32_bf16 v[110:113], v[146:149], v[176:179], v[110:113]
	v_mfma_f32_16x16x32_bf16 v[106:109], v[168:171], v[176:179], v[106:109]
	v_mfma_f32_16x16x32_bf16 v[102:105], v[146:149], v[192:195], v[102:105]
	v_mfma_f32_16x16x32_bf16 v[98:101], v[168:171], v[192:195], v[98:101]
	v_mfma_f32_16x16x32_bf16 v[86:89], v[146:149], v[200:203], v[86:89]
	v_mfma_f32_16x16x32_bf16 v[78:81], v[168:171], v[200:203], v[78:81]
	v_mfma_f32_16x16x32_bf16 v[70:73], v[146:149], v[208:211], v[70:73]
	v_mfma_f32_16x16x32_bf16 v[66:69], v[168:171], v[208:211], v[66:69]
	v_mfma_f32_16x16x32_bf16 v[110:113], v[162:165], v[188:191], v[110:113]
	v_mfma_f32_16x16x32_bf16 v[106:109], v[172:175], v[188:191], v[106:109]
	v_mfma_f32_16x16x32_bf16 v[102:105], v[162:165], v[196:199], v[102:105]
	v_mfma_f32_16x16x32_bf16 v[98:101], v[172:175], v[196:199], v[98:101]
	v_mfma_f32_16x16x32_bf16 v[86:89], v[162:165], v[204:207], v[86:89]
	v_mfma_f32_16x16x32_bf16 v[78:81], v[172:175], v[204:207], v[78:81]
	v_mfma_f32_16x16x32_bf16 v[70:73], v[162:165], v[212:215], v[70:73]
	v_mfma_f32_16x16x32_bf16 v[66:69], v[172:175], v[212:215], v[66:69]
	s_setprio 0
	s_barrier
; #define PG8_STAGE(bufoff, gbase, voff) do { _Pragma("unroll") for (int _i = 0; _i < 2; ++_i) \
;         __builtin_amdgcn_global_load_lds((const unsigned*)((const char*)(gbase) + (voff)[_i]), (LAS unsigned*)(lds + (bufoff) + ldsw + _i * 8192), 16, 0, 0); } while (0)
; #define PG8_LDA(dst, b, h) do { _Pragma("unroll") for (int m = 0; m < 4; ++m) _Pragma("unroll") for (int k = 0; k < 2; ++k) dst[m][k] = *(const LAS bf16x8*)(lds + PG8_SA(b, h) + aoff + m * 2048 + k * 1024); } while (0)
; #define PG8_MMA(ai, bj, At, Bt) do { __builtin_amdgcn_s_setprio(1); _Pragma("unroll") for (int m = 0; m < 4; ++m) _Pragma("unroll") for (int n = 0; n < 2; ++n) _Pragma("unroll") for (int k = 0; k < 2; ++k) \
;         acc[ai][bj][m][n] = __builtin_amdgcn_mfma_f32_16x16x32_bf16(Bt[n][k], At[m][k], acc[ai][bj][m][n], 0, 0, 0); __builtin_amdgcn_s_setprio(0); } while (0)
; #define PG8_WAIT_V(n) asm volatile("s_waitcnt vmcnt(" #n ")" ::: "memory")
; #define PG8_WAIT_L(n) asm volatile("s_waitcnt lgkmcnt(" #n ")" ::: "memory")
; #define PG8_BAR __builtin_amdgcn_s_barrier()
; #define PG8_SCHED __builtin_amdgcn_sched_barrier(0)
; template <class Epi>
; __device__ __forceinline__ void gemm_phase(LAS unsigned char* lds, const Gemm g, const StaticOrder& S, const Epi& E) {
;     ...
;             PG8_LDA(At, 1, 1); PG8_STAGE(PG8_SB(1, 0), b3, voffB); PG8_STAGE(PG8_SB(1, 1), b3 + hstepB, voffB); PG8_STAGE(PG8_SA(1, 0), a3, voffA);
;             PG8_WAIT_V(8); PG8_WAIT_L(0); PG8_BAR; PG8_MMA(1, 0, At, B0); PG8_MMA(1, 1, At, B1); PG8_BAR; PG8_SCHED;
;         }
;         if (wr == 0) PG8_BAR;
	s_add_i32 s26, s52, s30
	v_lshl_add_u64 v[184:185], v[184:185], 0, s[84:85]
	s_mov_b32 m0, s26
	ds_read_b128 v[176:179], v166 offset:49152
	ds_read_b128 v[188:191], v166 offset:50176
	ds_read_b128 v[192:195], v166 offset:51200
	ds_read_b128 v[196:199], v166 offset:52224
	ds_read_b128 v[200:203], v166 offset:53248
	ds_read_b128 v[204:207], v166 offset:54272
	ds_read_b128 v[208:211], v166 offset:55296
	ds_read_b128 v[212:215], v166 offset:56320
	global_load_lds_dwordx4 v[184:185], off nt
	s_add_i32 m0, s26, 0x2000
	s_add_u32 s14, s14, 0x200080
	v_lshl_add_u64 v[184:185], v[216:217], 0, s[84:85]
	s_addc_u32 s15, s15, 0
	s_add_i32 s26, s53, s30
	global_load_lds_dwordx4 v[184:185], off nt
	v_lshl_add_u64 v[184:185], s[14:15], 0, v[152:153]
	s_mov_b32 m0, s26
	s_nop 0
	global_load_lds_dwordx4 v[184:185], off nt
	v_lshl_add_u64 v[184:185], s[14:15], 0, v[156:157]
	s_add_i32 m0, s26, 0x2000
	s_nop 0
	global_load_lds_dwordx4 v[184:185], off nt
	v_lshl_add_u64 v[184:185], v[218:219], 0, s[84:85]
	s_mov_b32 m0, s68
	s_nop 0
	global_load_lds_dwordx4 v[184:185], off
	v_lshl_add_u64 v[184:185], v[220:221], 0, s[84:85]
	s_mov_b32 m0, s69
	s_nop 0
	global_load_lds_dwordx4 v[184:185], off
	s_waitcnt vmcnt(8)
	s_waitcnt lgkmcnt(0)
	s_barrier
	s_setprio 1
	s_waitcnt lgkmcnt(0)
	v_mfma_f32_16x16x32_bf16 v[62:65], v[130:133], v[176:179], v[62:65]
	v_mfma_f32_16x16x32_bf16 v[58:61], v[138:141], v[176:179], v[58:61]
	v_mfma_f32_16x16x32_bf16 v[50:53], v[130:133], v[192:195], v[50:53]
	v_mfma_f32_16x16x32_bf16 v[42:45], v[138:141], v[192:195], v[42:45]
	v_mfma_f32_16x16x32_bf16 v[30:33], v[130:133], v[200:203], v[30:33]
	v_mfma_f32_16x16x32_bf16 v[26:29], v[138:141], v[200:203], v[26:29]
	v_mfma_f32_16x16x32_bf16 v[18:21], v[130:133], v[208:211], v[18:21]
	v_mfma_f32_16x16x32_bf16 v[10:13], v[138:141], v[208:211], v[10:13]
	v_mfma_f32_16x16x32_bf16 v[62:65], v[134:137], v[188:191], v[62:65]
	v_mfma_f32_16x16x32_bf16 v[58:61], v[142:145], v[188:191], v[58:61]
	v_mfma_f32_16x16x32_bf16 v[50:53], v[134:137], v[196:199], v[50:53]
	v_mfma_f32_16x16x32_bf16 v[42:45], v[142:145], v[196:199], v[42:45]
	v_mfma_f32_16x16x32_bf16 v[30:33], v[134:137], v[204:207], v[30:33]
	v_mfma_f32_16x16x32_bf16 v[26:29], v[142:145], v[204:207], v[26:29]
	v_mfma_f32_16x16x32_bf16 v[18:21], v[134:137], v[212:215], v[18:21]
	v_mfma_f32_16x16x32_bf16 v[10:13], v[142:145], v[212:215], v[10:13]
	s_setprio 0
	s_setprio 1
	v_mfma_f32_16x16x32_bf16 v[54:57], v[146:149], v[176:179], v[54:57]
	v_mfma_f32_16x16x32_bf16 v[46:49], v[168:171], v[176:179], v[46:49]
	v_mfma_f32_16x16x32_bf16 v[38:41], v[146:149], v[192:195], v[38:41]
	v_mfma_f32_16x16x32_bf16 v[34:37], v[168:171], v[192:195], v[34:37]
	v_mfma_f32_16x16x32_bf16 v[22:25], v[146:149], v[200:203], v[22:25]
	v_mfma_f32_16x16x32_bf16 v[14:17], v[168:171], v[200:203], v[14:17]
	v_mfma_f32_16x16x32_bf16 v[6:9], v[146:149], v[208:211], v[6:9]
	v_mfma_f32_16x16x32_bf16 v[2:5], v[168:171], v[208:211], v[2:5]
	v_mfma_f32_16x16x32_bf16 v[54:57], v[162:165], v[188:191], v[54:57]
	v_mfma_f32_16x16x32_bf16 v[46:49], v[172:175], v[188:191], v[46:49]
	v_mfma_f32_16x16x32_bf16 v[38:41], v[162:165], v[196:199], v[38:41]
	v_mfma_f32_16x16x32_bf16 v[34:37], v[172:175], v[196:199], v[34:37]
	v_mfma_f32_16x16x32_bf16 v[22:25], v[162:165], v[204:207], v[22:25]
	v_mfma_f32_16x16x32_bf16 v[14:17], v[172:175], v[204:207], v[14:17]
	v_mfma_f32_16x16x32_bf16 v[6:9], v[162:165], v[212:215], v[6:9]
	v_mfma_f32_16x16x32_bf16 v[2:5], v[172:175], v[212:215], v[2:5]
	s_setprio 0
	s_barrier
	s_add_i32 s41, s41, 2
	s_add_u32 s24, s24, 0x100
	s_addc_u32 s25, s25, 0
	s_add_u32 s19, s19, 0x100
	s_addc_u32 s40, s40, 0
	s_cmpk_gt_u32 s41, 0x7d
	s_cbranch_scc0 .LBB0_2233
	s_and_b64 vcc, exec, s[12:13]
	s_cbranch_vccz .LBB0_2236
	s_barrier

; #define PG8_STAGE(bufoff, gbase, voff) do { _Pragma("unroll") for (int _i = 0; _i < 2; ++_i) \
;         __builtin_amdgcn_global_load_lds((const unsigned*)((const char*)(gbase) + (voff)[_i]), (LAS unsigned*)(lds + (bufoff) + ldsw + _i * 8192), 16, 0, 0); } while (0)
; #define PG8_LDA(dst, b, h) do { _Pragma("unroll") for (int m = 0; m < 4; ++m) _Pragma("unroll") for (int k = 0; k < 2; ++k) dst[m][k] = *(const LAS bf16x8*)(lds + PG8_SA(b, h) + aoff + m * 2048 + k * 1024); } while (0)
; #define PG8_LDB(dst, b, h) do { _Pragma("unroll") for (int n = 0; n < 2; ++n) _Pragma("unroll") for (int k = 0; k < 2; ++k) dst[n][k] = *(const LAS bf16x8*)(lds + PG8_SB(b, h) + boff + n * 2048 + k * 1024); } while (0)
; #define PG8_MMA(ai, bj, At, Bt) do { __builtin_amdgcn_s_setprio(1); _Pragma("unroll") for (int m = 0; m < 4; ++m) _Pragma("unroll") for (int n = 0; n < 2; ++n) _Pragma("unroll") for (int k = 0; k < 2; ++k) \
;         acc[ai][bj][m][n] = __builtin_amdgcn_mfma_f32_16x16x32_bf16(Bt[n][k], At[m][k], acc[ai][bj][m][n], 0, 0, 0); __builtin_amdgcn_s_setprio(0); } while (0)
; #define PG8_WAIT_V(n) asm volatile("s_waitcnt vmcnt(" #n ")" ::: "memory")
; #define PG8_WAIT_L(n) asm volatile("s_waitcnt lgkmcnt(" #n ")" ::: "memory")
; #define PG8_BAR __builtin_amdgcn_s_barrier()
; #define PG8_SCHED __builtin_amdgcn_sched_barrier(0)
; template <class Epi>
; __device__ __forceinline__ void gemm_phase(LAS unsigned char* lds, const Gemm g, const StaticOrder& S, const Epi& E) {
;     ...
;             const bool last = (t == nt - 2);
;             const char* a1 = cA + (size_t)(t + 1) * kstep;
;             const char* a2 = last ? nA : cA + (size_t)(t + 2) * kstep; const char* b2 = last ? nB : cB + (size_t)(t + 2) * kstep;
;             const char* a3 = a2 + kstep; const char* b3 = b2 + kstep;
;             PG8_LDB(B0, 0, 0); PG8_LDB(B1, 0, 1); PG8_SCHED; PG8_LDA(At, 0, 0); PG8_STAGE(PG8_SA(1, 1), a1 + hstepA, voffA);
;             PG8_WAIT_V(8); PG8_WAIT_L(0); PG8_BAR; PG8_MMA(0, 0, At, B0); PG8_MMA(0, 1, At, B1); PG8_BAR; PG8_SCHED;
;             PG8_LDA(At, 0, 1); PG8_STAGE(PG8_SB(0, 0), b2, voffB); PG8_STAGE(PG8_SB(0, 1), b2 + hstepB, voffB); PG8_STAGE(PG8_SA(0, 0), a2, voffA);
.LBB0_2332:
	s_add_u32 s14, s24, 0xfff80080
	s_addc_u32 s15, s25, -1
	s_add_i32 s41, 0, 0x10000
	s_cmp_eq_u32 s40, 28
	s_cselect_b32 s27, s1, s15
	s_cselect_b32 s26, s3, s14
	s_cselect_b32 s15, s9, s33
	s_cselect_b32 s14, s17, s19
	s_add_i32 s62, 0, 0x14000
	v_add_u32_e32 v142, s41, v1
	v_add_u32_e32 v170, s62, v1
	ds_read_b128 v[130:133], v142
	ds_read_b128 v[134:137], v142 offset:1024
	ds_read_b128 v[138:141], v142 offset:2048
	ds_read_b128 v[142:145], v142 offset:3072
	ds_read_b128 v[146:149], v170
	ds_read_b128 v[150:153], v170 offset:1024
	ds_read_b128 v[166:169], v170 offset:2048
	ds_read_b128 v[170:173], v170 offset:3072
	v_lshl_add_u64 v[178:179], s[24:25], 0, v[162:163]
	s_add_i32 m0, s35, 0xc000
	ds_read_b128 v[174:177], v181
	ds_read_b128 v[188:191], v181 offset:1024
	ds_read_b128 v[192:195], v181 offset:2048
	ds_read_b128 v[196:199], v181 offset:3072
	ds_read_b128 v[200:203], v181 offset:4096
	ds_read_b128 v[204:207], v181 offset:5120
	ds_read_b128 v[208:211], v181 offset:6144
	ds_read_b128 v[212:215], v181 offset:7168
	global_load_lds_dwordx4 v[178:179], off
	v_lshl_add_u64 v[178:179], s[24:25], 0, v[164:165]
	s_add_i32 m0, s35, 0xe000
	s_nop 0
	global_load_lds_dwordx4 v[178:179], off
	s_waitcnt vmcnt(8)
	s_waitcnt lgkmcnt(0)
	s_barrier
	s_setprio 1
	s_waitcnt lgkmcnt(0)
	v_mfma_f32_16x16x32_bf16 v[126:129], v[130:133], v[174:177], v[126:129]
	v_mfma_f32_16x16x32_bf16 v[122:125], v[138:141], v[174:177], v[122:125]
	v_mfma_f32_16x16x32_bf16 v[118:121], v[130:133], v[192:195], v[118:121]
	v_mfma_f32_16x16x32_bf16 v[114:117], v[138:141], v[192:195], v[114:117]
	v_mfma_f32_16x16x32_bf16 v[102:105], v[130:133], v[200:203], v[102:105]
	v_mfma_f32_16x16x32_bf16 v[98:101], v[138:141], v[200:203], v[98:101]
	v_mfma_f32_16x16x32_bf16 v[86:89], v[130:133], v[208:211], v[86:89]
	v_mfma_f32_16x16x32_bf16 v[82:85], v[138:141], v[208:211], v[82:85]
	v_mfma_f32_16x16x32_bf16 v[126:129], v[134:137], v[188:191], v[126:129]
	v_mfma_f32_16x16x32_bf16 v[122:125], v[142:145], v[188:191], v[122:125]
	v_mfma_f32_16x16x32_bf16 v[118:121], v[134:137], v[196:199], v[118:121]
	v_mfma_f32_16x16x32_bf16 v[114:117], v[142:145], v[196:199], v[114:117]
	v_mfma_f32_16x16x32_bf16 v[102:105], v[134:137], v[204:207], v[102:105]
	v_mfma_f32_16x16x32_bf16 v[98:101], v[142:145], v[204:207], v[98:101]
	v_mfma_f32_16x16x32_bf16 v[86:89], v[134:137], v[212:215], v[86:89]
	v_mfma_f32_16x16x32_bf16 v[82:85], v[142:145], v[212:215], v[82:85]
	s_setprio 0
	s_setprio 1
	v_mfma_f32_16x16x32_bf16 v[110:113], v[146:149], v[174:177], v[110:113]
	v_mfma_f32_16x16x32_bf16 v[106:109], v[166:169], v[174:177], v[106:109]
	v_mfma_f32_16x16x32_bf16 v[94:97], v[146:149], v[192:195], v[94:97]
	v_mfma_f32_16x16x32_bf16 v[90:93], v[166:169], v[192:195], v[90:93]
	v_mfma_f32_16x16x32_bf16 v[78:81], v[146:149], v[200:203], v[78:81]
	v_mfma_f32_16x16x32_bf16 v[74:77], v[166:169], v[200:203], v[74:77]
	v_mfma_f32_16x16x32_bf16 v[70:73], v[146:149], v[208:211], v[70:73]
	v_mfma_f32_16x16x32_bf16 v[66:69], v[166:169], v[208:211], v[66:69]
	v_mfma_f32_16x16x32_bf16 v[110:113], v[150:153], v[188:191], v[110:113]
	v_mfma_f32_16x16x32_bf16 v[106:109], v[170:173], v[188:191], v[106:109]
	v_mfma_f32_16x16x32_bf16 v[94:97], v[150:153], v[196:199], v[94:97]
	v_mfma_f32_16x16x32_bf16 v[90:93], v[170:173], v[196:199], v[90:93]
	v_mfma_f32_16x16x32_bf16 v[78:81], v[150:153], v[204:207], v[78:81]
	v_mfma_f32_16x16x32_bf16 v[74:77], v[170:173], v[204:207], v[74:77]
	v_mfma_f32_16x16x32_bf16 v[70:73], v[150:153], v[212:215], v[70:73]
	v_mfma_f32_16x16x32_bf16 v[66:69], v[170:173], v[212:215], v[66:69]
	s_setprio 0
	s_barrier
	s_add_i32 s41, s41, s34
	v_lshl_add_u64 v[178:179], s[14:15], 0, v[156:157]
	s_mov_b32 m0, s41
	ds_read_b128 v[174:177], v181 offset:16384
	ds_read_b128 v[188:191], v181 offset:17408
	ds_read_b128 v[192:195], v181 offset:18432
	ds_read_b128 v[196:199], v181 offset:19456
	ds_read_b128 v[200:203], v181 offset:20480
	ds_read_b128 v[204:207], v181 offset:21504
	ds_read_b128 v[208:211], v181 offset:22528
	ds_read_b128 v[212:215], v181 offset:23552
	global_load_lds_dwordx4 v[178:179], off nt
	s_add_i32 m0, s41, 0x2000
	s_add_u32 s52, s14, 0x80000
	v_lshl_add_u64 v[184:185], s[14:15], 0, v[160:161]
	s_addc_u32 s53, s15, 0
	s_add_i32 s41, s62, s34
	global_load_lds_dwordx4 v[184:185], off nt
	v_lshl_add_u64 v[216:217], s[52:53], 0, v[156:157]
	s_mov_b32 m0, s41
	v_lshl_add_u64 v[218:219], s[26:27], 0, v[158:159]
	global_load_lds_dwordx4 v[216:217], off nt
	v_lshl_add_u64 v[216:217], s[52:53], 0, v[160:161]
	s_add_i32 m0, s41, 0x2000
	s_nop 0
	global_load_lds_dwordx4 v[216:217], off nt
	v_lshl_add_u64 v[216:217], s[26:27], 0, v[154:155]
	s_mov_b32 m0, s35
	s_nop 0
	global_load_lds_dwordx4 v[216:217], off
	s_mov_b32 m0, s42
	s_nop 0
	global_load_lds_dwordx4 v[218:219], off
	s_waitcnt vmcnt(8)
	s_waitcnt lgkmcnt(0)
	s_barrier
; #define PG8_STAGE(bufoff, gbase, voff) do { _Pragma("unroll") for (int _i = 0; _i < 2; ++_i) \
;         __builtin_amdgcn_global_load_lds((const unsigned*)((const char*)(gbase) + (voff)[_i]), (LAS unsigned*)(lds + (bufoff) + ldsw + _i * 8192), 16, 0, 0); } while (0)
; #define PG8_LDA(dst, b, h) do { _Pragma("unroll") for (int m = 0; m < 4; ++m) _Pragma("unroll") for (int k = 0; k < 2; ++k) dst[m][k] = *(const LAS bf16x8*)(lds + PG8_SA(b, h) + aoff + m * 2048 + k * 1024); } while (0)
; #define PG8_LDB(dst, b, h) do { _Pragma("unroll") for (int n = 0; n < 2; ++n) _Pragma("unroll") for (int k = 0; k < 2; ++k) dst[n][k] = *(const LAS bf16x8*)(lds + PG8_SB(b, h) + boff + n * 2048 + k * 1024); } while (0)
; #define PG8_MMA(ai, bj, At, Bt) do { __builtin_amdgcn_s_setprio(1); _Pragma("unroll") for (int m = 0; m < 4; ++m) _Pragma("unroll") for (int n = 0; n < 2; ++n) _Pragma("unroll") for (int k = 0; k < 2; ++k) \
;         acc[ai][bj][m][n] = __builtin_amdgcn_mfma_f32_16x16x32_bf16(Bt[n][k], At[m][k], acc[ai][bj][m][n], 0, 0, 0); __builtin_amdgcn_s_setprio(0); } while (0)
; #define PG8_WAIT_V(n) asm volatile("s_waitcnt vmcnt(" #n ")" ::: "memory")
; #define PG8_WAIT_L(n) asm volatile("s_waitcnt lgkmcnt(" #n ")" ::: "memory")
; #define PG8_BAR __builtin_amdgcn_s_barrier()
; #define PG8_SCHED __builtin_amdgcn_sched_barrier(0)
; template <class Epi>
; __device__ __forceinline__ void gemm_phase(LAS unsigned char* lds, const Gemm g, const StaticOrder& S, const Epi& E) {
;     ...
;             PG8_WAIT_V(8); PG8_WAIT_L(0); PG8_BAR; PG8_MMA(1, 0, At, B0); PG8_MMA(1, 1, At, B1); PG8_BAR; PG8_SCHED;
;             PG8_LDB(B0, 1, 0); PG8_LDB(B1, 1, 1); PG8_SCHED; PG8_LDA(At, 1, 0); PG8_STAGE(PG8_SA(0, 1), a2 + hstepA, voffA);
;             PG8_WAIT_V(8); PG8_WAIT_L(0); PG8_BAR; PG8_MMA(0, 0, At, B0); PG8_MMA(0, 1, At, B1); PG8_BAR; PG8_SCHED;
	s_setprio 1
	s_waitcnt lgkmcnt(0)
	v_mfma_f32_16x16x32_bf16 v[62:65], v[130:133], v[174:177], v[62:65]
	v_mfma_f32_16x16x32_bf16 v[58:61], v[138:141], v[174:177], v[58:61]
	v_mfma_f32_16x16x32_bf16 v[54:57], v[130:133], v[192:195], v[54:57]
	v_mfma_f32_16x16x32_bf16 v[50:53], v[138:141], v[192:195], v[50:53]
	v_mfma_f32_16x16x32_bf16 v[46:49], v[130:133], v[200:203], v[46:49]
	v_mfma_f32_16x16x32_bf16 v[38:41], v[138:141], v[200:203], v[38:41]
	v_mfma_f32_16x16x32_bf16 v[30:33], v[130:133], v[208:211], v[30:33]
	v_mfma_f32_16x16x32_bf16 v[22:25], v[138:141], v[208:211], v[22:25]
	v_mfma_f32_16x16x32_bf16 v[62:65], v[134:137], v[188:191], v[62:65]
	v_mfma_f32_16x16x32_bf16 v[58:61], v[142:145], v[188:191], v[58:61]
	v_mfma_f32_16x16x32_bf16 v[54:57], v[134:137], v[196:199], v[54:57]
	v_mfma_f32_16x16x32_bf16 v[50:53], v[142:145], v[196:199], v[50:53]
	v_mfma_f32_16x16x32_bf16 v[46:49], v[134:137], v[204:207], v[46:49]
	v_mfma_f32_16x16x32_bf16 v[38:41], v[142:145], v[204:207], v[38:41]
	v_mfma_f32_16x16x32_bf16 v[30:33], v[134:137], v[212:215], v[30:33]
	v_mfma_f32_16x16x32_bf16 v[22:25], v[142:145], v[212:215], v[22:25]
	s_setprio 0
	s_setprio 1
	v_mfma_f32_16x16x32_bf16 v[42:45], v[146:149], v[174:177], v[42:45]
	v_mfma_f32_16x16x32_bf16 v[34:37], v[166:169], v[174:177], v[34:37]
	v_mfma_f32_16x16x32_bf16 v[26:29], v[146:149], v[192:195], v[26:29]
	v_mfma_f32_16x16x32_bf16 v[18:21], v[166:169], v[192:195], v[18:21]
	v_mfma_f32_16x16x32_bf16 v[14:17], v[146:149], v[200:203], v[14:17]
	v_mfma_f32_16x16x32_bf16 v[10:13], v[166:169], v[200:203], v[10:13]
	v_mfma_f32_16x16x32_bf16 v[6:9], v[146:149], v[208:211], v[6:9]
	v_mfma_f32_16x16x32_bf16 v[2:5], v[166:169], v[208:211], v[2:5]
	v_mfma_f32_16x16x32_bf16 v[42:45], v[150:153], v[188:191], v[42:45]
	v_mfma_f32_16x16x32_bf16 v[34:37], v[170:173], v[188:191], v[34:37]
	v_mfma_f32_16x16x32_bf16 v[26:29], v[150:153], v[196:199], v[26:29]
	v_mfma_f32_16x16x32_bf16 v[18:21], v[170:173], v[196:199], v[18:21]
	v_mfma_f32_16x16x32_bf16 v[14:17], v[150:153], v[204:207], v[14:17]
	v_mfma_f32_16x16x32_bf16 v[10:13], v[170:173], v[204:207], v[10:13]
	v_mfma_f32_16x16x32_bf16 v[6:9], v[150:153], v[212:215], v[6:9]
	v_mfma_f32_16x16x32_bf16 v[2:5], v[170:173], v[212:215], v[2:5]
	s_setprio 0
	s_barrier
	s_add_i32 s41, 0, 0x18000
	s_add_i32 s52, 0, 0x1c000
	v_add_u32_e32 v142, s41, v1
	v_add_u32_e32 v170, s52, v1
	ds_read_b128 v[130:133], v142
	ds_read_b128 v[134:137], v142 offset:1024
	ds_read_b128 v[138:141], v142 offset:2048
	ds_read_b128 v[142:145], v142 offset:3072
	ds_read_b128 v[146:149], v170
	ds_read_b128 v[150:153], v170 offset:1024
	ds_read_b128 v[166:169], v170 offset:2048
	ds_read_b128 v[170:173], v170 offset:3072
	s_add_u32 s26, s26, 0x80000
	s_addc_u32 s27, s27, 0
	s_mov_b32 m0, s44
	v_lshl_add_u64 v[220:221], s[26:27], 0, v[154:155]
	ds_read_b128 v[174:177], v181 offset:32768
	ds_read_b128 v[188:191], v181 offset:33792
	ds_read_b128 v[192:195], v181 offset:34816
	ds_read_b128 v[196:199], v181 offset:35840
	ds_read_b128 v[200:203], v181 offset:36864
	ds_read_b128 v[204:207], v181 offset:37888
	ds_read_b128 v[208:211], v181 offset:38912
	ds_read_b128 v[212:215], v181 offset:39936
	global_load_lds_dwordx4 v[220:221], off
	v_lshl_add_u64 v[220:221], s[26:27], 0, v[158:159]
	s_mov_b32 m0, s45
	s_nop 0
	global_load_lds_dwordx4 v[220:221], off
	s_waitcnt vmcnt(8)
	s_waitcnt lgkmcnt(0)
	s_barrier
	s_setprio 1
	s_waitcnt lgkmcnt(0)
	v_mfma_f32_16x16x32_bf16 v[126:129], v[130:133], v[174:177], v[126:129]
	v_mfma_f32_16x16x32_bf16 v[122:125], v[138:141], v[174:177], v[122:125]
	v_mfma_f32_16x16x32_bf16 v[118:121], v[130:133], v[192:195], v[118:121]
	v_mfma_f32_16x16x32_bf16 v[114:117], v[138:141], v[192:195], v[114:117]
	v_mfma_f32_16x16x32_bf16 v[102:105], v[130:133], v[200:203], v[102:105]
	v_mfma_f32_16x16x32_bf16 v[98:101], v[138:141], v[200:203], v[98:101]
	v_mfma_f32_16x16x32_bf16 v[86:89], v[130:133], v[208:211], v[86:89]
	v_mfma_f32_16x16x32_bf16 v[82:85], v[138:141], v[208:211], v[82:85]
	v_mfma_f32_16x16x32_bf16 v[126:129], v[134:137], v[188:191], v[126:129]
	v_mfma_f32_16x16x32_bf16 v[122:125], v[142:145], v[188:191], v[122:125]
	v_mfma_f32_16x16x32_bf16 v[118:121], v[134:137], v[196:199], v[118:121]
	v_mfma_f32_16x16x32_bf16 v[114:117], v[142:145], v[196:199], v[114:117]
	v_mfma_f32_16x16x32_bf16 v[102:105], v[134:137], v[204:207], v[102:105]
	v_mfma_f32_16x16x32_bf16 v[98:101], v[142:145], v[204:207], v[98:101]
	v_mfma_f32_16x16x32_bf16 v[86:89], v[134:137], v[212:215], v[86:89]
	v_mfma_f32_16x16x32_bf16 v[82:85], v[142:145], v[212:215], v[82:85]
	s_setprio 0
	s_setprio 1
	v_mfma_f32_16x16x32_bf16 v[110:113], v[146:149], v[174:177], v[110:113]
	v_mfma_f32_16x16x32_bf16 v[106:109], v[166:169], v[174:177], v[106:109]
	v_mfma_f32_16x16x32_bf16 v[94:97], v[146:149], v[192:195], v[94:97]
	v_mfma_f32_16x16x32_bf16 v[90:93], v[166:169], v[192:195], v[90:93]
	v_mfma_f32_16x16x32_bf16 v[78:81], v[146:149], v[200:203], v[78:81]
	v_mfma_f32_16x16x32_bf16 v[74:77], v[166:169], v[200:203], v[74:77]
	v_mfma_f32_16x16x32_bf16 v[70:73], v[146:149], v[208:211], v[70:73]
	v_mfma_f32_16x16x32_bf16 v[66:69], v[166:169], v[208:211], v[66:69]
	v_mfma_f32_16x16x32_bf16 v[110:113], v[150:153], v[188:191], v[110:113]
	v_mfma_f32_16x16x32_bf16 v[106:109], v[170:173], v[188:191], v[106:109]
	v_mfma_f32_16x16x32_bf16 v[94:97], v[150:153], v[196:199], v[94:97]
	v_mfma_f32_16x16x32_bf16 v[90:93], v[170:173], v[196:199], v[90:93]
	v_mfma_f32_16x16x32_bf16 v[78:81], v[150:153], v[204:207], v[78:81]
	v_mfma_f32_16x16x32_bf16 v[74:77], v[170:173], v[204:207], v[74:77]
	v_mfma_f32_16x16x32_bf16 v[70:73], v[150:153], v[212:215], v[70:73]
	v_mfma_f32_16x16x32_bf16 v[66:69], v[170:173], v[212:215], v[66:69]
	s_setprio 0
	s_barrier
; #define PG8_STAGE(bufoff, gbase, voff) do { _Pragma("unroll") for (int _i = 0; _i < 2; ++_i) \
;         __builtin_amdgcn_global_load_lds((const unsigned*)((const char*)(gbase) + (voff)[_i]), (LAS unsigned*)(lds + (bufoff) + ldsw + _i * 8192), 16, 0, 0); } while (0)
; #define PG8_LDA(dst, b, h) do { _Pragma("unroll") for (int m = 0; m < 4; ++m) _Pragma("unroll") for (int k = 0; k < 2; ++k) dst[m][k] = *(const LAS bf16x8*)(lds + PG8_SA(b, h) + aoff + m * 2048 + k * 1024); } while (0)
; #define PG8_MMA(ai, bj, At, Bt) do { __builtin_amdgcn_s_setprio(1); _Pragma("unroll") for (int m = 0; m < 4; ++m) _Pragma("unroll") for (int n = 0; n < 2; ++n) _Pragma("unroll") for (int k = 0; k < 2; ++k) \
;         acc[ai][bj][m][n] = __builtin_amdgcn_mfma_f32_16x16x32_bf16(Bt[n][k], At[m][k], acc[ai][bj][m][n], 0, 0, 0); __builtin_amdgcn_s_setprio(0); } while (0)
; #define PG8_WAIT_V(n) asm volatile("s_waitcnt vmcnt(" #n ")" ::: "memory")
; #define PG8_WAIT_L(n) asm volatile("s_waitcnt lgkmcnt(" #n ")" ::: "memory")
; #define PG8_BAR __builtin_amdgcn_s_barrier()
; #define PG8_SCHED __builtin_amdgcn_sched_barrier(0)
; template <class Epi>
; __device__ __forceinline__ void gemm_phase(LAS unsigned char* lds, const Gemm g, const StaticOrder& S, const Epi& E) {
;     ...
;             PG8_LDA(At, 1, 1); PG8_STAGE(PG8_SB(1, 0), b3, voffB); PG8_STAGE(PG8_SB(1, 1), b3 + hstepB, voffB); PG8_STAGE(PG8_SA(1, 0), a3, voffA);
;             PG8_WAIT_V(8); PG8_WAIT_L(0); PG8_BAR; PG8_MMA(1, 0, At, B0); PG8_MMA(1, 1, At, B1); PG8_BAR; PG8_SCHED;
;         }
;         if (wr == 0) PG8_BAR;
	s_add_i32 s26, s41, s34
	v_lshl_add_u64 v[178:179], v[178:179], 0, s[84:85]
	s_mov_b32 m0, s26
	ds_read_b128 v[174:177], v181 offset:49152
	ds_read_b128 v[188:191], v181 offset:50176
	ds_read_b128 v[192:195], v181 offset:51200
	ds_read_b128 v[196:199], v181 offset:52224
	ds_read_b128 v[200:203], v181 offset:53248
	ds_read_b128 v[204:207], v181 offset:54272
	ds_read_b128 v[208:211], v181 offset:55296
	ds_read_b128 v[212:215], v181 offset:56320
	global_load_lds_dwordx4 v[178:179], off nt
	s_add_i32 m0, s26, 0x2000
	s_add_u32 s14, s14, 0x80080
	v_lshl_add_u64 v[178:179], v[184:185], 0, s[84:85]
	s_addc_u32 s15, s15, 0
	s_add_i32 s26, s52, s34
	global_load_lds_dwordx4 v[178:179], off nt
	v_lshl_add_u64 v[178:179], s[14:15], 0, v[156:157]
	s_mov_b32 m0, s26
	s_nop 0
	global_load_lds_dwordx4 v[178:179], off nt
	v_lshl_add_u64 v[178:179], s[14:15], 0, v[160:161]
	s_add_i32 m0, s26, 0x2000
	s_nop 0
	global_load_lds_dwordx4 v[178:179], off nt
	v_lshl_add_u64 v[178:179], v[216:217], 0, s[84:85]
	s_mov_b32 m0, s86
	s_nop 0
	global_load_lds_dwordx4 v[178:179], off
	v_lshl_add_u64 v[178:179], v[218:219], 0, s[84:85]
	s_mov_b32 m0, s87
	s_nop 0
	global_load_lds_dwordx4 v[178:179], off
	s_waitcnt vmcnt(8)
	s_waitcnt lgkmcnt(0)
	s_barrier
	s_setprio 1
	s_waitcnt lgkmcnt(0)
	v_mfma_f32_16x16x32_bf16 v[62:65], v[130:133], v[174:177], v[62:65]
	v_mfma_f32_16x16x32_bf16 v[58:61], v[138:141], v[174:177], v[58:61]
	v_mfma_f32_16x16x32_bf16 v[54:57], v[130:133], v[192:195], v[54:57]
	v_mfma_f32_16x16x32_bf16 v[50:53], v[138:141], v[192:195], v[50:53]
	v_mfma_f32_16x16x32_bf16 v[46:49], v[130:133], v[200:203], v[46:49]
	v_mfma_f32_16x16x32_bf16 v[38:41], v[138:141], v[200:203], v[38:41]
	v_mfma_f32_16x16x32_bf16 v[30:33], v[130:133], v[208:211], v[30:33]
	v_mfma_f32_16x16x32_bf16 v[22:25], v[138:141], v[208:211], v[22:25]
	v_mfma_f32_16x16x32_bf16 v[62:65], v[134:137], v[188:191], v[62:65]
	v_mfma_f32_16x16x32_bf16 v[58:61], v[142:145], v[188:191], v[58:61]
	v_mfma_f32_16x16x32_bf16 v[54:57], v[134:137], v[196:199], v[54:57]
	v_mfma_f32_16x16x32_bf16 v[50:53], v[142:145], v[196:199], v[50:53]
	v_mfma_f32_16x16x32_bf16 v[46:49], v[134:137], v[204:207], v[46:49]
	v_mfma_f32_16x16x32_bf16 v[38:41], v[142:145], v[204:207], v[38:41]
	v_mfma_f32_16x16x32_bf16 v[30:33], v[134:137], v[212:215], v[30:33]
	v_mfma_f32_16x16x32_bf16 v[22:25], v[142:145], v[212:215], v[22:25]
	s_setprio 0
	s_setprio 1
	v_mfma_f32_16x16x32_bf16 v[42:45], v[146:149], v[174:177], v[42:45]
	v_mfma_f32_16x16x32_bf16 v[34:37], v[166:169], v[174:177], v[34:37]
	v_mfma_f32_16x16x32_bf16 v[26:29], v[146:149], v[192:195], v[26:29]
	v_mfma_f32_16x16x32_bf16 v[18:21], v[166:169], v[192:195], v[18:21]
	v_mfma_f32_16x16x32_bf16 v[14:17], v[146:149], v[200:203], v[14:17]
	v_mfma_f32_16x16x32_bf16 v[10:13], v[166:169], v[200:203], v[10:13]
	v_mfma_f32_16x16x32_bf16 v[6:9], v[146:149], v[208:211], v[6:9]
	v_mfma_f32_16x16x32_bf16 v[2:5], v[166:169], v[208:211], v[2:5]
	v_mfma_f32_16x16x32_bf16 v[42:45], v[150:153], v[188:191], v[42:45]
	v_mfma_f32_16x16x32_bf16 v[34:37], v[170:173], v[188:191], v[34:37]
	v_mfma_f32_16x16x32_bf16 v[26:29], v[150:153], v[196:199], v[26:29]
	v_mfma_f32_16x16x32_bf16 v[18:21], v[170:173], v[196:199], v[18:21]
	v_mfma_f32_16x16x32_bf16 v[14:17], v[150:153], v[204:207], v[14:17]
	v_mfma_f32_16x16x32_bf16 v[10:13], v[170:173], v[204:207], v[10:13]
	v_mfma_f32_16x16x32_bf16 v[6:9], v[150:153], v[212:215], v[6:9]
	v_mfma_f32_16x16x32_bf16 v[2:5], v[170:173], v[212:215], v[2:5]
	s_setprio 0
	s_barrier
	s_add_i32 s40, s40, 2
	s_add_u32 s24, s24, 0x100
	s_addc_u32 s25, s25, 0
	s_add_u32 s19, s19, 0x100
	s_addc_u32 s33, s33, 0
	s_cmp_gt_u32 s40, 29
	s_cbranch_scc0 .LBB0_2332
	s_and_b64 vcc, exec, s[12:13]
	s_cbranch_vccz .LBB0_2335
	s_barrier

; #define PG8_STAGE(bufoff, gbase, voff) do { _Pragma("unroll") for (int _i = 0; _i < 2; ++_i) \
;         __builtin_amdgcn_global_load_lds((const unsigned*)((const char*)(gbase) + (voff)[_i]), (LAS unsigned*)(lds + (bufoff) + ldsw + _i * 8192), 16, 0, 0); } while (0)
; #define PG8_LDA(dst, b, h) do { _Pragma("unroll") for (int m = 0; m < 4; ++m) _Pragma("unroll") for (int k = 0; k < 2; ++k) dst[m][k] = *(const LAS bf16x8*)(lds + PG8_SA(b, h) + aoff + m * 2048 + k * 1024); } while (0)
; #define PG8_LDB(dst, b, h) do { _Pragma("unroll") for (int n = 0; n < 2; ++n) _Pragma("unroll") for (int k = 0; k < 2; ++k) dst[n][k] = *(const LAS bf16x8*)(lds + PG8_SB(b, h) + boff + n * 2048 + k * 1024); } while (0)
; #define PG8_MMA(ai, bj, At, Bt) do { __builtin_amdgcn_s_setprio(1); _Pragma("unroll") for (int m = 0; m < 4; ++m) _Pragma("unroll") for (int n = 0; n < 2; ++n) _Pragma("unroll") for (int k = 0; k < 2; ++k) \
;         acc[ai][bj][m][n] = __builtin_amdgcn_mfma_f32_16x16x32_bf16(Bt[n][k], At[m][k], acc[ai][bj][m][n], 0, 0, 0); __builtin_amdgcn_s_setprio(0); } while (0)
; #define PG8_WAIT_V(n) asm volatile("s_waitcnt vmcnt(" #n ")" ::: "memory")
; #define PG8_WAIT_L(n) asm volatile("s_waitcnt lgkmcnt(" #n ")" ::: "memory")
; #define PG8_BAR __builtin_amdgcn_s_barrier()
; #define PG8_SCHED __builtin_amdgcn_sched_barrier(0)
; template <class Epi>
; __device__ __forceinline__ void gemm_phase(LAS unsigned char* lds, const Gemm g, const StaticOrder& S, const Epi& E) {
;     ...
;             const bool last = (t == nt - 2);
;             const char* a1 = cA + (size_t)(t + 1) * kstep;
;             const char* a2 = last ? nA : cA + (size_t)(t + 2) * kstep; const char* b2 = last ? nB : cB + (size_t)(t + 2) * kstep;
;             const char* a3 = a2 + kstep; const char* b3 = b2 + kstep;
;             PG8_LDB(B0, 0, 0); PG8_LDB(B1, 0, 1); PG8_SCHED; PG8_LDA(At, 0, 0); PG8_STAGE(PG8_SA(1, 1), a1 + hstepA, voffA);
;             PG8_WAIT_V(8); PG8_WAIT_L(0); PG8_BAR; PG8_MMA(0, 0, At, B0); PG8_MMA(0, 1, At, B1); PG8_BAR; PG8_SCHED;
;             PG8_LDA(At, 0, 1); PG8_STAGE(PG8_SB(0, 0), b2, voffB); PG8_STAGE(PG8_SB(0, 1), b2 + hstepB, voffB); PG8_STAGE(PG8_SA(0, 0), a2, voffA);
.LBB0_2376:
	s_add_u32 s14, s22, 0xfff80080
	s_addc_u32 s15, s23, -1
	s_add_i32 s53, 0, 0x10000
	s_cmp_eq_u32 s41, 28
	s_cselect_b32 s25, s3, s15
	s_cselect_b32 s24, s9, s14
	s_cselect_b32 s15, s13, s52
	s_cselect_b32 s14, s17, s40
	s_add_i32 s64, 0, 0x14000
	v_add_u32_e32 v142, s53, v1
	v_add_u32_e32 v170, s64, v1
	ds_read_b128 v[130:133], v142
	ds_read_b128 v[134:137], v142 offset:1024
	ds_read_b128 v[138:141], v142 offset:2048
	ds_read_b128 v[142:145], v142 offset:3072
	ds_read_b128 v[146:149], v170
	ds_read_b128 v[150:153], v170 offset:1024
	ds_read_b128 v[166:169], v170 offset:2048
	ds_read_b128 v[170:173], v170 offset:3072
	v_lshl_add_u64 v[178:179], s[22:23], 0, v[162:163]
	s_add_i32 m0, s30, 0xc000
	ds_read_b128 v[174:177], v181
	ds_read_b128 v[188:191], v181 offset:1024
	ds_read_b128 v[192:195], v181 offset:2048
	ds_read_b128 v[196:199], v181 offset:3072
	ds_read_b128 v[200:203], v181 offset:4096
	ds_read_b128 v[204:207], v181 offset:5120
	ds_read_b128 v[208:211], v181 offset:6144
	ds_read_b128 v[212:215], v181 offset:7168
	global_load_lds_dwordx4 v[178:179], off
	v_lshl_add_u64 v[178:179], s[22:23], 0, v[164:165]
	s_add_i32 m0, s30, 0xe000
	s_nop 0
	global_load_lds_dwordx4 v[178:179], off
	s_waitcnt vmcnt(8)
	s_waitcnt lgkmcnt(0)
	s_barrier
	s_setprio 1
	s_waitcnt lgkmcnt(0)
	v_mfma_f32_16x16x32_bf16 v[126:129], v[130:133], v[174:177], v[126:129]
	v_mfma_f32_16x16x32_bf16 v[122:125], v[138:141], v[174:177], v[122:125]
	v_mfma_f32_16x16x32_bf16 v[118:121], v[130:133], v[192:195], v[118:121]
	v_mfma_f32_16x16x32_bf16 v[114:117], v[138:141], v[192:195], v[114:117]
	v_mfma_f32_16x16x32_bf16 v[102:105], v[130:133], v[200:203], v[102:105]
	v_mfma_f32_16x16x32_bf16 v[98:101], v[138:141], v[200:203], v[98:101]
	v_mfma_f32_16x16x32_bf16 v[86:89], v[130:133], v[208:211], v[86:89]
	v_mfma_f32_16x16x32_bf16 v[82:85], v[138:141], v[208:211], v[82:85]
	v_mfma_f32_16x16x32_bf16 v[126:129], v[134:137], v[188:191], v[126:129]
	v_mfma_f32_16x16x32_bf16 v[122:125], v[142:145], v[188:191], v[122:125]
	v_mfma_f32_16x16x32_bf16 v[118:121], v[134:137], v[196:199], v[118:121]
	v_mfma_f32_16x16x32_bf16 v[114:117], v[142:145], v[196:199], v[114:117]
	v_mfma_f32_16x16x32_bf16 v[102:105], v[134:137], v[204:207], v[102:105]
	v_mfma_f32_16x16x32_bf16 v[98:101], v[142:145], v[204:207], v[98:101]
	v_mfma_f32_16x16x32_bf16 v[86:89], v[134:137], v[212:215], v[86:89]
	v_mfma_f32_16x16x32_bf16 v[82:85], v[142:145], v[212:215], v[82:85]
	s_setprio 0
	s_setprio 1
	v_mfma_f32_16x16x32_bf16 v[110:113], v[146:149], v[174:177], v[110:113]
	v_mfma_f32_16x16x32_bf16 v[106:109], v[166:169], v[174:177], v[106:109]
	v_mfma_f32_16x16x32_bf16 v[94:97], v[146:149], v[192:195], v[94:97]
	v_mfma_f32_16x16x32_bf16 v[90:93], v[166:169], v[192:195], v[90:93]
	v_mfma_f32_16x16x32_bf16 v[78:81], v[146:149], v[200:203], v[78:81]
	v_mfma_f32_16x16x32_bf16 v[74:77], v[166:169], v[200:203], v[74:77]
	v_mfma_f32_16x16x32_bf16 v[70:73], v[146:149], v[208:211], v[70:73]
	v_mfma_f32_16x16x32_bf16 v[66:69], v[166:169], v[208:211], v[66:69]
	v_mfma_f32_16x16x32_bf16 v[110:113], v[150:153], v[188:191], v[110:113]
	v_mfma_f32_16x16x32_bf16 v[106:109], v[170:173], v[188:191], v[106:109]
	v_mfma_f32_16x16x32_bf16 v[94:97], v[150:153], v[196:199], v[94:97]
	v_mfma_f32_16x16x32_bf16 v[90:93], v[170:173], v[196:199], v[90:93]
	v_mfma_f32_16x16x32_bf16 v[78:81], v[150:153], v[204:207], v[78:81]
	v_mfma_f32_16x16x32_bf16 v[74:77], v[170:173], v[204:207], v[74:77]
	v_mfma_f32_16x16x32_bf16 v[70:73], v[150:153], v[212:215], v[70:73]
	v_mfma_f32_16x16x32_bf16 v[66:69], v[170:173], v[212:215], v[66:69]
	s_setprio 0
	s_barrier
	s_add_i32 s53, s53, s27
	v_lshl_add_u64 v[178:179], s[14:15], 0, v[156:157]
	s_mov_b32 m0, s53
	ds_read_b128 v[174:177], v181 offset:16384
	ds_read_b128 v[188:191], v181 offset:17408
	ds_read_b128 v[192:195], v181 offset:18432
	ds_read_b128 v[196:199], v181 offset:19456
	ds_read_b128 v[200:203], v181 offset:20480
	ds_read_b128 v[204:207], v181 offset:21504
	ds_read_b128 v[208:211], v181 offset:22528
	ds_read_b128 v[212:215], v181 offset:23552
	global_load_lds_dwordx4 v[178:179], off nt
	s_add_i32 m0, s53, 0x2000
	s_add_u32 s62, s14, 0x80000
	v_lshl_add_u64 v[184:185], s[14:15], 0, v[160:161]
	s_addc_u32 s63, s15, 0
	s_add_i32 s53, s64, s27
	global_load_lds_dwordx4 v[184:185], off nt
	v_lshl_add_u64 v[186:187], s[62:63], 0, v[156:157]
	s_mov_b32 m0, s53
	v_lshl_add_u64 v[216:217], s[24:25], 0, v[158:159]
	global_load_lds_dwordx4 v[186:187], off nt
	v_lshl_add_u64 v[186:187], s[62:63], 0, v[160:161]
	s_add_i32 m0, s53, 0x2000
	s_nop 0
	global_load_lds_dwordx4 v[186:187], off nt
	v_lshl_add_u64 v[186:187], s[24:25], 0, v[154:155]
	s_mov_b32 m0, s30
	s_nop 0
	global_load_lds_dwordx4 v[186:187], off
	s_mov_b32 m0, s31
	s_nop 0
	global_load_lds_dwordx4 v[216:217], off
	s_waitcnt vmcnt(8)
	s_waitcnt lgkmcnt(0)
	s_barrier
; #define PG8_STAGE(bufoff, gbase, voff) do { _Pragma("unroll") for (int _i = 0; _i < 2; ++_i) \
;         __builtin_amdgcn_global_load_lds((const unsigned*)((const char*)(gbase) + (voff)[_i]), (LAS unsigned*)(lds + (bufoff) + ldsw + _i * 8192), 16, 0, 0); } while (0)
; #define PG8_LDA(dst, b, h) do { _Pragma("unroll") for (int m = 0; m < 4; ++m) _Pragma("unroll") for (int k = 0; k < 2; ++k) dst[m][k] = *(const LAS bf16x8*)(lds + PG8_SA(b, h) + aoff + m * 2048 + k * 1024); } while (0)
; #define PG8_LDB(dst, b, h) do { _Pragma("unroll") for (int n = 0; n < 2; ++n) _Pragma("unroll") for (int k = 0; k < 2; ++k) dst[n][k] = *(const LAS bf16x8*)(lds + PG8_SB(b, h) + boff + n * 2048 + k * 1024); } while (0)
; #define PG8_MMA(ai, bj, At, Bt) do { __builtin_amdgcn_s_setprio(1); _Pragma("unroll") for (int m = 0; m < 4; ++m) _Pragma("unroll") for (int n = 0; n < 2; ++n) _Pragma("unroll") for (int k = 0; k < 2; ++k) \
;         acc[ai][bj][m][n] = __builtin_amdgcn_mfma_f32_16x16x32_bf16(Bt[n][k], At[m][k], acc[ai][bj][m][n], 0, 0, 0); __builtin_amdgcn_s_setprio(0); } while (0)
; #define PG8_WAIT_V(n) asm volatile("s_waitcnt vmcnt(" #n ")" ::: "memory")
; #define PG8_WAIT_L(n) asm volatile("s_waitcnt lgkmcnt(" #n ")" ::: "memory")
; #define PG8_BAR __builtin_amdgcn_s_barrier()
; #define PG8_SCHED __builtin_amdgcn_sched_barrier(0)
; template <class Epi>
; __device__ __forceinline__ void gemm_phase(LAS unsigned char* lds, const Gemm g, const StaticOrder& S, const Epi& E) {
;     ...
;             PG8_WAIT_V(8); PG8_WAIT_L(0); PG8_BAR; PG8_MMA(1, 0, At, B0); PG8_MMA(1, 1, At, B1); PG8_BAR; PG8_SCHED;
;             PG8_LDB(B0, 1, 0); PG8_LDB(B1, 1, 1); PG8_SCHED; PG8_LDA(At, 1, 0); PG8_STAGE(PG8_SA(0, 1), a2 + hstepA, voffA);
;             PG8_WAIT_V(8); PG8_WAIT_L(0); PG8_BAR; PG8_MMA(0, 0, At, B0); PG8_MMA(0, 1, At, B1); PG8_BAR; PG8_SCHED;
	s_setprio 1
	s_waitcnt lgkmcnt(0)
	v_mfma_f32_16x16x32_bf16 v[62:65], v[130:133], v[174:177], v[62:65]
	v_mfma_f32_16x16x32_bf16 v[58:61], v[138:141], v[174:177], v[58:61]
	v_mfma_f32_16x16x32_bf16 v[54:57], v[130:133], v[192:195], v[54:57]
	v_mfma_f32_16x16x32_bf16 v[50:53], v[138:141], v[192:195], v[50:53]
	v_mfma_f32_16x16x32_bf16 v[46:49], v[130:133], v[200:203], v[46:49]
	v_mfma_f32_16x16x32_bf16 v[38:41], v[138:141], v[200:203], v[38:41]
	v_mfma_f32_16x16x32_bf16 v[30:33], v[130:133], v[208:211], v[30:33]
	v_mfma_f32_16x16x32_bf16 v[22:25], v[138:141], v[208:211], v[22:25]
	v_mfma_f32_16x16x32_bf16 v[62:65], v[134:137], v[188:191], v[62:65]
	v_mfma_f32_16x16x32_bf16 v[58:61], v[142:145], v[188:191], v[58:61]
	v_mfma_f32_16x16x32_bf16 v[54:57], v[134:137], v[196:199], v[54:57]
	v_mfma_f32_16x16x32_bf16 v[50:53], v[142:145], v[196:199], v[50:53]
	v_mfma_f32_16x16x32_bf16 v[46:49], v[134:137], v[204:207], v[46:49]
	v_mfma_f32_16x16x32_bf16 v[38:41], v[142:145], v[204:207], v[38:41]
	v_mfma_f32_16x16x32_bf16 v[30:33], v[134:137], v[212:215], v[30:33]
	v_mfma_f32_16x16x32_bf16 v[22:25], v[142:145], v[212:215], v[22:25]
	s_setprio 0
	s_setprio 1
	v_mfma_f32_16x16x32_bf16 v[42:45], v[146:149], v[174:177], v[42:45]
	v_mfma_f32_16x16x32_bf16 v[34:37], v[166:169], v[174:177], v[34:37]
	v_mfma_f32_16x16x32_bf16 v[26:29], v[146:149], v[192:195], v[26:29]
	v_mfma_f32_16x16x32_bf16 v[18:21], v[166:169], v[192:195], v[18:21]
	v_mfma_f32_16x16x32_bf16 v[14:17], v[146:149], v[200:203], v[14:17]
	v_mfma_f32_16x16x32_bf16 v[10:13], v[166:169], v[200:203], v[10:13]
	v_mfma_f32_16x16x32_bf16 v[6:9], v[146:149], v[208:211], v[6:9]
	v_mfma_f32_16x16x32_bf16 v[2:5], v[166:169], v[208:211], v[2:5]
	v_mfma_f32_16x16x32_bf16 v[42:45], v[150:153], v[188:191], v[42:45]
	v_mfma_f32_16x16x32_bf16 v[34:37], v[170:173], v[188:191], v[34:37]
	v_mfma_f32_16x16x32_bf16 v[26:29], v[150:153], v[196:199], v[26:29]
	v_mfma_f32_16x16x32_bf16 v[18:21], v[170:173], v[196:199], v[18:21]
	v_mfma_f32_16x16x32_bf16 v[14:17], v[150:153], v[204:207], v[14:17]
	v_mfma_f32_16x16x32_bf16 v[10:13], v[170:173], v[204:207], v[10:13]
	v_mfma_f32_16x16x32_bf16 v[6:9], v[150:153], v[212:215], v[6:9]
	v_mfma_f32_16x16x32_bf16 v[2:5], v[170:173], v[212:215], v[2:5]
	s_setprio 0
	s_barrier
	s_add_i32 s53, 0, 0x18000
	s_add_i32 s62, 0, 0x1c000
	v_add_u32_e32 v142, s53, v1
	v_add_u32_e32 v170, s62, v1
	ds_read_b128 v[130:133], v142
	ds_read_b128 v[134:137], v142 offset:1024
	ds_read_b128 v[138:141], v142 offset:2048
	ds_read_b128 v[142:145], v142 offset:3072
	ds_read_b128 v[146:149], v170
	ds_read_b128 v[150:153], v170 offset:1024
	ds_read_b128 v[166:169], v170 offset:2048
	ds_read_b128 v[170:173], v170 offset:3072
	s_add_u32 s24, s24, 0x80000
	s_addc_u32 s25, s25, 0
	s_mov_b32 m0, s34
	v_lshl_add_u64 v[218:219], s[24:25], 0, v[154:155]
	ds_read_b128 v[174:177], v181 offset:32768
	ds_read_b128 v[188:191], v181 offset:33792
	ds_read_b128 v[192:195], v181 offset:34816
	ds_read_b128 v[196:199], v181 offset:35840
	ds_read_b128 v[200:203], v181 offset:36864
	ds_read_b128 v[204:207], v181 offset:37888
	ds_read_b128 v[208:211], v181 offset:38912
	ds_read_b128 v[212:215], v181 offset:39936
	global_load_lds_dwordx4 v[218:219], off
	v_lshl_add_u64 v[218:219], s[24:25], 0, v[158:159]
	s_mov_b32 m0, s35
	s_nop 0
	global_load_lds_dwordx4 v[218:219], off
	s_waitcnt vmcnt(8)
	s_waitcnt lgkmcnt(0)
	s_barrier
	s_setprio 1
	s_waitcnt lgkmcnt(0)
	v_mfma_f32_16x16x32_bf16 v[126:129], v[130:133], v[174:177], v[126:129]
	v_mfma_f32_16x16x32_bf16 v[122:125], v[138:141], v[174:177], v[122:125]
	v_mfma_f32_16x16x32_bf16 v[118:121], v[130:133], v[192:195], v[118:121]
	v_mfma_f32_16x16x32_bf16 v[114:117], v[138:141], v[192:195], v[114:117]
	v_mfma_f32_16x16x32_bf16 v[102:105], v[130:133], v[200:203], v[102:105]
	v_mfma_f32_16x16x32_bf16 v[98:101], v[138:141], v[200:203], v[98:101]
	v_mfma_f32_16x16x32_bf16 v[86:89], v[130:133], v[208:211], v[86:89]
	v_mfma_f32_16x16x32_bf16 v[82:85], v[138:141], v[208:211], v[82:85]
	v_mfma_f32_16x16x32_bf16 v[126:129], v[134:137], v[188:191], v[126:129]
	v_mfma_f32_16x16x32_bf16 v[122:125], v[142:145], v[188:191], v[122:125]
	v_mfma_f32_16x16x32_bf16 v[118:121], v[134:137], v[196:199], v[118:121]
	v_mfma_f32_16x16x32_bf16 v[114:117], v[142:145], v[196:199], v[114:117]
	v_mfma_f32_16x16x32_bf16 v[102:105], v[134:137], v[204:207], v[102:105]
	v_mfma_f32_16x16x32_bf16 v[98:101], v[142:145], v[204:207], v[98:101]
	v_mfma_f32_16x16x32_bf16 v[86:89], v[134:137], v[212:215], v[86:89]
	v_mfma_f32_16x16x32_bf16 v[82:85], v[142:145], v[212:215], v[82:85]
	s_setprio 0
	s_setprio 1
	v_mfma_f32_16x16x32_bf16 v[110:113], v[146:149], v[174:177], v[110:113]
	v_mfma_f32_16x16x32_bf16 v[106:109], v[166:169], v[174:177], v[106:109]
	v_mfma_f32_16x16x32_bf16 v[94:97], v[146:149], v[192:195], v[94:97]
	v_mfma_f32_16x16x32_bf16 v[90:93], v[166:169], v[192:195], v[90:93]
	v_mfma_f32_16x16x32_bf16 v[78:81], v[146:149], v[200:203], v[78:81]
	v_mfma_f32_16x16x32_bf16 v[74:77], v[166:169], v[200:203], v[74:77]
	v_mfma_f32_16x16x32_bf16 v[70:73], v[146:149], v[208:211], v[70:73]
	v_mfma_f32_16x16x32_bf16 v[66:69], v[166:169], v[208:211], v[66:69]
	v_mfma_f32_16x16x32_bf16 v[110:113], v[150:153], v[188:191], v[110:113]
	v_mfma_f32_16x16x32_bf16 v[106:109], v[170:173], v[188:191], v[106:109]
	v_mfma_f32_16x16x32_bf16 v[94:97], v[150:153], v[196:199], v[94:97]
	v_mfma_f32_16x16x32_bf16 v[90:93], v[170:173], v[196:199], v[90:93]
	v_mfma_f32_16x16x32_bf16 v[78:81], v[150:153], v[204:207], v[78:81]
	v_mfma_f32_16x16x32_bf16 v[74:77], v[170:173], v[204:207], v[74:77]
	v_mfma_f32_16x16x32_bf16 v[70:73], v[150:153], v[212:215], v[70:73]
	v_mfma_f32_16x16x32_bf16 v[66:69], v[170:173], v[212:215], v[66:69]
	s_setprio 0
	s_barrier
; #define PG8_STAGE(bufoff, gbase, voff) do { _Pragma("unroll") for (int _i = 0; _i < 2; ++_i) \
;         __builtin_amdgcn_global_load_lds((const unsigned*)((const char*)(gbase) + (voff)[_i]), (LAS unsigned*)(lds + (bufoff) + ldsw + _i * 8192), 16, 0, 0); } while (0)
; #define PG8_LDA(dst, b, h) do { _Pragma("unroll") for (int m = 0; m < 4; ++m) _Pragma("unroll") for (int k = 0; k < 2; ++k) dst[m][k] = *(const LAS bf16x8*)(lds + PG8_SA(b, h) + aoff + m * 2048 + k * 1024); } while (0)
; #define PG8_MMA(ai, bj, At, Bt) do { __builtin_amdgcn_s_setprio(1); _Pragma("unroll") for (int m = 0; m < 4; ++m) _Pragma("unroll") for (int n = 0; n < 2; ++n) _Pragma("unroll") for (int k = 0; k < 2; ++k) \
;         acc[ai][bj][m][n] = __builtin_amdgcn_mfma_f32_16x16x32_bf16(Bt[n][k], At[m][k], acc[ai][bj][m][n], 0, 0, 0); __builtin_amdgcn_s_setprio(0); } while (0)
; #define PG8_WAIT_V(n) asm volatile("s_waitcnt vmcnt(" #n ")" ::: "memory")
; #define PG8_WAIT_L(n) asm volatile("s_waitcnt lgkmcnt(" #n ")" ::: "memory")
; #define PG8_BAR __builtin_amdgcn_s_barrier()
; #define PG8_SCHED __builtin_amdgcn_sched_barrier(0)
; template <class Epi>
; __device__ __forceinline__ void gemm_phase(LAS unsigned char* lds, const Gemm g, const StaticOrder& S, const Epi& E) {
;     ...
;             PG8_LDA(At, 1, 1); PG8_STAGE(PG8_SB(1, 0), b3, voffB); PG8_STAGE(PG8_SB(1, 1), b3 + hstepB, voffB); PG8_STAGE(PG8_SA(1, 0), a3, voffA);
;             PG8_WAIT_V(8); PG8_WAIT_L(0); PG8_BAR; PG8_MMA(1, 0, At, B0); PG8_MMA(1, 1, At, B1); PG8_BAR; PG8_SCHED;
;         }
;         if (wr == 0) PG8_BAR;
	s_add_i32 s24, s53, s27
	v_lshl_add_u64 v[178:179], v[178:179], 0, s[84:85]
	s_mov_b32 m0, s24
	ds_read_b128 v[174:177], v181 offset:49152
	ds_read_b128 v[188:191], v181 offset:50176
	ds_read_b128 v[192:195], v181 offset:51200
	ds_read_b128 v[196:199], v181 offset:52224
	ds_read_b128 v[200:203], v181 offset:53248
	ds_read_b128 v[204:207], v181 offset:54272
	ds_read_b128 v[208:211], v181 offset:55296
	ds_read_b128 v[212:215], v181 offset:56320
	global_load_lds_dwordx4 v[178:179], off nt
	s_add_i32 m0, s24, 0x2000
	s_add_u32 s14, s14, 0x80080
	v_lshl_add_u64 v[178:179], v[184:185], 0, s[84:85]
	s_addc_u32 s15, s15, 0
	s_add_i32 s24, s62, s27
	global_load_lds_dwordx4 v[178:179], off nt
	v_lshl_add_u64 v[178:179], s[14:15], 0, v[156:157]
	s_mov_b32 m0, s24
	s_nop 0
	global_load_lds_dwordx4 v[178:179], off nt
	v_lshl_add_u64 v[178:179], s[14:15], 0, v[160:161]
	s_add_i32 m0, s24, 0x2000
	s_nop 0
	global_load_lds_dwordx4 v[178:179], off nt
	v_lshl_add_u64 v[178:179], v[186:187], 0, s[84:85]
	s_mov_b32 m0, s45
	s_nop 0
	global_load_lds_dwordx4 v[178:179], off
	v_lshl_add_u64 v[178:179], v[216:217], 0, s[84:85]
	s_mov_b32 m0, s68
	s_nop 0
	global_load_lds_dwordx4 v[178:179], off
	s_waitcnt vmcnt(8)
	s_waitcnt lgkmcnt(0)
	s_barrier
	s_setprio 1
	s_waitcnt lgkmcnt(0)
	v_mfma_f32_16x16x32_bf16 v[62:65], v[130:133], v[174:177], v[62:65]
	v_mfma_f32_16x16x32_bf16 v[58:61], v[138:141], v[174:177], v[58:61]
	v_mfma_f32_16x16x32_bf16 v[54:57], v[130:133], v[192:195], v[54:57]
	v_mfma_f32_16x16x32_bf16 v[50:53], v[138:141], v[192:195], v[50:53]
	v_mfma_f32_16x16x32_bf16 v[46:49], v[130:133], v[200:203], v[46:49]
	v_mfma_f32_16x16x32_bf16 v[38:41], v[138:141], v[200:203], v[38:41]
	v_mfma_f32_16x16x32_bf16 v[30:33], v[130:133], v[208:211], v[30:33]
	v_mfma_f32_16x16x32_bf16 v[22:25], v[138:141], v[208:211], v[22:25]
	v_mfma_f32_16x16x32_bf16 v[62:65], v[134:137], v[188:191], v[62:65]
	v_mfma_f32_16x16x32_bf16 v[58:61], v[142:145], v[188:191], v[58:61]
	v_mfma_f32_16x16x32_bf16 v[54:57], v[134:137], v[196:199], v[54:57]
	v_mfma_f32_16x16x32_bf16 v[50:53], v[142:145], v[196:199], v[50:53]
	v_mfma_f32_16x16x32_bf16 v[46:49], v[134:137], v[204:207], v[46:49]
	v_mfma_f32_16x16x32_bf16 v[38:41], v[142:145], v[204:207], v[38:41]
	v_mfma_f32_16x16x32_bf16 v[30:33], v[134:137], v[212:215], v[30:33]
	v_mfma_f32_16x16x32_bf16 v[22:25], v[142:145], v[212:215], v[22:25]
	s_setprio 0
	s_setprio 1
	v_mfma_f32_16x16x32_bf16 v[42:45], v[146:149], v[174:177], v[42:45]
	v_mfma_f32_16x16x32_bf16 v[34:37], v[166:169], v[174:177], v[34:37]
	v_mfma_f32_16x16x32_bf16 v[26:29], v[146:149], v[192:195], v[26:29]
	v_mfma_f32_16x16x32_bf16 v[18:21], v[166:169], v[192:195], v[18:21]
	v_mfma_f32_16x16x32_bf16 v[14:17], v[146:149], v[200:203], v[14:17]
	v_mfma_f32_16x16x32_bf16 v[10:13], v[166:169], v[200:203], v[10:13]
	v_mfma_f32_16x16x32_bf16 v[6:9], v[146:149], v[208:211], v[6:9]
	v_mfma_f32_16x16x32_bf16 v[2:5], v[166:169], v[208:211], v[2:5]
	v_mfma_f32_16x16x32_bf16 v[42:45], v[150:153], v[188:191], v[42:45]
	v_mfma_f32_16x16x32_bf16 v[34:37], v[170:173], v[188:191], v[34:37]
	v_mfma_f32_16x16x32_bf16 v[26:29], v[150:153], v[196:199], v[26:29]
	v_mfma_f32_16x16x32_bf16 v[18:21], v[170:173], v[196:199], v[18:21]
	v_mfma_f32_16x16x32_bf16 v[14:17], v[150:153], v[204:207], v[14:17]
	v_mfma_f32_16x16x32_bf16 v[10:13], v[170:173], v[204:207], v[10:13]
	v_mfma_f32_16x16x32_bf16 v[6:9], v[150:153], v[212:215], v[6:9]
	v_mfma_f32_16x16x32_bf16 v[2:5], v[170:173], v[212:215], v[2:5]
	s_setprio 0
	s_barrier
	s_add_i32 s41, s41, 2
	s_add_u32 s22, s22, 0x100
	s_addc_u32 s23, s23, 0
	s_add_u32 s40, s40, 0x100
	s_addc_u32 s52, s52, 0
	s_cmp_gt_u32 s41, 29
	s_cbranch_scc0 .LBB0_2376
	v_mov_b64_e32 v[250:251], 0xff
	v_mov_b64_e32 v[252:253], 0x100
	v_mov_b32_e32 v183, 0x7f800000
	s_and_b64 vcc, exec, s[10:11]
	s_cbranch_vccz .LBB0_2379
	s_barrier
